# v7 plus remaining address adds removed and B-fragment LDS address hoisted to one add per K-loop iteration (load segments now VALU-free except 1)
# speedup vs baseline: 1.0077x; 1.0062x over previous
; #define PG8_STAGE(bufoff, gbase, voff) do { _Pragma("unroll") for (int _i = 0; _i < 2; ++_i) \
;         __builtin_amdgcn_global_load_lds((const unsigned*)((const char*)(gbase) + (voff)[_i]), (PG8_LAS unsigned*)(lds + (bufoff) + ldsw + _i * 8192), 16, 0, 0); } while (0)
; #define PG8_LDA(dst, b, h) do { _Pragma("unroll") for (int m = 0; m < 4; ++m) _Pragma("unroll") for (int k = 0; k < 2; ++k) dst[m][k] = *(const PG8_LAS bf16x8*)(lds + PG8_SA(b, h) + aoff + m * 2048 + k * 1024); } while (0)
; #define PG8_LDB(dst, b, h) do { _Pragma("unroll") for (int n = 0; n < 2; ++n) _Pragma("unroll") for (int k = 0; k < 2; ++k) dst[n][k] = *(const PG8_LAS bf16x8*)(lds + PG8_SB(b, h) + boff + n * 2048 + k * 1024); } while (0)
; #define PG8_WAIT_V(n) asm volatile("s_waitcnt vmcnt(" #n ")" ::: "memory")
; #define PG8_WAIT_L(n) asm volatile("s_waitcnt lgkmcnt(" #n ")" ::: "memory")
; #define PG8_BAR __builtin_amdgcn_s_barrier()
; #define PG8_SCHED __builtin_amdgcn_sched_barrier(0)
;     ...
;             const bool last = (t == nt - 2);
;             const char* a1 = cA + (size_t)(t + 1) * kstep;
;             const char* a2 = last ? nA : cA + (size_t)(t + 2) * kstep; const char* b2 = last ? nB : cB + (size_t)(t + 2) * kstep;
;             const char* a3 = a2 + kstep; const char* b3 = b2 + kstep;
;             if (last && has_next) S.a_ready(nxt);
;             if constexpr (SP2) {
;             PG8_LDB(B0, 0, 0); PG8_LDB(B1, 0, 1); PG8_SCHED; PG8_LDA(At, 0, 0); PG8_STAGE(PG8_SA(1, 1), a1 + hstepA, voffA);
;             PG8_WAIT_V(8); PG8_WAIT_L(0); PG8_BAR; PG8_MMA(0, 0, At, B0); PG8_MMA(0, 1, At, B1); PG8_BAR; PG8_SCHED;
;             PG8_LDA(At, 0, 1); PG8_STAGE(PG8_SB(0, 0), b2, voffB); PG8_STAGE(PG8_SB(0, 1), b2 + hstepB, voffB); PG8_STAGE(PG8_SA(0, 0), a2, voffA);
;             PG8_WAIT_V(8); PG8_WAIT_L(0); PG8_BAR; PG8_MMA(1, 0, At, B0); PG8_MMA(1, 1, At, B1); PG8_BAR; PG8_SCHED;
.LBB0_538:
	v_add_u32_e32 v162, 0x10000, v153
	s_add_u32 s63, s64, 0xfffc0080
	s_addc_u32 s66, s65, -1
	s_add_i32 s68, 0, 0x10000
	s_cmp_eq_u32 s57, 12
	s_cselect_b32 s75, s6, s66
	s_cselect_b32 s74, s15, s63
	s_cselect_b32 s67, s34, s55
	s_cselect_b32 s66, s35, s45
	s_add_i32 s63, 0, 0x14000
	ds_read_b128 v[142:145], v162
	ds_read_b128 v[146:149], v162 offset:1024
	ds_read_b128 v[158:161], v162 offset:2048
	ds_read_b128 v[186:189], v162 offset:3072
	ds_read_b128 v[190:193], v162 offset:16384
	ds_read_b128 v[194:197], v162 offset:17408
	ds_read_b128 v[198:201], v162 offset:18432
	ds_read_b128 v[202:205], v162 offset:19456
	s_add_i32 m0, s81, 0xc000
	ds_read_b128 v[206:209], v156
	ds_read_b128 v[210:213], v156 offset:1024
	ds_read_b128 v[214:217], v156 offset:2048
	ds_read_b128 v[218:221], v156 offset:3072
	ds_read_b128 v[222:225], v156 offset:4096
	ds_read_b128 v[234:237], v156 offset:5120
	ds_read_b128 v[238:241], v156 offset:6144
	ds_read_b128 v[242:245], v156 offset:7168
	global_load_lds_dwordx4 v138, s[64:65]
	s_add_i32 m0, s81, 0xe000
	s_nop 0
	global_load_lds_dwordx4 v140, s[64:65]
	s_waitcnt vmcnt(8)
	s_waitcnt lgkmcnt(0)
	s_barrier
	s_setprio 1
	v_mfma_i32_16x16x64_i8 v[128:131], v[142:145], v[206:209], v[128:131]
	v_mfma_i32_16x16x64_i8 v[120:123], v[158:161], v[206:209], v[120:123]
	v_mfma_i32_16x16x64_i8 v[112:115], v[142:145], v[214:217], v[112:115]
	v_mfma_i32_16x16x64_i8 v[104:107], v[158:161], v[214:217], v[104:107]
	v_mfma_i32_16x16x64_i8 v[96:99], v[142:145], v[222:225], v[96:99]
	v_mfma_i32_16x16x64_i8 v[88:91], v[158:161], v[222:225], v[88:91]
	v_mfma_i32_16x16x64_i8 v[80:83], v[142:145], v[238:241], v[80:83]
	v_mfma_i32_16x16x64_i8 v[72:75], v[158:161], v[238:241], v[72:75]
	v_mfma_i32_16x16x64_i8 v[128:131], v[146:149], v[210:213], v[128:131]
	v_mfma_i32_16x16x64_i8 v[120:123], v[186:189], v[210:213], v[120:123]
	v_mfma_i32_16x16x64_i8 v[112:115], v[146:149], v[218:221], v[112:115]
	v_mfma_i32_16x16x64_i8 v[104:107], v[186:189], v[218:221], v[104:107]
	v_mfma_i32_16x16x64_i8 v[96:99], v[146:149], v[234:237], v[96:99]
	v_mfma_i32_16x16x64_i8 v[88:91], v[186:189], v[234:237], v[88:91]
	v_mfma_i32_16x16x64_i8 v[80:83], v[146:149], v[242:245], v[80:83]
	v_mfma_i32_16x16x64_i8 v[72:75], v[186:189], v[242:245], v[72:75]
	v_mfma_i32_16x16x64_i8 v[124:127], v[190:193], v[206:209], v[124:127]
	v_mfma_i32_16x16x64_i8 v[116:119], v[198:201], v[206:209], v[116:119]
	v_mfma_i32_16x16x64_i8 v[108:111], v[190:193], v[214:217], v[108:111]
	v_mfma_i32_16x16x64_i8 v[100:103], v[198:201], v[214:217], v[100:103]
	v_mfma_i32_16x16x64_i8 v[92:95], v[190:193], v[222:225], v[92:95]
	v_mfma_i32_16x16x64_i8 v[84:87], v[198:201], v[222:225], v[84:87]
	v_mfma_i32_16x16x64_i8 v[76:79], v[190:193], v[238:241], v[76:79]
	v_mfma_i32_16x16x64_i8 v[68:71], v[198:201], v[238:241], v[68:71]
	v_mfma_i32_16x16x64_i8 v[124:127], v[194:197], v[210:213], v[124:127]
	v_mfma_i32_16x16x64_i8 v[116:119], v[202:205], v[210:213], v[116:119]
	v_mfma_i32_16x16x64_i8 v[108:111], v[194:197], v[218:221], v[108:111]
	v_mfma_i32_16x16x64_i8 v[100:103], v[202:205], v[218:221], v[100:103]
	v_mfma_i32_16x16x64_i8 v[92:95], v[194:197], v[234:237], v[92:95]
	v_mfma_i32_16x16x64_i8 v[84:87], v[202:205], v[234:237], v[84:87]
	v_mfma_i32_16x16x64_i8 v[76:79], v[194:197], v[242:245], v[76:79]
	v_mfma_i32_16x16x64_i8 v[68:71], v[202:205], v[242:245], v[68:71]
	s_setprio 0
	s_barrier
	s_add_i32 s68, s68, s10
	s_mov_b32 m0, s68
	ds_read_b128 v[206:209], v156 offset:16384
	ds_read_b128 v[210:213], v156 offset:17408
	ds_read_b128 v[214:217], v156 offset:18432
	ds_read_b128 v[218:221], v156 offset:19456
	ds_read_b128 v[222:225], v156 offset:20480
	ds_read_b128 v[234:237], v156 offset:21504
	ds_read_b128 v[238:241], v156 offset:22528
	ds_read_b128 v[242:245], v156 offset:23552
	global_load_lds_dwordx4 v34, s[66:67]
	s_add_i32 m0, s68, 0x2000
	s_add_u32 s70, s66, 0x40000
	s_addc_u32 s71, s67, 0
	s_add_i32 s63, s63, s10
	global_load_lds_dwordx4 v136, s[66:67]
	s_mov_b32 m0, s63
	s_nop 0
	global_load_lds_dwordx4 v34, s[70:71]
	s_add_i32 m0, s63, 0x2000
	s_nop 0
	global_load_lds_dwordx4 v136, s[70:71]
	s_mov_b32 m0, s81
	s_nop 0
	global_load_lds_dwordx4 v132, s[74:75]
	s_mov_b32 m0, s82
	s_nop 0
	global_load_lds_dwordx4 v134, s[74:75]
	s_waitcnt vmcnt(8)
	s_waitcnt lgkmcnt(0)
	s_barrier
	s_setprio 1
	v_mfma_i32_16x16x64_i8 v[64:67], v[142:145], v[206:209], v[64:67]
	v_mfma_i32_16x16x64_i8 v[56:59], v[158:161], v[206:209], v[56:59]
	v_mfma_i32_16x16x64_i8 v[48:51], v[142:145], v[214:217], v[48:51]
	v_mfma_i32_16x16x64_i8 v[40:43], v[158:161], v[214:217], v[40:43]
	v_mfma_i32_16x16x64_i8 v[30:33], v[142:145], v[222:225], v[30:33]
	v_mfma_i32_16x16x64_i8 v[22:25], v[158:161], v[222:225], v[22:25]
	v_mfma_i32_16x16x64_i8 v[14:17], v[142:145], v[238:241], v[14:17]
	v_mfma_i32_16x16x64_i8 v[6:9], v[158:161], v[238:241], v[6:9]
	v_mfma_i32_16x16x64_i8 v[64:67], v[146:149], v[210:213], v[64:67]
	v_mfma_i32_16x16x64_i8 v[56:59], v[186:189], v[210:213], v[56:59]
	v_mfma_i32_16x16x64_i8 v[48:51], v[146:149], v[218:221], v[48:51]
	v_mfma_i32_16x16x64_i8 v[40:43], v[186:189], v[218:221], v[40:43]
	v_mfma_i32_16x16x64_i8 v[30:33], v[146:149], v[234:237], v[30:33]
	v_mfma_i32_16x16x64_i8 v[22:25], v[186:189], v[234:237], v[22:25]
	v_mfma_i32_16x16x64_i8 v[14:17], v[146:149], v[242:245], v[14:17]
	v_mfma_i32_16x16x64_i8 v[6:9], v[186:189], v[242:245], v[6:9]
	v_mfma_i32_16x16x64_i8 v[60:63], v[190:193], v[206:209], v[60:63]
	v_mfma_i32_16x16x64_i8 v[52:55], v[198:201], v[206:209], v[52:55]
	v_mfma_i32_16x16x64_i8 v[44:47], v[190:193], v[214:217], v[44:47]
	v_mfma_i32_16x16x64_i8 v[36:39], v[198:201], v[214:217], v[36:39]
	v_mfma_i32_16x16x64_i8 v[26:29], v[190:193], v[222:225], v[26:29]
	v_mfma_i32_16x16x64_i8 v[18:21], v[198:201], v[222:225], v[18:21]
	v_mfma_i32_16x16x64_i8 v[10:13], v[190:193], v[238:241], v[10:13]
	v_mfma_i32_16x16x64_i8 v[2:5], v[198:201], v[238:241], v[2:5]
	v_mfma_i32_16x16x64_i8 v[60:63], v[194:197], v[210:213], v[60:63]
	v_mfma_i32_16x16x64_i8 v[52:55], v[202:205], v[210:213], v[52:55]
	v_mfma_i32_16x16x64_i8 v[44:47], v[194:197], v[218:221], v[44:47]
	v_mfma_i32_16x16x64_i8 v[36:39], v[202:205], v[218:221], v[36:39]
	v_mfma_i32_16x16x64_i8 v[26:29], v[194:197], v[234:237], v[26:29]
	v_mfma_i32_16x16x64_i8 v[18:21], v[202:205], v[234:237], v[18:21]
	v_mfma_i32_16x16x64_i8 v[10:13], v[194:197], v[242:245], v[10:13]
	v_mfma_i32_16x16x64_i8 v[2:5], v[202:205], v[242:245], v[2:5]
	s_setprio 0
	s_barrier
; #define PG8_STAGE(bufoff, gbase, voff) do { _Pragma("unroll") for (int _i = 0; _i < 2; ++_i) \
;         __builtin_amdgcn_global_load_lds((const unsigned*)((const char*)(gbase) + (voff)[_i]), (PG8_LAS unsigned*)(lds + (bufoff) + ldsw + _i * 8192), 16, 0, 0); } while (0)
; #define PG8_LDA(dst, b, h) do { _Pragma("unroll") for (int m = 0; m < 4; ++m) _Pragma("unroll") for (int k = 0; k < 2; ++k) dst[m][k] = *(const PG8_LAS bf16x8*)(lds + PG8_SA(b, h) + aoff + m * 2048 + k * 1024); } while (0)
; #define PG8_LDB(dst, b, h) do { _Pragma("unroll") for (int n = 0; n < 2; ++n) _Pragma("unroll") for (int k = 0; k < 2; ++k) dst[n][k] = *(const PG8_LAS bf16x8*)(lds + PG8_SB(b, h) + boff + n * 2048 + k * 1024); } while (0)
; #define PG8_WAIT_V(n) asm volatile("s_waitcnt vmcnt(" #n ")" ::: "memory")
; #define PG8_WAIT_L(n) asm volatile("s_waitcnt lgkmcnt(" #n ")" ::: "memory")
; #define PG8_BAR __builtin_amdgcn_s_barrier()
; #define PG8_SCHED __builtin_amdgcn_sched_barrier(0)
;     ...
;             PG8_LDB(B0, 1, 0); PG8_LDB(B1, 1, 1); PG8_SCHED; PG8_LDA(At, 1, 0); PG8_STAGE(PG8_SA(0, 1), a2 + hstepA, voffA);
;             PG8_WAIT_V(8); PG8_WAIT_L(0); PG8_BAR; PG8_MMA(0, 0, At, B0); PG8_MMA(0, 1, At, B1); PG8_BAR; PG8_SCHED;
	s_add_i32 s63, 0, 0x18000
	s_add_i32 s68, 0, 0x1c000
	ds_read_b128 v[142:145], v162 offset:32768
	ds_read_b128 v[146:149], v162 offset:33792
	ds_read_b128 v[158:161], v162 offset:34816
	ds_read_b128 v[186:189], v162 offset:35840
	ds_read_b128 v[190:193], v162 offset:49152
	ds_read_b128 v[194:197], v162 offset:50176
	ds_read_b128 v[198:201], v162 offset:51200
	ds_read_b128 v[202:205], v162 offset:52224
	s_add_u32 s70, s74, 0x40000
	s_addc_u32 s71, s75, 0
	s_mov_b32 m0, s83
	ds_read_b128 v[206:209], v156 offset:32768
	ds_read_b128 v[210:213], v156 offset:33792
	ds_read_b128 v[214:217], v156 offset:34816
	ds_read_b128 v[218:221], v156 offset:35840
	ds_read_b128 v[222:225], v156 offset:36864
	ds_read_b128 v[234:237], v156 offset:37888
	ds_read_b128 v[238:241], v156 offset:38912
	ds_read_b128 v[242:245], v156 offset:39936
	global_load_lds_dwordx4 v132, s[70:71]
	s_mov_b32 m0, s84
	s_nop 0
	global_load_lds_dwordx4 v134, s[70:71]
	s_waitcnt vmcnt(8)
	s_waitcnt lgkmcnt(0)
	s_barrier
	s_setprio 1
	v_mfma_i32_16x16x64_i8 v[128:131], v[142:145], v[206:209], v[128:131]
	v_mfma_i32_16x16x64_i8 v[120:123], v[158:161], v[206:209], v[120:123]
	v_mfma_i32_16x16x64_i8 v[112:115], v[142:145], v[214:217], v[112:115]
	v_mfma_i32_16x16x64_i8 v[104:107], v[158:161], v[214:217], v[104:107]
	v_mfma_i32_16x16x64_i8 v[96:99], v[142:145], v[222:225], v[96:99]
	v_mfma_i32_16x16x64_i8 v[88:91], v[158:161], v[222:225], v[88:91]
	v_mfma_i32_16x16x64_i8 v[80:83], v[142:145], v[238:241], v[80:83]
	v_mfma_i32_16x16x64_i8 v[72:75], v[158:161], v[238:241], v[72:75]
	v_mfma_i32_16x16x64_i8 v[128:131], v[146:149], v[210:213], v[128:131]
	v_mfma_i32_16x16x64_i8 v[120:123], v[186:189], v[210:213], v[120:123]
	v_mfma_i32_16x16x64_i8 v[112:115], v[146:149], v[218:221], v[112:115]
	v_mfma_i32_16x16x64_i8 v[104:107], v[186:189], v[218:221], v[104:107]
	v_mfma_i32_16x16x64_i8 v[96:99], v[146:149], v[234:237], v[96:99]
	v_mfma_i32_16x16x64_i8 v[88:91], v[186:189], v[234:237], v[88:91]
	v_mfma_i32_16x16x64_i8 v[80:83], v[146:149], v[242:245], v[80:83]
	v_mfma_i32_16x16x64_i8 v[72:75], v[186:189], v[242:245], v[72:75]
	v_mfma_i32_16x16x64_i8 v[124:127], v[190:193], v[206:209], v[124:127]
	v_mfma_i32_16x16x64_i8 v[116:119], v[198:201], v[206:209], v[116:119]
	v_mfma_i32_16x16x64_i8 v[108:111], v[190:193], v[214:217], v[108:111]
	v_mfma_i32_16x16x64_i8 v[100:103], v[198:201], v[214:217], v[100:103]
	v_mfma_i32_16x16x64_i8 v[92:95], v[190:193], v[222:225], v[92:95]
	v_mfma_i32_16x16x64_i8 v[84:87], v[198:201], v[222:225], v[84:87]
	v_mfma_i32_16x16x64_i8 v[76:79], v[190:193], v[238:241], v[76:79]
	v_mfma_i32_16x16x64_i8 v[68:71], v[198:201], v[238:241], v[68:71]
	v_mfma_i32_16x16x64_i8 v[124:127], v[194:197], v[210:213], v[124:127]
	v_mfma_i32_16x16x64_i8 v[116:119], v[202:205], v[210:213], v[116:119]
	v_mfma_i32_16x16x64_i8 v[108:111], v[194:197], v[218:221], v[108:111]
	v_mfma_i32_16x16x64_i8 v[100:103], v[202:205], v[218:221], v[100:103]
	v_mfma_i32_16x16x64_i8 v[92:95], v[194:197], v[234:237], v[92:95]
	v_mfma_i32_16x16x64_i8 v[84:87], v[202:205], v[234:237], v[84:87]
	v_mfma_i32_16x16x64_i8 v[76:79], v[194:197], v[242:245], v[76:79]
	v_mfma_i32_16x16x64_i8 v[68:71], v[202:205], v[242:245], v[68:71]
	s_setprio 0
	s_barrier
; #define PG8_STAGE(bufoff, gbase, voff) do { _Pragma("unroll") for (int _i = 0; _i < 2; ++_i) \
;         __builtin_amdgcn_global_load_lds((const unsigned*)((const char*)(gbase) + (voff)[_i]), (PG8_LAS unsigned*)(lds + (bufoff) + ldsw + _i * 8192), 16, 0, 0); } while (0)
; #define PG8_LDA(dst, b, h) do { _Pragma("unroll") for (int m = 0; m < 4; ++m) _Pragma("unroll") for (int k = 0; k < 2; ++k) dst[m][k] = *(const PG8_LAS bf16x8*)(lds + PG8_SA(b, h) + aoff + m * 2048 + k * 1024); } while (0)
; #define PG8_WAIT_V(n) asm volatile("s_waitcnt vmcnt(" #n ")" ::: "memory")
; #define PG8_WAIT_L(n) asm volatile("s_waitcnt lgkmcnt(" #n ")" ::: "memory")
; #define PG8_BAR __builtin_amdgcn_s_barrier()
; #define PG8_SCHED __builtin_amdgcn_sched_barrier(0)
;     __device__ __forceinline__ void operator()(const f32x4 (&acc)[2][2][4][2], const Unit& u, int wr, int wc, int fr, int fq) const {
;     ...
;             for (int m = 0; m < 4; ++m) { const size_t ro = (size_t)(row0 + ai * HALF + m * 16) * ldc + col0;
;                 float r[8]; const float scr_ = rs ? rs[row0 + ai * HALF + m * 16] * sc : sc;
;     ...
;             PG8_LDA(At, 1, 1); PG8_STAGE(PG8_SB(1, 0), b3, voffB); PG8_STAGE(PG8_SB(1, 1), b3 + hstepB, voffB); PG8_STAGE(PG8_SA(1, 0), a3, voffA);
;             PG8_WAIT_V(8); PG8_WAIT_L(0); PG8_BAR; PG8_MMA(1, 0, At, B0); PG8_MMA(1, 1, At, B1); PG8_BAR; PG8_SCHED;
	s_add_i32 s63, s63, s10
	s_mov_b32 m0, s63
	ds_read_b128 v[206:209], v156 offset:49152
	ds_read_b128 v[210:213], v156 offset:50176
	ds_read_b128 v[214:217], v156 offset:51200
	ds_read_b128 v[218:221], v156 offset:52224
	ds_read_b128 v[222:225], v156 offset:53248
	ds_read_b128 v[234:237], v156 offset:54272
	ds_read_b128 v[238:241], v156 offset:55296
	ds_read_b128 v[242:245], v156 offset:56320
	s_add_u32 s98, s66, 0x80
	s_addc_u32 s99, s67, 0
	global_load_lds_dwordx4 v34, s[98:99]
	s_add_i32 m0, s63, 0x2000
	s_add_u32 s66, s66, 0x40080
	s_addc_u32 s67, s67, 0
	s_add_i32 s63, s68, s10
	s_add_u32 s98, s66, 0xfffc0000
	s_addc_u32 s99, s67, -1
	global_load_lds_dwordx4 v136, s[98:99]
	s_mov_b32 m0, s63
	s_nop 0
	global_load_lds_dwordx4 v34, s[66:67]
	s_add_i32 m0, s63, 0x2000
	s_nop 0
	global_load_lds_dwordx4 v136, s[66:67]
	s_mov_b32 m0, s86
	s_nop 0
	s_add_u32 s98, s74, 0x80
	s_addc_u32 s99, s75, 0
	global_load_lds_dwordx4 v132, s[98:99]
	s_mov_b32 m0, s87
	s_nop 0
	s_add_u32 s98, s74, 0x80
	s_addc_u32 s99, s75, 0
	global_load_lds_dwordx4 v134, s[98:99]
	s_waitcnt vmcnt(8)
	s_waitcnt lgkmcnt(0)
	s_barrier
	s_setprio 1
	v_mfma_i32_16x16x64_i8 v[64:67], v[142:145], v[206:209], v[64:67]
	v_mfma_i32_16x16x64_i8 v[56:59], v[158:161], v[206:209], v[56:59]
	v_mfma_i32_16x16x64_i8 v[48:51], v[142:145], v[214:217], v[48:51]
	v_mfma_i32_16x16x64_i8 v[40:43], v[158:161], v[214:217], v[40:43]
	v_mfma_i32_16x16x64_i8 v[30:33], v[142:145], v[222:225], v[30:33]
	v_mfma_i32_16x16x64_i8 v[22:25], v[158:161], v[222:225], v[22:25]
	v_mfma_i32_16x16x64_i8 v[14:17], v[142:145], v[238:241], v[14:17]
	v_mfma_i32_16x16x64_i8 v[6:9], v[158:161], v[238:241], v[6:9]
	v_mfma_i32_16x16x64_i8 v[64:67], v[146:149], v[210:213], v[64:67]
	v_mfma_i32_16x16x64_i8 v[56:59], v[186:189], v[210:213], v[56:59]
	v_mfma_i32_16x16x64_i8 v[48:51], v[146:149], v[218:221], v[48:51]
	v_mfma_i32_16x16x64_i8 v[40:43], v[186:189], v[218:221], v[40:43]
	v_mfma_i32_16x16x64_i8 v[30:33], v[146:149], v[234:237], v[30:33]
	v_mfma_i32_16x16x64_i8 v[22:25], v[186:189], v[234:237], v[22:25]
	v_mfma_i32_16x16x64_i8 v[14:17], v[146:149], v[242:245], v[14:17]
	v_mfma_i32_16x16x64_i8 v[6:9], v[186:189], v[242:245], v[6:9]
	v_mfma_i32_16x16x64_i8 v[60:63], v[190:193], v[206:209], v[60:63]
	v_mfma_i32_16x16x64_i8 v[52:55], v[198:201], v[206:209], v[52:55]
	v_mfma_i32_16x16x64_i8 v[44:47], v[190:193], v[214:217], v[44:47]
	v_mfma_i32_16x16x64_i8 v[36:39], v[198:201], v[214:217], v[36:39]
	v_mfma_i32_16x16x64_i8 v[26:29], v[190:193], v[222:225], v[26:29]
	v_mfma_i32_16x16x64_i8 v[18:21], v[198:201], v[222:225], v[18:21]
	v_mfma_i32_16x16x64_i8 v[10:13], v[190:193], v[238:241], v[10:13]
	v_mfma_i32_16x16x64_i8 v[2:5], v[198:201], v[238:241], v[2:5]
	v_mfma_i32_16x16x64_i8 v[60:63], v[194:197], v[210:213], v[60:63]
	v_mfma_i32_16x16x64_i8 v[52:55], v[202:205], v[210:213], v[52:55]
	v_mfma_i32_16x16x64_i8 v[44:47], v[194:197], v[218:221], v[44:47]
	v_mfma_i32_16x16x64_i8 v[36:39], v[202:205], v[218:221], v[36:39]
	v_mfma_i32_16x16x64_i8 v[26:29], v[194:197], v[234:237], v[26:29]
	v_mfma_i32_16x16x64_i8 v[18:21], v[202:205], v[234:237], v[18:21]
	v_mfma_i32_16x16x64_i8 v[10:13], v[194:197], v[242:245], v[10:13]
	v_mfma_i32_16x16x64_i8 v[2:5], v[202:205], v[242:245], v[2:5]
	s_setprio 0
	s_barrier
	s_add_i32 s57, s57, 2
	s_add_u32 s64, s64, 0x100
	s_addc_u32 s65, s65, 0
	s_add_u32 s45, s45, 0x100
	s_addc_u32 s55, s55, 0
	s_cmp_gt_u32 s57, 13
	s_cbranch_scc0 .LBB0_538
	v_lshl_add_u32 v144, s62, 8, v152
	v_ashrrev_i32_e32 v145, 31, v144
	v_lshl_add_u64 v[146:147], v[144:145], 2, s[50:51]
	global_load_dword v186, v[146:147], off
	global_load_dword v187, v[146:147], off offset:64
	global_load_dword v188, v[146:147], off offset:128
	global_load_dword v189, v[146:147], off offset:192
	global_load_dword v190, v[146:147], off offset:512
	global_load_dword v191, v[146:147], off offset:576
	global_load_dword v192, v[146:147], off offset:640
	global_load_dword v193, v[146:147], off offset:704
	s_and_b64 vcc, exec, s[52:53]
	s_cbranch_vccz .LBB0_541
	s_barrier

; #define PG8_STAGE(bufoff, gbase, voff) do { _Pragma("unroll") for (int _i = 0; _i < 2; ++_i) \
;         __builtin_amdgcn_global_load_lds((const unsigned*)((const char*)(gbase) + (voff)[_i]), (PG8_LAS unsigned*)(lds + (bufoff) + ldsw + _i * 8192), 16, 0, 0); } while (0)
; #define PG8_LDA(dst, b, h) do { _Pragma("unroll") for (int m = 0; m < 4; ++m) _Pragma("unroll") for (int k = 0; k < 2; ++k) dst[m][k] = *(const PG8_LAS bf16x8*)(lds + PG8_SA(b, h) + aoff + m * 2048 + k * 1024); } while (0)
; #define PG8_LDB(dst, b, h) do { _Pragma("unroll") for (int n = 0; n < 2; ++n) _Pragma("unroll") for (int k = 0; k < 2; ++k) dst[n][k] = *(const PG8_LAS bf16x8*)(lds + PG8_SB(b, h) + boff + n * 2048 + k * 1024); } while (0)
; #define PG8_WAIT_V(n) asm volatile("s_waitcnt vmcnt(" #n ")" ::: "memory")
; #define PG8_WAIT_L(n) asm volatile("s_waitcnt lgkmcnt(" #n ")" ::: "memory")
; #define PG8_BAR __builtin_amdgcn_s_barrier()
; #define PG8_SCHED __builtin_amdgcn_sched_barrier(0)
;     ...
;             const bool last = (t == nt - 2);
;             const char* a1 = cA + (size_t)(t + 1) * kstep;
;             const char* a2 = last ? nA : cA + (size_t)(t + 2) * kstep; const char* b2 = last ? nB : cB + (size_t)(t + 2) * kstep;
;             const char* a3 = a2 + kstep; const char* b3 = b2 + kstep;
;             if (last && has_next) S.a_ready(nxt);
;             if constexpr (SP2) {
;             PG8_LDB(B0, 0, 0); PG8_LDB(B1, 0, 1); PG8_SCHED; PG8_LDA(At, 0, 0); PG8_STAGE(PG8_SA(1, 1), a1 + hstepA, voffA);
;             PG8_WAIT_V(8); PG8_WAIT_L(0); PG8_BAR; PG8_MMA(0, 0, At, B0); PG8_MMA(0, 1, At, B1); PG8_BAR; PG8_SCHED;
;             PG8_LDA(At, 0, 1); PG8_STAGE(PG8_SB(0, 0), b2, voffB); PG8_STAGE(PG8_SB(0, 1), b2 + hstepB, voffB); PG8_STAGE(PG8_SA(0, 0), a2, voffA);
;             PG8_WAIT_V(8); PG8_WAIT_L(0); PG8_BAR; PG8_MMA(1, 0, At, B0); PG8_MMA(1, 1, At, B1); PG8_BAR; PG8_SCHED;
.LBB0_608:
	v_add_u32_e32 v226, 0x10000, v145
	s_add_u32 s52, s50, 0xfff80080
	s_addc_u32 s53, s51, -1
	s_add_i32 s63, 0, 0x10000
	s_cmp_eq_u32 s62, 28
	s_cselect_b32 s55, s37, s53
	s_cselect_b32 s54, s58, s52
	s_cselect_b32 s53, s31, s61
	s_cselect_b32 s52, s59, s60
	s_add_i32 s66, 0, 0x14000
	ds_read_b128 v[148:151], v226
	ds_read_b128 v[152:155], v226 offset:1024
	ds_read_b128 v[156:159], v226 offset:2048
	ds_read_b128 v[160:163], v226 offset:3072
	ds_read_b128 v[186:189], v226 offset:16384
	ds_read_b128 v[190:193], v226 offset:17408
	ds_read_b128 v[194:197], v226 offset:18432
	ds_read_b128 v[198:201], v226 offset:19456
	s_add_i32 m0, s12, 0xc000
	ds_read_b128 v[202:205], v147
	ds_read_b128 v[206:209], v147 offset:1024
	ds_read_b128 v[210:213], v147 offset:2048
	ds_read_b128 v[214:217], v147 offset:3072
	ds_read_b128 v[218:221], v147 offset:4096
	ds_read_b128 v[222:225], v147 offset:5120
	ds_read_b128 v[234:237], v147 offset:6144
	ds_read_b128 v[238:241], v147 offset:7168
	global_load_lds_dwordx4 v138, s[50:51]
	s_add_i32 m0, s12, 0xe000
	s_nop 0
	global_load_lds_dwordx4 v140, s[50:51]
	s_waitcnt vmcnt(8)
	s_waitcnt lgkmcnt(0)
	s_barrier
	s_setprio 1
	v_mfma_f32_16x16x32_bf16 v[128:131], v[148:151], v[202:205], v[128:131]
	v_mfma_f32_16x16x32_bf16 v[124:127], v[156:159], v[202:205], v[124:127]
	v_mfma_f32_16x16x32_bf16 v[112:115], v[148:151], v[210:213], v[112:115]
	v_mfma_f32_16x16x32_bf16 v[108:111], v[156:159], v[210:213], v[108:111]
	v_mfma_f32_16x16x32_bf16 v[96:99], v[148:151], v[218:221], v[96:99]
	v_mfma_f32_16x16x32_bf16 v[92:95], v[156:159], v[218:221], v[92:95]
	v_mfma_f32_16x16x32_bf16 v[80:83], v[148:151], v[234:237], v[80:83]
	v_mfma_f32_16x16x32_bf16 v[76:79], v[156:159], v[234:237], v[76:79]
	v_mfma_f32_16x16x32_bf16 v[128:131], v[152:155], v[206:209], v[128:131]
	v_mfma_f32_16x16x32_bf16 v[124:127], v[160:163], v[206:209], v[124:127]
	v_mfma_f32_16x16x32_bf16 v[112:115], v[152:155], v[214:217], v[112:115]
	v_mfma_f32_16x16x32_bf16 v[108:111], v[160:163], v[214:217], v[108:111]
	v_mfma_f32_16x16x32_bf16 v[96:99], v[152:155], v[222:225], v[96:99]
	v_mfma_f32_16x16x32_bf16 v[92:95], v[160:163], v[222:225], v[92:95]
	v_mfma_f32_16x16x32_bf16 v[80:83], v[152:155], v[238:241], v[80:83]
	v_mfma_f32_16x16x32_bf16 v[76:79], v[160:163], v[238:241], v[76:79]
	v_mfma_f32_16x16x32_bf16 v[120:123], v[186:189], v[202:205], v[120:123]
	v_mfma_f32_16x16x32_bf16 v[116:119], v[194:197], v[202:205], v[116:119]
	v_mfma_f32_16x16x32_bf16 v[104:107], v[186:189], v[210:213], v[104:107]
	v_mfma_f32_16x16x32_bf16 v[100:103], v[194:197], v[210:213], v[100:103]
	v_mfma_f32_16x16x32_bf16 v[88:91], v[186:189], v[218:221], v[88:91]
	v_mfma_f32_16x16x32_bf16 v[84:87], v[194:197], v[218:221], v[84:87]
	v_mfma_f32_16x16x32_bf16 v[72:75], v[186:189], v[234:237], v[72:75]
	v_mfma_f32_16x16x32_bf16 v[68:71], v[194:197], v[234:237], v[68:71]
	v_mfma_f32_16x16x32_bf16 v[120:123], v[190:193], v[206:209], v[120:123]
	v_mfma_f32_16x16x32_bf16 v[116:119], v[198:201], v[206:209], v[116:119]
	v_mfma_f32_16x16x32_bf16 v[104:107], v[190:193], v[214:217], v[104:107]
	v_mfma_f32_16x16x32_bf16 v[100:103], v[198:201], v[214:217], v[100:103]
	v_mfma_f32_16x16x32_bf16 v[88:91], v[190:193], v[222:225], v[88:91]
	v_mfma_f32_16x16x32_bf16 v[84:87], v[198:201], v[222:225], v[84:87]
	v_mfma_f32_16x16x32_bf16 v[72:75], v[190:193], v[238:241], v[72:75]
	v_mfma_f32_16x16x32_bf16 v[68:71], v[198:201], v[238:241], v[68:71]
	s_setprio 0
	s_barrier
	s_add_i32 s63, s63, s6
	s_mov_b32 m0, s63
	ds_read_b128 v[202:205], v147 offset:16384
	ds_read_b128 v[206:209], v147 offset:17408
	ds_read_b128 v[210:213], v147 offset:18432
	ds_read_b128 v[214:217], v147 offset:19456
	ds_read_b128 v[218:221], v147 offset:20480
	ds_read_b128 v[222:225], v147 offset:21504
	ds_read_b128 v[234:237], v147 offset:22528
	ds_read_b128 v[238:241], v147 offset:23552
	global_load_lds_dwordx4 v34, s[52:53]
	s_add_i32 m0, s63, 0x2000
	s_add_u32 s64, s52, 0x80000
	s_addc_u32 s65, s53, 0
	s_add_i32 s63, s66, s6
	global_load_lds_dwordx4 v132, s[52:53]
	s_mov_b32 m0, s63
	v_lshl_add_u64 v[244:245], s[54:55], 0, v[134:135]
	global_load_lds_dwordx4 v34, s[64:65]
	s_add_i32 m0, s63, 0x2000
	s_nop 0
	global_load_lds_dwordx4 v132, s[64:65]
	v_lshl_add_u64 v[242:243], s[54:55], 0, v[136:137]
	s_mov_b32 m0, s12
	s_nop 0
	global_load_lds_dwordx4 v136, s[54:55]
	s_mov_b32 m0, s13
	s_nop 0
	global_load_lds_dwordx4 v134, s[54:55]
	s_waitcnt vmcnt(8)
	s_waitcnt lgkmcnt(0)
	s_barrier
	s_setprio 1
	v_mfma_f32_16x16x32_bf16 v[64:67], v[148:151], v[202:205], v[64:67]
	v_mfma_f32_16x16x32_bf16 v[60:63], v[156:159], v[202:205], v[60:63]
	v_mfma_f32_16x16x32_bf16 v[48:51], v[148:151], v[210:213], v[48:51]
	v_mfma_f32_16x16x32_bf16 v[44:47], v[156:159], v[210:213], v[44:47]
	v_mfma_f32_16x16x32_bf16 v[30:33], v[148:151], v[218:221], v[30:33]
	v_mfma_f32_16x16x32_bf16 v[26:29], v[156:159], v[218:221], v[26:29]
	v_mfma_f32_16x16x32_bf16 v[14:17], v[148:151], v[234:237], v[14:17]
	v_mfma_f32_16x16x32_bf16 v[10:13], v[156:159], v[234:237], v[10:13]
	v_mfma_f32_16x16x32_bf16 v[64:67], v[152:155], v[206:209], v[64:67]
	v_mfma_f32_16x16x32_bf16 v[60:63], v[160:163], v[206:209], v[60:63]
	v_mfma_f32_16x16x32_bf16 v[48:51], v[152:155], v[214:217], v[48:51]
	v_mfma_f32_16x16x32_bf16 v[44:47], v[160:163], v[214:217], v[44:47]
	v_mfma_f32_16x16x32_bf16 v[30:33], v[152:155], v[222:225], v[30:33]
	v_mfma_f32_16x16x32_bf16 v[26:29], v[160:163], v[222:225], v[26:29]
	v_mfma_f32_16x16x32_bf16 v[14:17], v[152:155], v[238:241], v[14:17]
	v_mfma_f32_16x16x32_bf16 v[10:13], v[160:163], v[238:241], v[10:13]
	v_mfma_f32_16x16x32_bf16 v[56:59], v[186:189], v[202:205], v[56:59]
	v_mfma_f32_16x16x32_bf16 v[52:55], v[194:197], v[202:205], v[52:55]
	v_mfma_f32_16x16x32_bf16 v[40:43], v[186:189], v[210:213], v[40:43]
	v_mfma_f32_16x16x32_bf16 v[36:39], v[194:197], v[210:213], v[36:39]
	v_mfma_f32_16x16x32_bf16 v[22:25], v[186:189], v[218:221], v[22:25]
	v_mfma_f32_16x16x32_bf16 v[18:21], v[194:197], v[218:221], v[18:21]
	v_mfma_f32_16x16x32_bf16 v[6:9], v[186:189], v[234:237], v[6:9]
	v_mfma_f32_16x16x32_bf16 v[2:5], v[194:197], v[234:237], v[2:5]
	v_mfma_f32_16x16x32_bf16 v[56:59], v[190:193], v[206:209], v[56:59]
	v_mfma_f32_16x16x32_bf16 v[52:55], v[198:201], v[206:209], v[52:55]
	v_mfma_f32_16x16x32_bf16 v[40:43], v[190:193], v[214:217], v[40:43]
	v_mfma_f32_16x16x32_bf16 v[36:39], v[198:201], v[214:217], v[36:39]
	v_mfma_f32_16x16x32_bf16 v[22:25], v[190:193], v[222:225], v[22:25]
	v_mfma_f32_16x16x32_bf16 v[18:21], v[198:201], v[222:225], v[18:21]
	v_mfma_f32_16x16x32_bf16 v[6:9], v[190:193], v[238:241], v[6:9]
	v_mfma_f32_16x16x32_bf16 v[2:5], v[198:201], v[238:241], v[2:5]
	s_setprio 0
	s_barrier
; #define PG8_STAGE(bufoff, gbase, voff) do { _Pragma("unroll") for (int _i = 0; _i < 2; ++_i) \
;         __builtin_amdgcn_global_load_lds((const unsigned*)((const char*)(gbase) + (voff)[_i]), (PG8_LAS unsigned*)(lds + (bufoff) + ldsw + _i * 8192), 16, 0, 0); } while (0)
; #define PG8_LDA(dst, b, h) do { _Pragma("unroll") for (int m = 0; m < 4; ++m) _Pragma("unroll") for (int k = 0; k < 2; ++k) dst[m][k] = *(const PG8_LAS bf16x8*)(lds + PG8_SA(b, h) + aoff + m * 2048 + k * 1024); } while (0)
; #define PG8_LDB(dst, b, h) do { _Pragma("unroll") for (int n = 0; n < 2; ++n) _Pragma("unroll") for (int k = 0; k < 2; ++k) dst[n][k] = *(const PG8_LAS bf16x8*)(lds + PG8_SB(b, h) + boff + n * 2048 + k * 1024); } while (0)
; #define PG8_WAIT_V(n) asm volatile("s_waitcnt vmcnt(" #n ")" ::: "memory")
; #define PG8_WAIT_L(n) asm volatile("s_waitcnt lgkmcnt(" #n ")" ::: "memory")
; #define PG8_BAR __builtin_amdgcn_s_barrier()
; #define PG8_SCHED __builtin_amdgcn_sched_barrier(0)
;     ...
;             PG8_LDB(B0, 1, 0); PG8_LDB(B1, 1, 1); PG8_SCHED; PG8_LDA(At, 1, 0); PG8_STAGE(PG8_SA(0, 1), a2 + hstepA, voffA);
;             PG8_WAIT_V(8); PG8_WAIT_L(0); PG8_BAR; PG8_MMA(0, 0, At, B0); PG8_MMA(0, 1, At, B1); PG8_BAR; PG8_SCHED;
;             PG8_LDA(At, 1, 1); PG8_STAGE(PG8_SB(1, 0), b3, voffB); PG8_STAGE(PG8_SB(1, 1), b3 + hstepB, voffB); PG8_STAGE(PG8_SA(1, 0), a3, voffA);
;             PG8_WAIT_V(8); PG8_WAIT_L(0); PG8_BAR; PG8_MMA(1, 0, At, B0); PG8_MMA(1, 1, At, B1); PG8_BAR; PG8_SCHED;
	s_add_i32 s63, 0, 0x18000
	s_add_i32 s64, 0, 0x1c000
	ds_read_b128 v[148:151], v226 offset:32768
	ds_read_b128 v[152:155], v226 offset:33792
	ds_read_b128 v[156:159], v226 offset:34816
	ds_read_b128 v[160:163], v226 offset:35840
	ds_read_b128 v[186:189], v226 offset:49152
	ds_read_b128 v[190:193], v226 offset:50176
	ds_read_b128 v[194:197], v226 offset:51200
	ds_read_b128 v[198:201], v226 offset:52224
	s_add_u32 s54, s54, 0x80000
	s_addc_u32 s55, s55, 0
	s_mov_b32 m0, s15
	ds_read_b128 v[202:205], v147 offset:32768
	ds_read_b128 v[206:209], v147 offset:33792
	ds_read_b128 v[210:213], v147 offset:34816
	ds_read_b128 v[214:217], v147 offset:35840
	ds_read_b128 v[218:221], v147 offset:36864
	ds_read_b128 v[222:225], v147 offset:37888
	ds_read_b128 v[234:237], v147 offset:38912
	ds_read_b128 v[238:241], v147 offset:39936
	global_load_lds_dwordx4 v136, s[54:55]
	s_mov_b32 m0, s34
	s_nop 0
	global_load_lds_dwordx4 v134, s[54:55]
	s_waitcnt vmcnt(8)
	s_waitcnt lgkmcnt(0)
	s_barrier
	s_setprio 1
	v_mfma_f32_16x16x32_bf16 v[128:131], v[148:151], v[202:205], v[128:131]
	v_mfma_f32_16x16x32_bf16 v[124:127], v[156:159], v[202:205], v[124:127]
	v_mfma_f32_16x16x32_bf16 v[112:115], v[148:151], v[210:213], v[112:115]
	v_mfma_f32_16x16x32_bf16 v[108:111], v[156:159], v[210:213], v[108:111]
	v_mfma_f32_16x16x32_bf16 v[96:99], v[148:151], v[218:221], v[96:99]
	v_mfma_f32_16x16x32_bf16 v[92:95], v[156:159], v[218:221], v[92:95]
	v_mfma_f32_16x16x32_bf16 v[80:83], v[148:151], v[234:237], v[80:83]
	v_mfma_f32_16x16x32_bf16 v[76:79], v[156:159], v[234:237], v[76:79]
	v_mfma_f32_16x16x32_bf16 v[128:131], v[152:155], v[206:209], v[128:131]
	v_mfma_f32_16x16x32_bf16 v[124:127], v[160:163], v[206:209], v[124:127]
	v_mfma_f32_16x16x32_bf16 v[112:115], v[152:155], v[214:217], v[112:115]
	v_mfma_f32_16x16x32_bf16 v[108:111], v[160:163], v[214:217], v[108:111]
	v_mfma_f32_16x16x32_bf16 v[96:99], v[152:155], v[222:225], v[96:99]
	v_mfma_f32_16x16x32_bf16 v[92:95], v[160:163], v[222:225], v[92:95]
	v_mfma_f32_16x16x32_bf16 v[80:83], v[152:155], v[238:241], v[80:83]
	v_mfma_f32_16x16x32_bf16 v[76:79], v[160:163], v[238:241], v[76:79]
	v_mfma_f32_16x16x32_bf16 v[120:123], v[186:189], v[202:205], v[120:123]
	v_mfma_f32_16x16x32_bf16 v[116:119], v[194:197], v[202:205], v[116:119]
	v_mfma_f32_16x16x32_bf16 v[104:107], v[186:189], v[210:213], v[104:107]
	v_mfma_f32_16x16x32_bf16 v[100:103], v[194:197], v[210:213], v[100:103]
	v_mfma_f32_16x16x32_bf16 v[88:91], v[186:189], v[218:221], v[88:91]
	v_mfma_f32_16x16x32_bf16 v[84:87], v[194:197], v[218:221], v[84:87]
	v_mfma_f32_16x16x32_bf16 v[72:75], v[186:189], v[234:237], v[72:75]
	v_mfma_f32_16x16x32_bf16 v[68:71], v[194:197], v[234:237], v[68:71]
	v_mfma_f32_16x16x32_bf16 v[120:123], v[190:193], v[206:209], v[120:123]
	v_mfma_f32_16x16x32_bf16 v[116:119], v[198:201], v[206:209], v[116:119]
	v_mfma_f32_16x16x32_bf16 v[104:107], v[190:193], v[214:217], v[104:107]
	v_mfma_f32_16x16x32_bf16 v[100:103], v[198:201], v[214:217], v[100:103]
	v_mfma_f32_16x16x32_bf16 v[88:91], v[190:193], v[222:225], v[88:91]
	v_mfma_f32_16x16x32_bf16 v[84:87], v[198:201], v[222:225], v[84:87]
	v_mfma_f32_16x16x32_bf16 v[72:75], v[190:193], v[238:241], v[72:75]
	v_mfma_f32_16x16x32_bf16 v[68:71], v[198:201], v[238:241], v[68:71]
	s_setprio 0
	s_barrier
	s_add_i32 s54, s63, s6
	s_mov_b32 m0, s54
	ds_read_b128 v[202:205], v147 offset:49152
	ds_read_b128 v[206:209], v147 offset:50176
	ds_read_b128 v[210:213], v147 offset:51200
	ds_read_b128 v[214:217], v147 offset:52224
	ds_read_b128 v[218:221], v147 offset:53248
	ds_read_b128 v[222:225], v147 offset:54272
	ds_read_b128 v[234:237], v147 offset:55296
	ds_read_b128 v[238:241], v147 offset:56320
	s_add_u32 s98, s52, 0x80
	s_addc_u32 s99, s53, 0
	global_load_lds_dwordx4 v34, s[98:99]
	s_add_i32 m0, s54, 0x2000
	s_add_u32 s52, s52, 0x80080
	s_addc_u32 s53, s53, 0
	s_add_i32 s54, s64, s6
	s_add_u32 s98, s52, 0xfff80000
	s_addc_u32 s99, s53, -1
	global_load_lds_dwordx4 v132, s[98:99]
	s_mov_b32 m0, s54
	s_nop 0
	global_load_lds_dwordx4 v34, s[52:53]
	s_add_i32 m0, s54, 0x2000
	s_nop 0
	global_load_lds_dwordx4 v132, s[52:53]
	v_lshl_add_u64 v[142:143], v[242:243], 0, s[22:23]
	s_mov_b32 m0, s24
	s_nop 0
	global_load_lds_dwordx4 v[142:143], off
	v_lshl_add_u64 v[142:143], v[244:245], 0, s[22:23]
	s_mov_b32 m0, s35
	s_nop 0
	global_load_lds_dwordx4 v[142:143], off
	s_waitcnt vmcnt(8)
	s_waitcnt lgkmcnt(0)
	s_barrier
	s_setprio 1
	v_mfma_f32_16x16x32_bf16 v[64:67], v[148:151], v[202:205], v[64:67]
	v_mfma_f32_16x16x32_bf16 v[60:63], v[156:159], v[202:205], v[60:63]
	v_mfma_f32_16x16x32_bf16 v[48:51], v[148:151], v[210:213], v[48:51]
	v_mfma_f32_16x16x32_bf16 v[44:47], v[156:159], v[210:213], v[44:47]
	v_mfma_f32_16x16x32_bf16 v[30:33], v[148:151], v[218:221], v[30:33]
	v_mfma_f32_16x16x32_bf16 v[26:29], v[156:159], v[218:221], v[26:29]
	v_mfma_f32_16x16x32_bf16 v[14:17], v[148:151], v[234:237], v[14:17]
	v_mfma_f32_16x16x32_bf16 v[10:13], v[156:159], v[234:237], v[10:13]
	v_mfma_f32_16x16x32_bf16 v[64:67], v[152:155], v[206:209], v[64:67]
	v_mfma_f32_16x16x32_bf16 v[60:63], v[160:163], v[206:209], v[60:63]
	v_mfma_f32_16x16x32_bf16 v[48:51], v[152:155], v[214:217], v[48:51]
	v_mfma_f32_16x16x32_bf16 v[44:47], v[160:163], v[214:217], v[44:47]
	v_mfma_f32_16x16x32_bf16 v[30:33], v[152:155], v[222:225], v[30:33]
	v_mfma_f32_16x16x32_bf16 v[26:29], v[160:163], v[222:225], v[26:29]
	v_mfma_f32_16x16x32_bf16 v[14:17], v[152:155], v[238:241], v[14:17]
	v_mfma_f32_16x16x32_bf16 v[10:13], v[160:163], v[238:241], v[10:13]
	v_mfma_f32_16x16x32_bf16 v[56:59], v[186:189], v[202:205], v[56:59]
	v_mfma_f32_16x16x32_bf16 v[52:55], v[194:197], v[202:205], v[52:55]
	v_mfma_f32_16x16x32_bf16 v[40:43], v[186:189], v[210:213], v[40:43]
	v_mfma_f32_16x16x32_bf16 v[36:39], v[194:197], v[210:213], v[36:39]
	v_mfma_f32_16x16x32_bf16 v[22:25], v[186:189], v[218:221], v[22:25]
	v_mfma_f32_16x16x32_bf16 v[18:21], v[194:197], v[218:221], v[18:21]
	v_mfma_f32_16x16x32_bf16 v[6:9], v[186:189], v[234:237], v[6:9]
	v_mfma_f32_16x16x32_bf16 v[2:5], v[194:197], v[234:237], v[2:5]
	v_mfma_f32_16x16x32_bf16 v[56:59], v[190:193], v[206:209], v[56:59]
	v_mfma_f32_16x16x32_bf16 v[52:55], v[198:201], v[206:209], v[52:55]
	v_mfma_f32_16x16x32_bf16 v[40:43], v[190:193], v[214:217], v[40:43]
	v_mfma_f32_16x16x32_bf16 v[36:39], v[198:201], v[214:217], v[36:39]
	v_mfma_f32_16x16x32_bf16 v[22:25], v[190:193], v[222:225], v[22:25]
	v_mfma_f32_16x16x32_bf16 v[18:21], v[198:201], v[222:225], v[18:21]
	v_mfma_f32_16x16x32_bf16 v[6:9], v[190:193], v[238:241], v[6:9]
	v_mfma_f32_16x16x32_bf16 v[2:5], v[198:201], v[238:241], v[2:5]
	s_setprio 0
	s_barrier
	s_add_i32 s62, s62, 2
	s_add_u32 s50, s50, 0x100
	s_addc_u32 s51, s51, 0
	s_add_u32 s60, s60, 0x100
	s_addc_u32 s61, s61, 0
	s_cmp_gt_u32 s62, 29
	s_cbranch_scc0 .LBB0_608
	s_and_b64 vcc, exec, s[28:29]
	s_cbranch_vccz .LBB0_611
	s_barrier

; #define PG8_STAGE(bufoff, gbase, voff) do { _Pragma("unroll") for (int _i = 0; _i < 2; ++_i) \
;         __builtin_amdgcn_global_load_lds((const unsigned*)((const char*)(gbase) + (voff)[_i]), (PG8_LAS unsigned*)(lds + (bufoff) + ldsw + _i * 8192), 16, 0, 0); } while (0)
; #define PG8_LDA(dst, b, h) do { _Pragma("unroll") for (int m = 0; m < 4; ++m) _Pragma("unroll") for (int k = 0; k < 2; ++k) dst[m][k] = *(const PG8_LAS bf16x8*)(lds + PG8_SA(b, h) + aoff + m * 2048 + k * 1024); } while (0)
; #define PG8_LDB(dst, b, h) do { _Pragma("unroll") for (int n = 0; n < 2; ++n) _Pragma("unroll") for (int k = 0; k < 2; ++k) dst[n][k] = *(const PG8_LAS bf16x8*)(lds + PG8_SB(b, h) + boff + n * 2048 + k * 1024); } while (0)
; #define PG8_WAIT_V(n) asm volatile("s_waitcnt vmcnt(" #n ")" ::: "memory")
; #define PG8_WAIT_L(n) asm volatile("s_waitcnt lgkmcnt(" #n ")" ::: "memory")
; #define PG8_BAR __builtin_amdgcn_s_barrier()
; #define PG8_SCHED __builtin_amdgcn_sched_barrier(0)
;     ...
;             const bool last = (t == nt - 2);
;             const char* a1 = cA + (size_t)(t + 1) * kstep;
;             const char* a2 = last ? nA : cA + (size_t)(t + 2) * kstep; const char* b2 = last ? nB : cB + (size_t)(t + 2) * kstep;
;             const char* a3 = a2 + kstep; const char* b3 = b2 + kstep;
;             if (last && has_next) S.a_ready(nxt);
;             if constexpr (SP2) {
;             PG8_LDB(B0, 0, 0); PG8_LDB(B1, 0, 1); PG8_SCHED; PG8_LDA(At, 0, 0); PG8_STAGE(PG8_SA(1, 1), a1 + hstepA, voffA);
;             PG8_WAIT_V(8); PG8_WAIT_L(0); PG8_BAR; PG8_MMA(0, 0, At, B0); PG8_MMA(0, 1, At, B1); PG8_BAR; PG8_SCHED;
;             PG8_LDA(At, 0, 1); PG8_STAGE(PG8_SB(0, 0), b2, voffB); PG8_STAGE(PG8_SB(0, 1), b2 + hstepB, voffB); PG8_STAGE(PG8_SA(0, 0), a2, voffA);
;             PG8_WAIT_V(8); PG8_WAIT_L(0); PG8_BAR; PG8_MMA(1, 0, At, B0); PG8_MMA(1, 1, At, B1); PG8_BAR; PG8_SCHED;
.LBB0_694:
	v_add_u32_e32 v242, 0x10000, v143
	s_add_u32 s44, s42, 0x100
	s_addc_u32 s45, s43, 0
	s_add_i32 s67, 0, 0x10000
	s_cmpk_eq_i32 s66, 0x54
	s_cselect_b32 s53, s37, s45
	s_cselect_b32 s52, s36, s44
	s_cselect_b32 s51, s41, s65
	s_cselect_b32 s50, s40, s64
	s_add_i32 s68, 0, 0x14000
	ds_read_b128 v[146:149], v242
	ds_read_b128 v[150:153], v242 offset:1024
	ds_read_b128 v[154:157], v242 offset:2048
	ds_read_b128 v[158:161], v242 offset:3072
	ds_read_b128 v[186:189], v242 offset:16384
	ds_read_b128 v[190:193], v242 offset:17408
	ds_read_b128 v[194:197], v242 offset:18432
	ds_read_b128 v[198:201], v242 offset:19456
	s_add_i32 m0, s34, 0xc000
	ds_read_b128 v[202:205], v145
	ds_read_b128 v[206:209], v145 offset:1024
	ds_read_b128 v[210:213], v145 offset:2048
	ds_read_b128 v[214:217], v145 offset:3072
	ds_read_b128 v[218:221], v145 offset:4096
	ds_read_b128 v[222:225], v145 offset:5120
	ds_read_b128 v[234:237], v145 offset:6144
	ds_read_b128 v[238:241], v145 offset:7168
	global_load_lds_dwordx4 v138, s[42:43]
	s_add_i32 m0, s34, 0xe000
	s_nop 0
	global_load_lds_dwordx4 v140, s[42:43]
	s_waitcnt vmcnt(8)
	s_waitcnt lgkmcnt(0)
	s_barrier
	s_setprio 1
	v_mfma_f32_16x16x32_bf16 v[128:131], v[146:149], v[202:205], v[128:131]
	v_mfma_f32_16x16x32_bf16 v[124:127], v[154:157], v[202:205], v[124:127]
	v_mfma_f32_16x16x32_bf16 v[120:123], v[146:149], v[210:213], v[120:123]
	v_mfma_f32_16x16x32_bf16 v[116:119], v[154:157], v[210:213], v[116:119]
	v_mfma_f32_16x16x32_bf16 v[104:107], v[146:149], v[218:221], v[104:107]
	v_mfma_f32_16x16x32_bf16 v[100:103], v[154:157], v[218:221], v[100:103]
	v_mfma_f32_16x16x32_bf16 v[88:91], v[146:149], v[234:237], v[88:91]
	v_mfma_f32_16x16x32_bf16 v[84:87], v[154:157], v[234:237], v[84:87]
	v_mfma_f32_16x16x32_bf16 v[128:131], v[150:153], v[206:209], v[128:131]
	v_mfma_f32_16x16x32_bf16 v[124:127], v[158:161], v[206:209], v[124:127]
	v_mfma_f32_16x16x32_bf16 v[120:123], v[150:153], v[214:217], v[120:123]
	v_mfma_f32_16x16x32_bf16 v[116:119], v[158:161], v[214:217], v[116:119]
	v_mfma_f32_16x16x32_bf16 v[104:107], v[150:153], v[222:225], v[104:107]
	v_mfma_f32_16x16x32_bf16 v[100:103], v[158:161], v[222:225], v[100:103]
	v_mfma_f32_16x16x32_bf16 v[88:91], v[150:153], v[238:241], v[88:91]
	v_mfma_f32_16x16x32_bf16 v[84:87], v[158:161], v[238:241], v[84:87]
	v_mfma_f32_16x16x32_bf16 v[112:115], v[186:189], v[202:205], v[112:115]
	v_mfma_f32_16x16x32_bf16 v[108:111], v[194:197], v[202:205], v[108:111]
	v_mfma_f32_16x16x32_bf16 v[96:99], v[186:189], v[210:213], v[96:99]
	v_mfma_f32_16x16x32_bf16 v[92:95], v[194:197], v[210:213], v[92:95]
	v_mfma_f32_16x16x32_bf16 v[80:83], v[186:189], v[218:221], v[80:83]
	v_mfma_f32_16x16x32_bf16 v[76:79], v[194:197], v[218:221], v[76:79]
	v_mfma_f32_16x16x32_bf16 v[72:75], v[186:189], v[234:237], v[72:75]
	v_mfma_f32_16x16x32_bf16 v[68:71], v[194:197], v[234:237], v[68:71]
	v_mfma_f32_16x16x32_bf16 v[112:115], v[190:193], v[206:209], v[112:115]
	v_mfma_f32_16x16x32_bf16 v[108:111], v[198:201], v[206:209], v[108:111]
	v_mfma_f32_16x16x32_bf16 v[96:99], v[190:193], v[214:217], v[96:99]
	v_mfma_f32_16x16x32_bf16 v[92:95], v[198:201], v[214:217], v[92:95]
	v_mfma_f32_16x16x32_bf16 v[80:83], v[190:193], v[222:225], v[80:83]
	v_mfma_f32_16x16x32_bf16 v[76:79], v[198:201], v[222:225], v[76:79]
	v_mfma_f32_16x16x32_bf16 v[72:75], v[190:193], v[238:241], v[72:75]
	v_mfma_f32_16x16x32_bf16 v[68:71], v[198:201], v[238:241], v[68:71]
	s_setprio 0
	s_barrier
	s_add_i32 s42, s67, s15
	s_mov_b32 m0, s42
	ds_read_b128 v[202:205], v145 offset:16384
	ds_read_b128 v[206:209], v145 offset:17408
	ds_read_b128 v[210:213], v145 offset:18432
	ds_read_b128 v[214:217], v145 offset:19456
	ds_read_b128 v[218:221], v145 offset:20480
	ds_read_b128 v[222:225], v145 offset:21504
	ds_read_b128 v[234:237], v145 offset:22528
	ds_read_b128 v[238:241], v145 offset:23552
	global_load_lds_dwordx4 v34, s[50:51]
	s_add_i32 m0, s42, 0x2000
	s_add_u32 s42, s50, 0x160000
	v_lshl_add_u64 v[226:227], s[50:51], 0, v[136:137]
	s_addc_u32 s43, s51, 0
	s_add_i32 s67, s68, s15
	global_load_lds_dwordx4 v136, s[50:51]
	s_mov_b32 m0, s67
	s_nop 0
	global_load_lds_dwordx4 v34, s[42:43]
	s_add_i32 m0, s67, 0x2000
	s_nop 0
	global_load_lds_dwordx4 v136, s[42:43]
	s_mov_b32 m0, s34
	s_nop 0
	global_load_lds_dwordx4 v132, s[52:53]
	s_mov_b32 m0, s35
	s_nop 0
	global_load_lds_dwordx4 v134, s[52:53]
	s_waitcnt vmcnt(8)
	s_waitcnt lgkmcnt(0)
	s_barrier
	s_setprio 1
	v_mfma_f32_16x16x32_bf16 v[64:67], v[146:149], v[202:205], v[64:67]
	v_mfma_f32_16x16x32_bf16 v[60:63], v[154:157], v[202:205], v[60:63]
	v_mfma_f32_16x16x32_bf16 v[56:59], v[146:149], v[210:213], v[56:59]
	v_mfma_f32_16x16x32_bf16 v[52:55], v[154:157], v[210:213], v[52:55]
	v_mfma_f32_16x16x32_bf16 v[40:43], v[146:149], v[218:221], v[40:43]
	v_mfma_f32_16x16x32_bf16 v[36:39], v[154:157], v[218:221], v[36:39]
	v_mfma_f32_16x16x32_bf16 v[22:25], v[146:149], v[234:237], v[22:25]
	v_mfma_f32_16x16x32_bf16 v[18:21], v[154:157], v[234:237], v[18:21]
	v_mfma_f32_16x16x32_bf16 v[64:67], v[150:153], v[206:209], v[64:67]
	v_mfma_f32_16x16x32_bf16 v[60:63], v[158:161], v[206:209], v[60:63]
	v_mfma_f32_16x16x32_bf16 v[56:59], v[150:153], v[214:217], v[56:59]
	v_mfma_f32_16x16x32_bf16 v[52:55], v[158:161], v[214:217], v[52:55]
	v_mfma_f32_16x16x32_bf16 v[40:43], v[150:153], v[222:225], v[40:43]
	v_mfma_f32_16x16x32_bf16 v[36:39], v[158:161], v[222:225], v[36:39]
	v_mfma_f32_16x16x32_bf16 v[22:25], v[150:153], v[238:241], v[22:25]
	v_mfma_f32_16x16x32_bf16 v[18:21], v[158:161], v[238:241], v[18:21]
	v_mfma_f32_16x16x32_bf16 v[48:51], v[186:189], v[202:205], v[48:51]
	v_mfma_f32_16x16x32_bf16 v[44:47], v[194:197], v[202:205], v[44:47]
	v_mfma_f32_16x16x32_bf16 v[30:33], v[186:189], v[210:213], v[30:33]
	v_mfma_f32_16x16x32_bf16 v[26:29], v[194:197], v[210:213], v[26:29]
	v_mfma_f32_16x16x32_bf16 v[14:17], v[186:189], v[218:221], v[14:17]
	v_mfma_f32_16x16x32_bf16 v[10:13], v[194:197], v[218:221], v[10:13]
	v_mfma_f32_16x16x32_bf16 v[6:9], v[186:189], v[234:237], v[6:9]
	v_mfma_f32_16x16x32_bf16 v[2:5], v[194:197], v[234:237], v[2:5]
	v_mfma_f32_16x16x32_bf16 v[48:51], v[190:193], v[206:209], v[48:51]
	v_mfma_f32_16x16x32_bf16 v[44:47], v[198:201], v[206:209], v[44:47]
	v_mfma_f32_16x16x32_bf16 v[30:33], v[190:193], v[214:217], v[30:33]
	v_mfma_f32_16x16x32_bf16 v[26:29], v[198:201], v[214:217], v[26:29]
	v_mfma_f32_16x16x32_bf16 v[14:17], v[190:193], v[222:225], v[14:17]
	v_mfma_f32_16x16x32_bf16 v[10:13], v[198:201], v[222:225], v[10:13]
	v_mfma_f32_16x16x32_bf16 v[6:9], v[190:193], v[238:241], v[6:9]
	v_mfma_f32_16x16x32_bf16 v[2:5], v[198:201], v[238:241], v[2:5]
	s_setprio 0
	s_barrier
; #define PG8_STAGE(bufoff, gbase, voff) do { _Pragma("unroll") for (int _i = 0; _i < 2; ++_i) \
;         __builtin_amdgcn_global_load_lds((const unsigned*)((const char*)(gbase) + (voff)[_i]), (PG8_LAS unsigned*)(lds + (bufoff) + ldsw + _i * 8192), 16, 0, 0); } while (0)
; #define PG8_LDA(dst, b, h) do { _Pragma("unroll") for (int m = 0; m < 4; ++m) _Pragma("unroll") for (int k = 0; k < 2; ++k) dst[m][k] = *(const PG8_LAS bf16x8*)(lds + PG8_SA(b, h) + aoff + m * 2048 + k * 1024); } while (0)
; #define PG8_LDB(dst, b, h) do { _Pragma("unroll") for (int n = 0; n < 2; ++n) _Pragma("unroll") for (int k = 0; k < 2; ++k) dst[n][k] = *(const PG8_LAS bf16x8*)(lds + PG8_SB(b, h) + boff + n * 2048 + k * 1024); } while (0)
; #define PG8_WAIT_V(n) asm volatile("s_waitcnt vmcnt(" #n ")" ::: "memory")
; #define PG8_WAIT_L(n) asm volatile("s_waitcnt lgkmcnt(" #n ")" ::: "memory")
; #define PG8_BAR __builtin_amdgcn_s_barrier()
; #define PG8_SCHED __builtin_amdgcn_sched_barrier(0)
;     ...
;             PG8_LDB(B0, 1, 0); PG8_LDB(B1, 1, 1); PG8_SCHED; PG8_LDA(At, 1, 0); PG8_STAGE(PG8_SA(0, 1), a2 + hstepA, voffA);
;             PG8_WAIT_V(8); PG8_WAIT_L(0); PG8_BAR; PG8_MMA(0, 0, At, B0); PG8_MMA(0, 1, At, B1); PG8_BAR; PG8_SCHED;
;             PG8_LDA(At, 1, 1); PG8_STAGE(PG8_SB(1, 0), b3, voffB); PG8_STAGE(PG8_SB(1, 1), b3 + hstepB, voffB); PG8_STAGE(PG8_SA(1, 0), a3, voffA);
;             PG8_WAIT_V(8); PG8_WAIT_L(0); PG8_BAR; PG8_MMA(1, 0, At, B0); PG8_MMA(1, 1, At, B1); PG8_BAR; PG8_SCHED;
	s_add_i32 s67, 0, 0x18000
	s_add_i32 s68, 0, 0x1c000
	ds_read_b128 v[146:149], v242 offset:32768
	ds_read_b128 v[150:153], v242 offset:33792
	ds_read_b128 v[154:157], v242 offset:34816
	ds_read_b128 v[158:161], v242 offset:35840
	ds_read_b128 v[186:189], v242 offset:49152
	ds_read_b128 v[190:193], v242 offset:50176
	ds_read_b128 v[194:197], v242 offset:51200
	ds_read_b128 v[198:201], v242 offset:52224
	s_add_u32 s42, s52, 0x160000
	s_addc_u32 s43, s53, 0
	s_mov_b32 m0, s54
	ds_read_b128 v[202:205], v145 offset:32768
	ds_read_b128 v[206:209], v145 offset:33792
	ds_read_b128 v[210:213], v145 offset:34816
	ds_read_b128 v[214:217], v145 offset:35840
	ds_read_b128 v[218:221], v145 offset:36864
	ds_read_b128 v[222:225], v145 offset:37888
	ds_read_b128 v[234:237], v145 offset:38912
	ds_read_b128 v[238:241], v145 offset:39936
	global_load_lds_dwordx4 v132, s[42:43]
	s_mov_b32 m0, s55
	s_nop 0
	global_load_lds_dwordx4 v134, s[42:43]
	s_waitcnt vmcnt(8)
	s_waitcnt lgkmcnt(0)
	s_barrier
	s_setprio 1
	v_mfma_f32_16x16x32_bf16 v[128:131], v[146:149], v[202:205], v[128:131]
	v_mfma_f32_16x16x32_bf16 v[124:127], v[154:157], v[202:205], v[124:127]
	v_mfma_f32_16x16x32_bf16 v[120:123], v[146:149], v[210:213], v[120:123]
	v_mfma_f32_16x16x32_bf16 v[116:119], v[154:157], v[210:213], v[116:119]
	v_mfma_f32_16x16x32_bf16 v[104:107], v[146:149], v[218:221], v[104:107]
	v_mfma_f32_16x16x32_bf16 v[100:103], v[154:157], v[218:221], v[100:103]
	v_mfma_f32_16x16x32_bf16 v[88:91], v[146:149], v[234:237], v[88:91]
	v_mfma_f32_16x16x32_bf16 v[84:87], v[154:157], v[234:237], v[84:87]
	v_mfma_f32_16x16x32_bf16 v[128:131], v[150:153], v[206:209], v[128:131]
	v_mfma_f32_16x16x32_bf16 v[124:127], v[158:161], v[206:209], v[124:127]
	v_mfma_f32_16x16x32_bf16 v[120:123], v[150:153], v[214:217], v[120:123]
	v_mfma_f32_16x16x32_bf16 v[116:119], v[158:161], v[214:217], v[116:119]
	v_mfma_f32_16x16x32_bf16 v[104:107], v[150:153], v[222:225], v[104:107]
	v_mfma_f32_16x16x32_bf16 v[100:103], v[158:161], v[222:225], v[100:103]
	v_mfma_f32_16x16x32_bf16 v[88:91], v[150:153], v[238:241], v[88:91]
	v_mfma_f32_16x16x32_bf16 v[84:87], v[158:161], v[238:241], v[84:87]
	v_mfma_f32_16x16x32_bf16 v[112:115], v[186:189], v[202:205], v[112:115]
	v_mfma_f32_16x16x32_bf16 v[108:111], v[194:197], v[202:205], v[108:111]
	v_mfma_f32_16x16x32_bf16 v[96:99], v[186:189], v[210:213], v[96:99]
	v_mfma_f32_16x16x32_bf16 v[92:95], v[194:197], v[210:213], v[92:95]
	v_mfma_f32_16x16x32_bf16 v[80:83], v[186:189], v[218:221], v[80:83]
	v_mfma_f32_16x16x32_bf16 v[76:79], v[194:197], v[218:221], v[76:79]
	v_mfma_f32_16x16x32_bf16 v[72:75], v[186:189], v[234:237], v[72:75]
	v_mfma_f32_16x16x32_bf16 v[68:71], v[194:197], v[234:237], v[68:71]
	v_mfma_f32_16x16x32_bf16 v[112:115], v[190:193], v[206:209], v[112:115]
	v_mfma_f32_16x16x32_bf16 v[108:111], v[198:201], v[206:209], v[108:111]
	v_mfma_f32_16x16x32_bf16 v[96:99], v[190:193], v[214:217], v[96:99]
	v_mfma_f32_16x16x32_bf16 v[92:95], v[198:201], v[214:217], v[92:95]
	v_mfma_f32_16x16x32_bf16 v[80:83], v[190:193], v[222:225], v[80:83]
	v_mfma_f32_16x16x32_bf16 v[76:79], v[198:201], v[222:225], v[76:79]
	v_mfma_f32_16x16x32_bf16 v[72:75], v[190:193], v[238:241], v[72:75]
	v_mfma_f32_16x16x32_bf16 v[68:71], v[198:201], v[238:241], v[68:71]
	s_setprio 0
	s_barrier
	s_add_i32 s42, s67, s15
	s_mov_b32 m0, s42
	ds_read_b128 v[202:205], v145 offset:49152
	ds_read_b128 v[206:209], v145 offset:50176
	ds_read_b128 v[210:213], v145 offset:51200
	ds_read_b128 v[214:217], v145 offset:52224
	ds_read_b128 v[218:221], v145 offset:53248
	ds_read_b128 v[222:225], v145 offset:54272
	ds_read_b128 v[234:237], v145 offset:55296
	ds_read_b128 v[238:241], v145 offset:56320
	s_add_u32 s98, s50, 0x80
	s_addc_u32 s99, s51, 0
	global_load_lds_dwordx4 v34, s[98:99]
	s_add_i32 m0, s42, 0x2000
	s_add_u32 s42, s50, 0x160080
	v_lshl_add_u64 v[162:163], v[226:227], 0, s[22:23]
	s_addc_u32 s43, s51, 0
	s_add_i32 s50, s68, s15
	global_load_lds_dwordx4 v[162:163], off
	s_mov_b32 m0, s50
	s_nop 0
	global_load_lds_dwordx4 v34, s[42:43]
	s_add_i32 m0, s50, 0x2000
	s_nop 0
	global_load_lds_dwordx4 v136, s[42:43]
	s_mov_b32 m0, s56
	s_nop 0
	s_add_u32 s98, s52, 0x80
	s_addc_u32 s99, s53, 0
	global_load_lds_dwordx4 v132, s[98:99]
	s_mov_b32 m0, s57
	s_nop 0
	s_add_u32 s98, s52, 0x80
	s_addc_u32 s99, s53, 0
	global_load_lds_dwordx4 v134, s[98:99]
	s_waitcnt vmcnt(8)
	s_waitcnt lgkmcnt(0)
	s_barrier
	s_setprio 1
	v_mfma_f32_16x16x32_bf16 v[64:67], v[146:149], v[202:205], v[64:67]
	v_mfma_f32_16x16x32_bf16 v[60:63], v[154:157], v[202:205], v[60:63]
	v_mfma_f32_16x16x32_bf16 v[56:59], v[146:149], v[210:213], v[56:59]
	v_mfma_f32_16x16x32_bf16 v[52:55], v[154:157], v[210:213], v[52:55]
	v_mfma_f32_16x16x32_bf16 v[40:43], v[146:149], v[218:221], v[40:43]
	v_mfma_f32_16x16x32_bf16 v[36:39], v[154:157], v[218:221], v[36:39]
	v_mfma_f32_16x16x32_bf16 v[22:25], v[146:149], v[234:237], v[22:25]
	v_mfma_f32_16x16x32_bf16 v[18:21], v[154:157], v[234:237], v[18:21]
	v_mfma_f32_16x16x32_bf16 v[64:67], v[150:153], v[206:209], v[64:67]
	v_mfma_f32_16x16x32_bf16 v[60:63], v[158:161], v[206:209], v[60:63]
	v_mfma_f32_16x16x32_bf16 v[56:59], v[150:153], v[214:217], v[56:59]
	v_mfma_f32_16x16x32_bf16 v[52:55], v[158:161], v[214:217], v[52:55]
	v_mfma_f32_16x16x32_bf16 v[40:43], v[150:153], v[222:225], v[40:43]
	v_mfma_f32_16x16x32_bf16 v[36:39], v[158:161], v[222:225], v[36:39]
	v_mfma_f32_16x16x32_bf16 v[22:25], v[150:153], v[238:241], v[22:25]
	v_mfma_f32_16x16x32_bf16 v[18:21], v[158:161], v[238:241], v[18:21]
	v_mfma_f32_16x16x32_bf16 v[48:51], v[186:189], v[202:205], v[48:51]
	v_mfma_f32_16x16x32_bf16 v[44:47], v[194:197], v[202:205], v[44:47]
	v_mfma_f32_16x16x32_bf16 v[30:33], v[186:189], v[210:213], v[30:33]
	v_mfma_f32_16x16x32_bf16 v[26:29], v[194:197], v[210:213], v[26:29]
	v_mfma_f32_16x16x32_bf16 v[14:17], v[186:189], v[218:221], v[14:17]
	v_mfma_f32_16x16x32_bf16 v[10:13], v[194:197], v[218:221], v[10:13]
	v_mfma_f32_16x16x32_bf16 v[6:9], v[186:189], v[234:237], v[6:9]
	v_mfma_f32_16x16x32_bf16 v[2:5], v[194:197], v[234:237], v[2:5]
	v_mfma_f32_16x16x32_bf16 v[48:51], v[190:193], v[206:209], v[48:51]
	v_mfma_f32_16x16x32_bf16 v[44:47], v[198:201], v[206:209], v[44:47]
	v_mfma_f32_16x16x32_bf16 v[30:33], v[190:193], v[214:217], v[30:33]
	v_mfma_f32_16x16x32_bf16 v[26:29], v[198:201], v[214:217], v[26:29]
	v_mfma_f32_16x16x32_bf16 v[14:17], v[190:193], v[222:225], v[14:17]
	v_mfma_f32_16x16x32_bf16 v[10:13], v[198:201], v[222:225], v[10:13]
	v_mfma_f32_16x16x32_bf16 v[6:9], v[190:193], v[238:241], v[6:9]
	v_mfma_f32_16x16x32_bf16 v[2:5], v[198:201], v[238:241], v[2:5]
	s_setprio 0
	s_barrier
	s_add_i32 s66, s66, 2
	s_add_u32 s64, s64, 0x100
	s_addc_u32 s65, s65, 0
	s_cmpk_gt_u32 s66, 0x55
	s_mov_b64 s[42:43], s[44:45]
	s_cbranch_scc0 .LBB0_694
	s_and_b64 vcc, exec, s[30:31]
	s_cbranch_vccz .LBB0_697
	s_barrier

; #define PG8_STAGE(bufoff, gbase, voff) do { _Pragma("unroll") for (int _i = 0; _i < 2; ++_i) \
;         __builtin_amdgcn_global_load_lds((const unsigned*)((const char*)(gbase) + (voff)[_i]), (PG8_LAS unsigned*)(lds + (bufoff) + ldsw + _i * 8192), 16, 0, 0); } while (0)
; #define PG8_LDA(dst, b, h) do { _Pragma("unroll") for (int m = 0; m < 4; ++m) _Pragma("unroll") for (int k = 0; k < 2; ++k) dst[m][k] = *(const PG8_LAS bf16x8*)(lds + PG8_SA(b, h) + aoff + m * 2048 + k * 1024); } while (0)
; #define PG8_LDB(dst, b, h) do { _Pragma("unroll") for (int n = 0; n < 2; ++n) _Pragma("unroll") for (int k = 0; k < 2; ++k) dst[n][k] = *(const PG8_LAS bf16x8*)(lds + PG8_SB(b, h) + boff + n * 2048 + k * 1024); } while (0)
; #define PG8_WAIT_V(n) asm volatile("s_waitcnt vmcnt(" #n ")" ::: "memory")
; #define PG8_WAIT_L(n) asm volatile("s_waitcnt lgkmcnt(" #n ")" ::: "memory")
; #define PG8_BAR __builtin_amdgcn_s_barrier()
; #define PG8_SCHED __builtin_amdgcn_sched_barrier(0)
;     ...
;             const bool last = (t == nt - 2);
;             const char* a1 = cA + (size_t)(t + 1) * kstep;
;             const char* a2 = last ? nA : cA + (size_t)(t + 2) * kstep; const char* b2 = last ? nB : cB + (size_t)(t + 2) * kstep;
;             const char* a3 = a2 + kstep; const char* b3 = b2 + kstep;
;             if (last && has_next) S.a_ready(nxt);
;             if constexpr (SP2) {
;             PG8_LDB(B0, 0, 0); PG8_LDB(B1, 0, 1); PG8_SCHED; PG8_LDA(At, 0, 0); PG8_STAGE(PG8_SA(1, 1), a1 + hstepA, voffA);
;             PG8_WAIT_V(8); PG8_WAIT_L(0); PG8_BAR; PG8_MMA(0, 0, At, B0); PG8_MMA(0, 1, At, B1); PG8_BAR; PG8_SCHED;
;             PG8_LDA(At, 0, 1); PG8_STAGE(PG8_SB(0, 0), b2, voffB); PG8_STAGE(PG8_SB(0, 1), b2 + hstepB, voffB); PG8_STAGE(PG8_SA(0, 0), a2, voffA);
;             PG8_WAIT_V(8); PG8_WAIT_L(0); PG8_BAR; PG8_MMA(1, 0, At, B0); PG8_MMA(1, 1, At, B1); PG8_BAR; PG8_SCHED;
.LBB0_726:
	v_add_u32_e32 v250, 0x10000, v209
	s_add_u32 s40, s42, 0x100
	s_addc_u32 s41, s43, 0
	s_add_i32 s64, 0, 0x10000
	s_cmp_eq_u32 s63, 40
	s_cselect_b32 s51, s31, s41
	s_cselect_b32 s50, s30, s40
	s_cselect_b32 s45, s37, s62
	s_cselect_b32 s44, s36, s61
	s_add_i32 s65, 0, 0x14000
	ds_read_b128 v[26:29], v250
	ds_read_b128 v[30:33], v250 offset:1024
	ds_read_b128 v[18:21], v250 offset:2048
	ds_read_b128 v[22:25], v250 offset:3072
	ds_read_b128 v[10:13], v250 offset:16384
	ds_read_b128 v[14:17], v250 offset:17408
	ds_read_b128 v[2:5], v250 offset:18432
	ds_read_b128 v[6:9], v250 offset:19456
	s_add_i32 m0, s21, 0xc000
	ds_read_b128 v[200:203], v211
	ds_read_b128 v[204:207], v211 offset:1024
	ds_read_b128 v[212:215], v211 offset:2048
	ds_read_b128 v[216:219], v211 offset:3072
	ds_read_b128 v[220:223], v211 offset:4096
	ds_read_b128 v[224:227], v211 offset:5120
	ds_read_b128 v[234:237], v211 offset:6144
	ds_read_b128 v[238:241], v211 offset:7168
	global_load_lds_dwordx4 v196, s[42:43]
	s_add_i32 m0, s21, 0xe000
	s_nop 0
	global_load_lds_dwordx4 v198, s[42:43]
	s_waitcnt vmcnt(8)
	s_waitcnt lgkmcnt(0)
	s_barrier
	s_setprio 1
	v_mfma_f32_16x16x128_f8f6f4 v[160:163], v[26:33], v[200:207], v[160:163]
	v_mfma_f32_16x16x128_f8f6f4 v[156:159], v[18:25], v[200:207], v[156:159]
	v_mfma_f32_16x16x128_f8f6f4 v[152:155], v[26:33], v[212:219], v[152:155]
	v_mfma_f32_16x16x128_f8f6f4 v[144:147], v[18:25], v[212:219], v[144:147]
	v_mfma_f32_16x16x128_f8f6f4 v[136:139], v[26:33], v[220:227], v[136:139]
	v_mfma_f32_16x16x128_f8f6f4 v[128:131], v[18:25], v[220:227], v[128:131]
	v_mfma_f32_16x16x128_f8f6f4 v[120:123], v[26:33], v[234:241], v[120:123]
	v_mfma_f32_16x16x128_f8f6f4 v[112:115], v[18:25], v[234:241], v[112:115]
	v_mfma_f32_16x16x128_f8f6f4 v[148:151], v[10:17], v[200:207], v[148:151]
	v_mfma_f32_16x16x128_f8f6f4 v[140:143], v[2:9], v[200:207], v[140:143]
	v_mfma_f32_16x16x128_f8f6f4 v[132:135], v[10:17], v[212:219], v[132:135]
	v_mfma_f32_16x16x128_f8f6f4 v[124:127], v[2:9], v[212:219], v[124:127]
	v_mfma_f32_16x16x128_f8f6f4 v[116:119], v[10:17], v[220:227], v[116:119]
	v_mfma_f32_16x16x128_f8f6f4 v[108:111], v[2:9], v[220:227], v[108:111]
	v_mfma_f32_16x16x128_f8f6f4 v[104:107], v[10:17], v[234:241], v[104:107]
	v_mfma_f32_16x16x128_f8f6f4 v[100:103], v[2:9], v[234:241], v[100:103]
	s_setprio 0
	s_barrier
	s_add_i32 s42, s64, s15
	s_mov_b32 m0, s42
	ds_read_b128 v[212:215], v211 offset:16384
	ds_read_b128 v[216:219], v211 offset:17408
	ds_read_b128 v[220:223], v211 offset:18432
	ds_read_b128 v[224:227], v211 offset:19456
	ds_read_b128 v[234:237], v211 offset:20480
	ds_read_b128 v[238:241], v211 offset:21504
	ds_read_b128 v[242:245], v211 offset:22528
	ds_read_b128 v[246:249], v211 offset:23552
	global_load_lds_dwordx4 v34, s[44:45]
	s_add_i32 m0, s42, 0x2000
	s_add_u32 s42, s44, 0xb0000
	v_lshl_add_u64 v[202:203], s[44:45], 0, v[190:191]
	s_addc_u32 s43, s45, 0
	s_add_i32 s64, s65, s15
	global_load_lds_dwordx4 v190, s[44:45]
	s_mov_b32 m0, s64
	s_nop 0
	global_load_lds_dwordx4 v34, s[42:43]
	s_add_i32 m0, s64, 0x2000
	s_nop 0
	global_load_lds_dwordx4 v190, s[42:43]
	s_mov_b32 m0, s21
	s_nop 0
	global_load_lds_dwordx4 v186, s[50:51]
	s_mov_b32 m0, s34
	s_nop 0
	global_load_lds_dwordx4 v188, s[50:51]
	s_waitcnt vmcnt(8)
	s_waitcnt lgkmcnt(0)
	s_barrier
	s_setprio 1
	v_mfma_f32_16x16x128_f8f6f4 v[96:99], v[26:33], v[212:219], v[96:99]
	v_mfma_f32_16x16x128_f8f6f4 v[92:95], v[18:25], v[212:219], v[92:95]
	v_mfma_f32_16x16x128_f8f6f4 v[88:91], v[26:33], v[220:227], v[88:91]
	v_mfma_f32_16x16x128_f8f6f4 v[80:83], v[18:25], v[220:227], v[80:83]
	v_mfma_f32_16x16x128_f8f6f4 v[72:75], v[26:33], v[234:241], v[72:75]
	v_mfma_f32_16x16x128_f8f6f4 v[64:67], v[18:25], v[234:241], v[64:67]
	v_mfma_f32_16x16x128_f8f6f4 v[56:59], v[26:33], v[242:249], v[56:59]
	v_mfma_f32_16x16x128_f8f6f4 v[48:51], v[18:25], v[242:249], v[48:51]
	v_mfma_f32_16x16x128_f8f6f4 v[84:87], v[10:17], v[212:219], v[84:87]
	v_mfma_f32_16x16x128_f8f6f4 v[76:79], v[2:9], v[212:219], v[76:79]
	v_mfma_f32_16x16x128_f8f6f4 v[68:71], v[10:17], v[220:227], v[68:71]
	v_mfma_f32_16x16x128_f8f6f4 v[60:63], v[2:9], v[220:227], v[60:63]
	v_mfma_f32_16x16x128_f8f6f4 v[52:55], v[10:17], v[234:241], v[52:55]
	v_mfma_f32_16x16x128_f8f6f4 v[44:47], v[2:9], v[234:241], v[44:47]
	v_mfma_f32_16x16x128_f8f6f4 v[40:43], v[10:17], v[242:249], v[40:43]
	v_mfma_f32_16x16x128_f8f6f4 v[36:39], v[2:9], v[242:249], v[36:39]
	s_setprio 0
	s_barrier
; #define PG8_STAGE(bufoff, gbase, voff) do { _Pragma("unroll") for (int _i = 0; _i < 2; ++_i) \
;         __builtin_amdgcn_global_load_lds((const unsigned*)((const char*)(gbase) + (voff)[_i]), (PG8_LAS unsigned*)(lds + (bufoff) + ldsw + _i * 8192), 16, 0, 0); } while (0)
; #define PG8_LDA(dst, b, h) do { _Pragma("unroll") for (int m = 0; m < 4; ++m) _Pragma("unroll") for (int k = 0; k < 2; ++k) dst[m][k] = *(const PG8_LAS bf16x8*)(lds + PG8_SA(b, h) + aoff + m * 2048 + k * 1024); } while (0)
; #define PG8_LDB(dst, b, h) do { _Pragma("unroll") for (int n = 0; n < 2; ++n) _Pragma("unroll") for (int k = 0; k < 2; ++k) dst[n][k] = *(const PG8_LAS bf16x8*)(lds + PG8_SB(b, h) + boff + n * 2048 + k * 1024); } while (0)
; #define PG8_WAIT_V(n) asm volatile("s_waitcnt vmcnt(" #n ")" ::: "memory")
; #define PG8_WAIT_L(n) asm volatile("s_waitcnt lgkmcnt(" #n ")" ::: "memory")
; #define PG8_BAR __builtin_amdgcn_s_barrier()
; #define PG8_SCHED __builtin_amdgcn_sched_barrier(0)
;     ...
;             PG8_LDB(B0, 1, 0); PG8_LDB(B1, 1, 1); PG8_SCHED; PG8_LDA(At, 1, 0); PG8_STAGE(PG8_SA(0, 1), a2 + hstepA, voffA);
;             PG8_WAIT_V(8); PG8_WAIT_L(0); PG8_BAR; PG8_MMA(0, 0, At, B0); PG8_MMA(0, 1, At, B1); PG8_BAR; PG8_SCHED;
;             PG8_LDA(At, 1, 1); PG8_STAGE(PG8_SB(1, 0), b3, voffB); PG8_STAGE(PG8_SB(1, 1), b3 + hstepB, voffB); PG8_STAGE(PG8_SA(1, 0), a3, voffA);
;             PG8_WAIT_V(8); PG8_WAIT_L(0); PG8_BAR; PG8_MMA(1, 0, At, B0); PG8_MMA(1, 1, At, B1); PG8_BAR; PG8_SCHED;
	s_add_i32 s64, 0, 0x18000
	s_add_i32 s65, 0, 0x1c000
	ds_read_b128 v[2:5], v250 offset:32768
	ds_read_b128 v[6:9], v250 offset:33792
	ds_read_b128 v[10:13], v250 offset:34816
	ds_read_b128 v[14:17], v250 offset:35840
	ds_read_b128 v[18:21], v250 offset:49152
	ds_read_b128 v[22:25], v250 offset:50176
	ds_read_b128 v[26:29], v250 offset:51200
	ds_read_b128 v[30:33], v250 offset:52224
	s_add_u32 s42, s50, 0xb0000
	s_addc_u32 s43, s51, 0
	s_mov_b32 m0, s35
	ds_read_b128 v[212:215], v211 offset:32768
	ds_read_b128 v[216:219], v211 offset:33792
	ds_read_b128 v[220:223], v211 offset:34816
	ds_read_b128 v[224:227], v211 offset:35840
	ds_read_b128 v[234:237], v211 offset:36864
	ds_read_b128 v[238:241], v211 offset:37888
	ds_read_b128 v[242:245], v211 offset:38912
	ds_read_b128 v[246:249], v211 offset:39936
	global_load_lds_dwordx4 v186, s[42:43]
	s_mov_b32 m0, s52
	s_nop 0
	global_load_lds_dwordx4 v188, s[42:43]
	s_waitcnt vmcnt(8)
	s_waitcnt lgkmcnt(0)
	s_barrier
	s_setprio 1
	v_mfma_f32_16x16x128_f8f6f4 v[160:163], v[2:9], v[212:219], v[160:163]
	v_mfma_f32_16x16x128_f8f6f4 v[156:159], v[10:17], v[212:219], v[156:159]
	v_mfma_f32_16x16x128_f8f6f4 v[152:155], v[2:9], v[220:227], v[152:155]
	v_mfma_f32_16x16x128_f8f6f4 v[144:147], v[10:17], v[220:227], v[144:147]
	v_mfma_f32_16x16x128_f8f6f4 v[136:139], v[2:9], v[234:241], v[136:139]
	v_mfma_f32_16x16x128_f8f6f4 v[128:131], v[10:17], v[234:241], v[128:131]
	v_mfma_f32_16x16x128_f8f6f4 v[120:123], v[2:9], v[242:249], v[120:123]
	v_mfma_f32_16x16x128_f8f6f4 v[112:115], v[10:17], v[242:249], v[112:115]
	v_mfma_f32_16x16x128_f8f6f4 v[148:151], v[18:25], v[212:219], v[148:151]
	v_mfma_f32_16x16x128_f8f6f4 v[140:143], v[26:33], v[212:219], v[140:143]
	v_mfma_f32_16x16x128_f8f6f4 v[132:135], v[18:25], v[220:227], v[132:135]
	v_mfma_f32_16x16x128_f8f6f4 v[124:127], v[26:33], v[220:227], v[124:127]
	v_mfma_f32_16x16x128_f8f6f4 v[116:119], v[18:25], v[234:241], v[116:119]
	v_mfma_f32_16x16x128_f8f6f4 v[108:111], v[26:33], v[234:241], v[108:111]
	v_mfma_f32_16x16x128_f8f6f4 v[104:107], v[18:25], v[242:249], v[104:107]
	v_mfma_f32_16x16x128_f8f6f4 v[100:103], v[26:33], v[242:249], v[100:103]
	s_setprio 0
	s_barrier
	s_add_i32 s42, s64, s15
	s_mov_b32 m0, s42
	ds_read_b128 v[212:215], v211 offset:49152
	ds_read_b128 v[216:219], v211 offset:50176
	ds_read_b128 v[220:223], v211 offset:51200
	ds_read_b128 v[224:227], v211 offset:52224
	ds_read_b128 v[234:237], v211 offset:53248
	ds_read_b128 v[238:241], v211 offset:54272
	ds_read_b128 v[242:245], v211 offset:55296
	ds_read_b128 v[246:249], v211 offset:56320
	s_add_u32 s98, s44, 0x80
	s_addc_u32 s99, s45, 0
	global_load_lds_dwordx4 v34, s[98:99]
	s_add_i32 m0, s42, 0x2000
	s_add_u32 s42, s44, 0xb0080
	v_lshl_add_u64 v[200:201], v[202:203], 0, s[22:23]
	s_addc_u32 s43, s45, 0
	s_add_i32 s44, s65, s15
	global_load_lds_dwordx4 v[200:201], off
	s_mov_b32 m0, s44
	s_nop 0
	global_load_lds_dwordx4 v34, s[42:43]
	s_add_i32 m0, s44, 0x2000
	s_nop 0
	global_load_lds_dwordx4 v190, s[42:43]
	s_mov_b32 m0, s53
	s_nop 0
	s_add_u32 s98, s50, 0x80
	s_addc_u32 s99, s51, 0
	global_load_lds_dwordx4 v186, s[98:99]
	s_mov_b32 m0, s54
	s_nop 0
	s_add_u32 s98, s50, 0x80
	s_addc_u32 s99, s51, 0
	global_load_lds_dwordx4 v188, s[98:99]
	s_waitcnt vmcnt(8)
	s_waitcnt lgkmcnt(0)
	s_barrier
	s_setprio 1
	v_mfma_f32_16x16x128_f8f6f4 v[96:99], v[2:9], v[212:219], v[96:99]
	v_mfma_f32_16x16x128_f8f6f4 v[92:95], v[10:17], v[212:219], v[92:95]
	v_mfma_f32_16x16x128_f8f6f4 v[88:91], v[2:9], v[220:227], v[88:91]
	v_mfma_f32_16x16x128_f8f6f4 v[80:83], v[10:17], v[220:227], v[80:83]
	v_mfma_f32_16x16x128_f8f6f4 v[72:75], v[2:9], v[234:241], v[72:75]
	v_mfma_f32_16x16x128_f8f6f4 v[64:67], v[10:17], v[234:241], v[64:67]
	v_mfma_f32_16x16x128_f8f6f4 v[56:59], v[2:9], v[242:249], v[56:59]
	v_mfma_f32_16x16x128_f8f6f4 v[48:51], v[10:17], v[242:249], v[48:51]
	v_mfma_f32_16x16x128_f8f6f4 v[84:87], v[18:25], v[212:219], v[84:87]
	v_mfma_f32_16x16x128_f8f6f4 v[76:79], v[26:33], v[212:219], v[76:79]
	v_mfma_f32_16x16x128_f8f6f4 v[68:71], v[18:25], v[220:227], v[68:71]
	v_mfma_f32_16x16x128_f8f6f4 v[60:63], v[26:33], v[220:227], v[60:63]
	v_mfma_f32_16x16x128_f8f6f4 v[52:55], v[18:25], v[234:241], v[52:55]
	v_mfma_f32_16x16x128_f8f6f4 v[44:47], v[26:33], v[234:241], v[44:47]
	v_mfma_f32_16x16x128_f8f6f4 v[40:43], v[18:25], v[242:249], v[40:43]
	v_mfma_f32_16x16x128_f8f6f4 v[36:39], v[26:33], v[242:249], v[36:39]
	s_setprio 0
	s_barrier
	s_add_i32 s63, s63, 2
	s_add_u32 s61, s61, 0x100
	s_addc_u32 s62, s62, 0
	s_cmp_gt_u32 s63, 41
	s_mov_b64 s[42:43], s[40:41]
	s_cbranch_scc0 .LBB0_726
	s_and_b64 vcc, exec, s[28:29]
	s_cbranch_vccz .LBB0_729
	s_barrier

; #define PG8_STAGE(bufoff, gbase, voff) do { _Pragma("unroll") for (int _i = 0; _i < 2; ++_i) \
;         __builtin_amdgcn_global_load_lds((const unsigned*)((const char*)(gbase) + (voff)[_i]), (PG8_LAS unsigned*)(lds + (bufoff) + ldsw + _i * 8192), 16, 0, 0); } while (0)
; #define PG8_LDA(dst, b, h) do { _Pragma("unroll") for (int m = 0; m < 4; ++m) _Pragma("unroll") for (int k = 0; k < 2; ++k) dst[m][k] = *(const PG8_LAS bf16x8*)(lds + PG8_SA(b, h) + aoff + m * 2048 + k * 1024); } while (0)
; #define PG8_LDB(dst, b, h) do { _Pragma("unroll") for (int n = 0; n < 2; ++n) _Pragma("unroll") for (int k = 0; k < 2; ++k) dst[n][k] = *(const PG8_LAS bf16x8*)(lds + PG8_SB(b, h) + boff + n * 2048 + k * 1024); } while (0)
; #define PG8_WAIT_V(n) asm volatile("s_waitcnt vmcnt(" #n ")" ::: "memory")
; #define PG8_WAIT_L(n) asm volatile("s_waitcnt lgkmcnt(" #n ")" ::: "memory")
; #define PG8_BAR __builtin_amdgcn_s_barrier()
; #define PG8_SCHED __builtin_amdgcn_sched_barrier(0)
;     ...
;             const bool last = (t == nt - 2);
;             const char* a1 = cA + (size_t)(t + 1) * kstep;
;             const char* a2 = last ? nA : cA + (size_t)(t + 2) * kstep; const char* b2 = last ? nB : cB + (size_t)(t + 2) * kstep;
;             const char* a3 = a2 + kstep; const char* b3 = b2 + kstep;
;             if (last && has_next) S.a_ready(nxt);
;             if constexpr (SP2) {
;             PG8_LDB(B0, 0, 0); PG8_LDB(B1, 0, 1); PG8_SCHED; PG8_LDA(At, 0, 0); PG8_STAGE(PG8_SA(1, 1), a1 + hstepA, voffA);
;             PG8_WAIT_V(8); PG8_WAIT_L(0); PG8_BAR; PG8_MMA(0, 0, At, B0); PG8_MMA(0, 1, At, B1); PG8_BAR; PG8_SCHED;
;             PG8_LDA(At, 0, 1); PG8_STAGE(PG8_SB(0, 0), b2, voffB); PG8_STAGE(PG8_SB(0, 1), b2 + hstepB, voffB); PG8_STAGE(PG8_SA(0, 0), a2, voffA);
;             PG8_WAIT_V(8); PG8_WAIT_L(0); PG8_BAR; PG8_MMA(1, 0, At, B0); PG8_MMA(1, 1, At, B1); PG8_BAR; PG8_SCHED;
.LBB0_923:
	v_add_u32_e32 v242, 0x10000, v153
	s_add_u32 s56, s52, 0xfff80080
	s_addc_u32 s57, s53, -1
	s_add_i32 s68, 0, 0x10000
	s_cmp_eq_u32 s47, 28
	s_cselect_b32 s59, s6, s57
	s_cselect_b32 s58, s15, s56
	s_cselect_b32 s57, s34, s41
	s_cselect_b32 s56, s35, s37
	s_add_i32 s76, 0, 0x14000
	s_waitcnt vmcnt(0)
	ds_read_b128 v[132:135], v242
	ds_read_b128 v[136:139], v242 offset:1024
	ds_read_b128 v[156:159], v242 offset:2048
	ds_read_b128 v[160:163], v242 offset:3072
	ds_read_b128 v[186:189], v242 offset:16384
	ds_read_b128 v[190:193], v242 offset:17408
	ds_read_b128 v[194:197], v242 offset:18432
	ds_read_b128 v[198:201], v242 offset:19456
	s_add_i32 m0, s10, 0xc000
	ds_read_b128 v[202:205], v155
	ds_read_b128 v[206:209], v155 offset:1024
	ds_read_b128 v[210:213], v155 offset:2048
	ds_read_b128 v[214:217], v155 offset:3072
	ds_read_b128 v[218:221], v155 offset:4096
	ds_read_b128 v[222:225], v155 offset:5120
	ds_read_b128 v[234:237], v155 offset:6144
	ds_read_b128 v[238:241], v155 offset:7168
	global_load_lds_dwordx4 v148, s[52:53]
	s_add_i32 m0, s10, 0xe000
	s_nop 0
	global_load_lds_dwordx4 v150, s[52:53]
	s_waitcnt vmcnt(8)
	s_waitcnt lgkmcnt(0)
	s_barrier
	s_setprio 1
	v_mfma_f32_16x16x32_bf16 v[128:131], v[132:135], v[202:205], v[128:131]
	v_mfma_f32_16x16x32_bf16 v[124:127], v[156:159], v[202:205], v[124:127]
	v_mfma_f32_16x16x32_bf16 v[112:115], v[132:135], v[210:213], v[112:115]
	v_mfma_f32_16x16x32_bf16 v[108:111], v[156:159], v[210:213], v[108:111]
	v_mfma_f32_16x16x32_bf16 v[96:99], v[132:135], v[218:221], v[96:99]
	v_mfma_f32_16x16x32_bf16 v[92:95], v[156:159], v[218:221], v[92:95]
	v_mfma_f32_16x16x32_bf16 v[80:83], v[132:135], v[234:237], v[80:83]
	v_mfma_f32_16x16x32_bf16 v[76:79], v[156:159], v[234:237], v[76:79]
	v_mfma_f32_16x16x32_bf16 v[128:131], v[136:139], v[206:209], v[128:131]
	v_mfma_f32_16x16x32_bf16 v[124:127], v[160:163], v[206:209], v[124:127]
	v_mfma_f32_16x16x32_bf16 v[112:115], v[136:139], v[214:217], v[112:115]
	v_mfma_f32_16x16x32_bf16 v[108:111], v[160:163], v[214:217], v[108:111]
	v_mfma_f32_16x16x32_bf16 v[96:99], v[136:139], v[222:225], v[96:99]
	v_mfma_f32_16x16x32_bf16 v[92:95], v[160:163], v[222:225], v[92:95]
	v_mfma_f32_16x16x32_bf16 v[80:83], v[136:139], v[238:241], v[80:83]
	v_mfma_f32_16x16x32_bf16 v[76:79], v[160:163], v[238:241], v[76:79]
	v_mfma_f32_16x16x32_bf16 v[120:123], v[186:189], v[202:205], v[120:123]
	v_mfma_f32_16x16x32_bf16 v[116:119], v[194:197], v[202:205], v[116:119]
	v_mfma_f32_16x16x32_bf16 v[104:107], v[186:189], v[210:213], v[104:107]
	v_mfma_f32_16x16x32_bf16 v[100:103], v[194:197], v[210:213], v[100:103]
	v_mfma_f32_16x16x32_bf16 v[88:91], v[186:189], v[218:221], v[88:91]
	v_mfma_f32_16x16x32_bf16 v[84:87], v[194:197], v[218:221], v[84:87]
	v_mfma_f32_16x16x32_bf16 v[72:75], v[186:189], v[234:237], v[72:75]
	v_mfma_f32_16x16x32_bf16 v[68:71], v[194:197], v[234:237], v[68:71]
	v_mfma_f32_16x16x32_bf16 v[120:123], v[190:193], v[206:209], v[120:123]
	v_mfma_f32_16x16x32_bf16 v[116:119], v[198:201], v[206:209], v[116:119]
	v_mfma_f32_16x16x32_bf16 v[104:107], v[190:193], v[214:217], v[104:107]
	v_mfma_f32_16x16x32_bf16 v[100:103], v[198:201], v[214:217], v[100:103]
	v_mfma_f32_16x16x32_bf16 v[88:91], v[190:193], v[222:225], v[88:91]
	v_mfma_f32_16x16x32_bf16 v[84:87], v[198:201], v[222:225], v[84:87]
	v_mfma_f32_16x16x32_bf16 v[72:75], v[190:193], v[238:241], v[72:75]
	v_mfma_f32_16x16x32_bf16 v[68:71], v[198:201], v[238:241], v[68:71]
	s_setprio 0
	s_barrier
	s_add_i32 s68, s68, s9
	s_mov_b32 m0, s68
	ds_read_b128 v[202:205], v155 offset:16384
	ds_read_b128 v[206:209], v155 offset:17408
	ds_read_b128 v[210:213], v155 offset:18432
	ds_read_b128 v[214:217], v155 offset:19456
	ds_read_b128 v[218:221], v155 offset:20480
	ds_read_b128 v[222:225], v155 offset:21504
	ds_read_b128 v[234:237], v155 offset:22528
	ds_read_b128 v[238:241], v155 offset:23552
	global_load_lds_dwordx4 v142, s[56:57]
	s_add_i32 m0, s68, 0x2000
	s_add_u32 s70, s56, 0x80000
	s_addc_u32 s71, s57, 0
	s_add_i32 s68, s76, s9
	global_load_lds_dwordx4 v146, s[56:57]
	s_mov_b32 m0, s68
	v_lshl_add_u64 v[246:247], s[58:59], 0, v[144:145]
	global_load_lds_dwordx4 v142, s[70:71]
	s_add_i32 m0, s68, 0x2000
	s_nop 0
	global_load_lds_dwordx4 v146, s[70:71]
	v_lshl_add_u64 v[244:245], s[58:59], 0, v[140:141]
	s_mov_b32 m0, s10
	s_nop 0
	global_load_lds_dwordx4 v140, s[58:59]
	s_mov_b32 m0, s11
	s_nop 0
	global_load_lds_dwordx4 v144, s[58:59]
	s_waitcnt vmcnt(8)
	s_waitcnt lgkmcnt(0)
	s_barrier
	s_setprio 1
	v_mfma_f32_16x16x32_bf16 v[64:67], v[132:135], v[202:205], v[64:67]
	v_mfma_f32_16x16x32_bf16 v[60:63], v[156:159], v[202:205], v[60:63]
	v_mfma_f32_16x16x32_bf16 v[48:51], v[132:135], v[210:213], v[48:51]
	v_mfma_f32_16x16x32_bf16 v[44:47], v[156:159], v[210:213], v[44:47]
	v_mfma_f32_16x16x32_bf16 v[30:33], v[132:135], v[218:221], v[30:33]
	v_mfma_f32_16x16x32_bf16 v[26:29], v[156:159], v[218:221], v[26:29]
	v_mfma_f32_16x16x32_bf16 v[14:17], v[132:135], v[234:237], v[14:17]
	v_mfma_f32_16x16x32_bf16 v[10:13], v[156:159], v[234:237], v[10:13]
	v_mfma_f32_16x16x32_bf16 v[64:67], v[136:139], v[206:209], v[64:67]
	v_mfma_f32_16x16x32_bf16 v[60:63], v[160:163], v[206:209], v[60:63]
	v_mfma_f32_16x16x32_bf16 v[48:51], v[136:139], v[214:217], v[48:51]
	v_mfma_f32_16x16x32_bf16 v[44:47], v[160:163], v[214:217], v[44:47]
	v_mfma_f32_16x16x32_bf16 v[30:33], v[136:139], v[222:225], v[30:33]
	v_mfma_f32_16x16x32_bf16 v[26:29], v[160:163], v[222:225], v[26:29]
	v_mfma_f32_16x16x32_bf16 v[14:17], v[136:139], v[238:241], v[14:17]
	v_mfma_f32_16x16x32_bf16 v[10:13], v[160:163], v[238:241], v[10:13]
	v_mfma_f32_16x16x32_bf16 v[56:59], v[186:189], v[202:205], v[56:59]
	v_mfma_f32_16x16x32_bf16 v[52:55], v[194:197], v[202:205], v[52:55]
	v_mfma_f32_16x16x32_bf16 v[40:43], v[186:189], v[210:213], v[40:43]
	v_mfma_f32_16x16x32_bf16 v[36:39], v[194:197], v[210:213], v[36:39]
	v_mfma_f32_16x16x32_bf16 v[22:25], v[186:189], v[218:221], v[22:25]
	v_mfma_f32_16x16x32_bf16 v[18:21], v[194:197], v[218:221], v[18:21]
	v_mfma_f32_16x16x32_bf16 v[6:9], v[186:189], v[234:237], v[6:9]
	v_mfma_f32_16x16x32_bf16 v[2:5], v[194:197], v[234:237], v[2:5]
	v_mfma_f32_16x16x32_bf16 v[56:59], v[190:193], v[206:209], v[56:59]
	v_mfma_f32_16x16x32_bf16 v[52:55], v[198:201], v[206:209], v[52:55]
	v_mfma_f32_16x16x32_bf16 v[40:43], v[190:193], v[214:217], v[40:43]
	v_mfma_f32_16x16x32_bf16 v[36:39], v[198:201], v[214:217], v[36:39]
	v_mfma_f32_16x16x32_bf16 v[22:25], v[190:193], v[222:225], v[22:25]
	v_mfma_f32_16x16x32_bf16 v[18:21], v[198:201], v[222:225], v[18:21]
	v_mfma_f32_16x16x32_bf16 v[6:9], v[190:193], v[238:241], v[6:9]
	v_mfma_f32_16x16x32_bf16 v[2:5], v[198:201], v[238:241], v[2:5]
	s_setprio 0
	s_barrier
; #define PG8_STAGE(bufoff, gbase, voff) do { _Pragma("unroll") for (int _i = 0; _i < 2; ++_i) \
;         __builtin_amdgcn_global_load_lds((const unsigned*)((const char*)(gbase) + (voff)[_i]), (PG8_LAS unsigned*)(lds + (bufoff) + ldsw + _i * 8192), 16, 0, 0); } while (0)
; #define PG8_LDA(dst, b, h) do { _Pragma("unroll") for (int m = 0; m < 4; ++m) _Pragma("unroll") for (int k = 0; k < 2; ++k) dst[m][k] = *(const PG8_LAS bf16x8*)(lds + PG8_SA(b, h) + aoff + m * 2048 + k * 1024); } while (0)
; #define PG8_LDB(dst, b, h) do { _Pragma("unroll") for (int n = 0; n < 2; ++n) _Pragma("unroll") for (int k = 0; k < 2; ++k) dst[n][k] = *(const PG8_LAS bf16x8*)(lds + PG8_SB(b, h) + boff + n * 2048 + k * 1024); } while (0)
; #define PG8_WAIT_V(n) asm volatile("s_waitcnt vmcnt(" #n ")" ::: "memory")
; #define PG8_WAIT_L(n) asm volatile("s_waitcnt lgkmcnt(" #n ")" ::: "memory")
; #define PG8_BAR __builtin_amdgcn_s_barrier()
; #define PG8_SCHED __builtin_amdgcn_sched_barrier(0)
;     ...
;             PG8_LDB(B0, 1, 0); PG8_LDB(B1, 1, 1); PG8_SCHED; PG8_LDA(At, 1, 0); PG8_STAGE(PG8_SA(0, 1), a2 + hstepA, voffA);
;             PG8_WAIT_V(8); PG8_WAIT_L(0); PG8_BAR; PG8_MMA(0, 0, At, B0); PG8_MMA(0, 1, At, B1); PG8_BAR; PG8_SCHED;
;             PG8_LDA(At, 1, 1); PG8_STAGE(PG8_SB(1, 0), b3, voffB); PG8_STAGE(PG8_SB(1, 1), b3 + hstepB, voffB); PG8_STAGE(PG8_SA(1, 0), a3, voffA);
;             PG8_WAIT_V(8); PG8_WAIT_L(0); PG8_BAR; PG8_MMA(1, 0, At, B0); PG8_MMA(1, 1, At, B1); PG8_BAR; PG8_SCHED;
	s_add_i32 s68, 0, 0x18000
	s_add_i32 s70, 0, 0x1c000
	ds_read_b128 v[132:135], v242 offset:32768
	ds_read_b128 v[136:139], v242 offset:33792
	ds_read_b128 v[156:159], v242 offset:34816
	ds_read_b128 v[160:163], v242 offset:35840
	ds_read_b128 v[186:189], v242 offset:49152
	ds_read_b128 v[190:193], v242 offset:50176
	ds_read_b128 v[194:197], v242 offset:51200
	ds_read_b128 v[198:201], v242 offset:52224
	s_add_u32 s58, s58, 0x80000
	s_addc_u32 s59, s59, 0
	s_mov_b32 m0, s12
	ds_read_b128 v[202:205], v155 offset:32768
	ds_read_b128 v[206:209], v155 offset:33792
	ds_read_b128 v[210:213], v155 offset:34816
	ds_read_b128 v[214:217], v155 offset:35840
	ds_read_b128 v[218:221], v155 offset:36864
	ds_read_b128 v[222:225], v155 offset:37888
	ds_read_b128 v[234:237], v155 offset:38912
	ds_read_b128 v[238:241], v155 offset:39936
	global_load_lds_dwordx4 v140, s[58:59]
	s_mov_b32 m0, s13
	s_nop 0
	global_load_lds_dwordx4 v144, s[58:59]
	s_waitcnt vmcnt(8)
	s_waitcnt lgkmcnt(0)
	s_barrier
	s_setprio 1
	v_mfma_f32_16x16x32_bf16 v[128:131], v[132:135], v[202:205], v[128:131]
	v_mfma_f32_16x16x32_bf16 v[124:127], v[156:159], v[202:205], v[124:127]
	v_mfma_f32_16x16x32_bf16 v[112:115], v[132:135], v[210:213], v[112:115]
	v_mfma_f32_16x16x32_bf16 v[108:111], v[156:159], v[210:213], v[108:111]
	v_mfma_f32_16x16x32_bf16 v[96:99], v[132:135], v[218:221], v[96:99]
	v_mfma_f32_16x16x32_bf16 v[92:95], v[156:159], v[218:221], v[92:95]
	v_mfma_f32_16x16x32_bf16 v[80:83], v[132:135], v[234:237], v[80:83]
	v_mfma_f32_16x16x32_bf16 v[76:79], v[156:159], v[234:237], v[76:79]
	v_mfma_f32_16x16x32_bf16 v[128:131], v[136:139], v[206:209], v[128:131]
	v_mfma_f32_16x16x32_bf16 v[124:127], v[160:163], v[206:209], v[124:127]
	v_mfma_f32_16x16x32_bf16 v[112:115], v[136:139], v[214:217], v[112:115]
	v_mfma_f32_16x16x32_bf16 v[108:111], v[160:163], v[214:217], v[108:111]
	v_mfma_f32_16x16x32_bf16 v[96:99], v[136:139], v[222:225], v[96:99]
	v_mfma_f32_16x16x32_bf16 v[92:95], v[160:163], v[222:225], v[92:95]
	v_mfma_f32_16x16x32_bf16 v[80:83], v[136:139], v[238:241], v[80:83]
	v_mfma_f32_16x16x32_bf16 v[76:79], v[160:163], v[238:241], v[76:79]
	v_mfma_f32_16x16x32_bf16 v[120:123], v[186:189], v[202:205], v[120:123]
	v_mfma_f32_16x16x32_bf16 v[116:119], v[194:197], v[202:205], v[116:119]
	v_mfma_f32_16x16x32_bf16 v[104:107], v[186:189], v[210:213], v[104:107]
	v_mfma_f32_16x16x32_bf16 v[100:103], v[194:197], v[210:213], v[100:103]
	v_mfma_f32_16x16x32_bf16 v[88:91], v[186:189], v[218:221], v[88:91]
	v_mfma_f32_16x16x32_bf16 v[84:87], v[194:197], v[218:221], v[84:87]
	v_mfma_f32_16x16x32_bf16 v[72:75], v[186:189], v[234:237], v[72:75]
	v_mfma_f32_16x16x32_bf16 v[68:71], v[194:197], v[234:237], v[68:71]
	v_mfma_f32_16x16x32_bf16 v[120:123], v[190:193], v[206:209], v[120:123]
	v_mfma_f32_16x16x32_bf16 v[116:119], v[198:201], v[206:209], v[116:119]
	v_mfma_f32_16x16x32_bf16 v[104:107], v[190:193], v[214:217], v[104:107]
	v_mfma_f32_16x16x32_bf16 v[100:103], v[198:201], v[214:217], v[100:103]
	v_mfma_f32_16x16x32_bf16 v[88:91], v[190:193], v[222:225], v[88:91]
	v_mfma_f32_16x16x32_bf16 v[84:87], v[198:201], v[222:225], v[84:87]
	v_mfma_f32_16x16x32_bf16 v[72:75], v[190:193], v[238:241], v[72:75]
	v_mfma_f32_16x16x32_bf16 v[68:71], v[198:201], v[238:241], v[68:71]
	s_setprio 0
	s_barrier
	s_add_i32 s58, s68, s9
	s_mov_b32 m0, s58
	ds_read_b128 v[202:205], v155 offset:49152
	ds_read_b128 v[206:209], v155 offset:50176
	ds_read_b128 v[210:213], v155 offset:51200
	ds_read_b128 v[214:217], v155 offset:52224
	ds_read_b128 v[218:221], v155 offset:53248
	ds_read_b128 v[222:225], v155 offset:54272
	ds_read_b128 v[234:237], v155 offset:55296
	ds_read_b128 v[238:241], v155 offset:56320
	s_add_u32 s98, s56, 0x80
	s_addc_u32 s99, s57, 0
	global_load_lds_dwordx4 v142, s[98:99]
	s_add_i32 m0, s58, 0x2000
	s_add_u32 s56, s56, 0x80080
	s_addc_u32 s57, s57, 0
	s_add_i32 s58, s70, s9
	s_add_u32 s98, s56, 0xfff80000
	s_addc_u32 s99, s57, -1
	global_load_lds_dwordx4 v146, s[98:99]
	s_mov_b32 m0, s58
	s_nop 0
	global_load_lds_dwordx4 v142, s[56:57]
	s_add_i32 m0, s58, 0x2000
	s_nop 0
	global_load_lds_dwordx4 v146, s[56:57]
	v_lshl_add_u64 v[226:227], v[244:245], 0, s[22:23]
	s_mov_b32 m0, s55
	s_nop 0
	global_load_lds_dwordx4 v[226:227], off
	v_lshl_add_u64 v[226:227], v[246:247], 0, s[22:23]
	s_mov_b32 m0, s66
	s_nop 0
	global_load_lds_dwordx4 v[226:227], off
	s_waitcnt vmcnt(8)
	s_waitcnt lgkmcnt(0)
	s_barrier
	s_setprio 1
	v_mfma_f32_16x16x32_bf16 v[64:67], v[132:135], v[202:205], v[64:67]
	v_mfma_f32_16x16x32_bf16 v[60:63], v[156:159], v[202:205], v[60:63]
	v_mfma_f32_16x16x32_bf16 v[48:51], v[132:135], v[210:213], v[48:51]
	v_mfma_f32_16x16x32_bf16 v[44:47], v[156:159], v[210:213], v[44:47]
	v_mfma_f32_16x16x32_bf16 v[30:33], v[132:135], v[218:221], v[30:33]
	v_mfma_f32_16x16x32_bf16 v[26:29], v[156:159], v[218:221], v[26:29]
	v_mfma_f32_16x16x32_bf16 v[14:17], v[132:135], v[234:237], v[14:17]
	v_mfma_f32_16x16x32_bf16 v[10:13], v[156:159], v[234:237], v[10:13]
	v_mfma_f32_16x16x32_bf16 v[64:67], v[136:139], v[206:209], v[64:67]
	v_mfma_f32_16x16x32_bf16 v[60:63], v[160:163], v[206:209], v[60:63]
	v_mfma_f32_16x16x32_bf16 v[48:51], v[136:139], v[214:217], v[48:51]
	v_mfma_f32_16x16x32_bf16 v[44:47], v[160:163], v[214:217], v[44:47]
	v_mfma_f32_16x16x32_bf16 v[30:33], v[136:139], v[222:225], v[30:33]
	v_mfma_f32_16x16x32_bf16 v[26:29], v[160:163], v[222:225], v[26:29]
	v_mfma_f32_16x16x32_bf16 v[14:17], v[136:139], v[238:241], v[14:17]
	v_mfma_f32_16x16x32_bf16 v[10:13], v[160:163], v[238:241], v[10:13]
	v_mfma_f32_16x16x32_bf16 v[56:59], v[186:189], v[202:205], v[56:59]
	v_mfma_f32_16x16x32_bf16 v[52:55], v[194:197], v[202:205], v[52:55]
	v_mfma_f32_16x16x32_bf16 v[40:43], v[186:189], v[210:213], v[40:43]
	v_mfma_f32_16x16x32_bf16 v[36:39], v[194:197], v[210:213], v[36:39]
	v_mfma_f32_16x16x32_bf16 v[22:25], v[186:189], v[218:221], v[22:25]
	v_mfma_f32_16x16x32_bf16 v[18:21], v[194:197], v[218:221], v[18:21]
	v_mfma_f32_16x16x32_bf16 v[6:9], v[186:189], v[234:237], v[6:9]
	v_mfma_f32_16x16x32_bf16 v[2:5], v[194:197], v[234:237], v[2:5]
	v_mfma_f32_16x16x32_bf16 v[56:59], v[190:193], v[206:209], v[56:59]
	v_mfma_f32_16x16x32_bf16 v[52:55], v[198:201], v[206:209], v[52:55]
	v_mfma_f32_16x16x32_bf16 v[40:43], v[190:193], v[214:217], v[40:43]
	v_mfma_f32_16x16x32_bf16 v[36:39], v[198:201], v[214:217], v[36:39]
	v_mfma_f32_16x16x32_bf16 v[22:25], v[190:193], v[222:225], v[22:25]
	v_mfma_f32_16x16x32_bf16 v[18:21], v[198:201], v[222:225], v[18:21]
	v_mfma_f32_16x16x32_bf16 v[6:9], v[190:193], v[238:241], v[6:9]
	v_mfma_f32_16x16x32_bf16 v[2:5], v[198:201], v[238:241], v[2:5]
	s_setprio 0
	s_barrier
	s_add_i32 s47, s47, 2
	s_add_u32 s52, s52, 0x100
	s_addc_u32 s53, s53, 0
	s_add_u32 s37, s37, 0x100
	s_addc_u32 s41, s41, 0
	s_cmp_gt_u32 s47, 29
	s_cbranch_scc0 .LBB0_923
	s_and_b64 vcc, exec, s[30:31]
	s_cbranch_vccz .LBB0_926
	s_barrier

; #define PG8_STAGE(bufoff, gbase, voff) do { _Pragma("unroll") for (int _i = 0; _i < 2; ++_i) \
;         __builtin_amdgcn_global_load_lds((const unsigned*)((const char*)(gbase) + (voff)[_i]), (PG8_LAS unsigned*)(lds + (bufoff) + ldsw + _i * 8192), 16, 0, 0); } while (0)
; #define PG8_LDA(dst, b, h) do { _Pragma("unroll") for (int m = 0; m < 4; ++m) _Pragma("unroll") for (int k = 0; k < 2; ++k) dst[m][k] = *(const PG8_LAS bf16x8*)(lds + PG8_SA(b, h) + aoff + m * 2048 + k * 1024); } while (0)
; #define PG8_LDB(dst, b, h) do { _Pragma("unroll") for (int n = 0; n < 2; ++n) _Pragma("unroll") for (int k = 0; k < 2; ++k) dst[n][k] = *(const PG8_LAS bf16x8*)(lds + PG8_SB(b, h) + boff + n * 2048 + k * 1024); } while (0)
; #define PG8_WAIT_V(n) asm volatile("s_waitcnt vmcnt(" #n ")" ::: "memory")
; #define PG8_WAIT_L(n) asm volatile("s_waitcnt lgkmcnt(" #n ")" ::: "memory")
; #define PG8_BAR __builtin_amdgcn_s_barrier()
; #define PG8_SCHED __builtin_amdgcn_sched_barrier(0)
;     ...
;             const bool last = (t == nt - 2);
;             const char* a1 = cA + (size_t)(t + 1) * kstep;
;             const char* a2 = last ? nA : cA + (size_t)(t + 2) * kstep; const char* b2 = last ? nB : cB + (size_t)(t + 2) * kstep;
;             const char* a3 = a2 + kstep; const char* b3 = b2 + kstep;
;             if (last && has_next) S.a_ready(nxt);
;             if constexpr (SP2) {
;             PG8_LDB(B0, 0, 0); PG8_LDB(B1, 0, 1); PG8_SCHED; PG8_LDA(At, 0, 0); PG8_STAGE(PG8_SA(1, 1), a1 + hstepA, voffA);
;             PG8_WAIT_V(8); PG8_WAIT_L(0); PG8_BAR; PG8_MMA(0, 0, At, B0); PG8_MMA(0, 1, At, B1); PG8_BAR; PG8_SCHED;
;             PG8_LDA(At, 0, 1); PG8_STAGE(PG8_SB(0, 0), b2, voffB); PG8_STAGE(PG8_SB(0, 1), b2 + hstepB, voffB); PG8_STAGE(PG8_SA(0, 0), a2, voffA);
;             PG8_WAIT_V(8); PG8_WAIT_L(0); PG8_BAR; PG8_MMA(1, 0, At, B0); PG8_MMA(1, 1, At, B1); PG8_BAR; PG8_SCHED;
.LBB0_1133:
	v_add_u32_e32 v226, 0x10000, v208
	s_add_u32 s52, s50, 0xfffc0080
	s_addc_u32 s53, s51, -1
	s_add_i32 s75, 0, 0x10000
	s_cmp_eq_u32 s74, 12
	s_cselect_b32 s55, s37, s53
	s_cselect_b32 s54, s67, s52
	s_cselect_b32 s53, s31, s71
	s_cselect_b32 s52, s68, s70
	s_add_i32 s76, 0, 0x14000
	ds_read_b128 v[26:29], v226
	ds_read_b128 v[30:33], v226 offset:1024
	ds_read_b128 v[18:21], v226 offset:2048
	ds_read_b128 v[22:25], v226 offset:3072
	ds_read_b128 v[10:13], v226 offset:16384
	ds_read_b128 v[14:17], v226 offset:17408
	ds_read_b128 v[2:5], v226 offset:18432
	ds_read_b128 v[6:9], v226 offset:19456
	s_add_i32 m0, s57, 0xc000
	ds_read_b128 v[198:201], v209
	ds_read_b128 v[202:205], v209 offset:1024
	ds_read_b128 v[210:213], v209 offset:2048
	ds_read_b128 v[214:217], v209 offset:3072
	ds_read_b128 v[218:221], v209 offset:4096
	ds_read_b128 v[222:225], v209 offset:5120
	ds_read_b128 v[234:237], v209 offset:6144
	ds_read_b128 v[238:241], v209 offset:7168
	global_load_lds_dwordx4 v194, s[50:51]
	s_add_i32 m0, s57, 0xe000
	s_nop 0
	global_load_lds_dwordx4 v196, s[50:51]
	s_waitcnt vmcnt(8)
	s_waitcnt lgkmcnt(0)
	s_barrier
	s_setprio 1
	v_mfma_f32_16x16x128_f8f6f4 v[160:163], v[26:33], v[198:205], v[160:163]
	v_mfma_f32_16x16x128_f8f6f4 v[156:159], v[18:25], v[198:205], v[156:159]
	v_mfma_f32_16x16x128_f8f6f4 v[144:147], v[26:33], v[210:217], v[144:147]
	v_mfma_f32_16x16x128_f8f6f4 v[140:143], v[18:25], v[210:217], v[140:143]
	v_mfma_f32_16x16x128_f8f6f4 v[128:131], v[26:33], v[218:225], v[128:131]
	v_mfma_f32_16x16x128_f8f6f4 v[124:127], v[18:25], v[218:225], v[124:127]
	v_mfma_f32_16x16x128_f8f6f4 v[112:115], v[26:33], v[234:241], v[112:115]
	v_mfma_f32_16x16x128_f8f6f4 v[108:111], v[18:25], v[234:241], v[108:111]
	v_mfma_f32_16x16x128_f8f6f4 v[152:155], v[10:17], v[198:205], v[152:155]
	v_mfma_f32_16x16x128_f8f6f4 v[148:151], v[2:9], v[198:205], v[148:151]
	v_mfma_f32_16x16x128_f8f6f4 v[136:139], v[10:17], v[210:217], v[136:139]
	v_mfma_f32_16x16x128_f8f6f4 v[132:135], v[2:9], v[210:217], v[132:135]
	v_mfma_f32_16x16x128_f8f6f4 v[120:123], v[10:17], v[218:225], v[120:123]
	v_mfma_f32_16x16x128_f8f6f4 v[116:119], v[2:9], v[218:225], v[116:119]
	v_mfma_f32_16x16x128_f8f6f4 v[104:107], v[10:17], v[234:241], v[104:107]
	v_mfma_f32_16x16x128_f8f6f4 v[100:103], v[2:9], v[234:241], v[100:103]
	s_setprio 0
	s_barrier
	s_add_i32 s75, s75, s11
	s_mov_b32 m0, s75
	ds_read_b128 v[210:213], v209 offset:16384
	ds_read_b128 v[214:217], v209 offset:17408
	ds_read_b128 v[218:221], v209 offset:18432
	ds_read_b128 v[222:225], v209 offset:19456
	ds_read_b128 v[234:237], v209 offset:20480
	ds_read_b128 v[238:241], v209 offset:21504
	ds_read_b128 v[242:245], v209 offset:22528
	ds_read_b128 v[246:249], v209 offset:23552
	global_load_lds_dwordx4 v34, s[52:53]
	s_add_i32 m0, s75, 0x2000
	s_add_u32 s78, s52, 0x40000
	s_addc_u32 s79, s53, 0
	s_add_i32 s75, s76, s11
	global_load_lds_dwordx4 v186, s[52:53]
	s_mov_b32 m0, s75
	v_lshl_add_u64 v[204:205], s[54:55], 0, v[188:189]
	global_load_lds_dwordx4 v34, s[78:79]
	s_add_i32 m0, s75, 0x2000
	s_nop 0
	global_load_lds_dwordx4 v186, s[78:79]
	v_lshl_add_u64 v[202:203], s[54:55], 0, v[190:191]
	s_mov_b32 m0, s57
	s_nop 0
	global_load_lds_dwordx4 v190, s[54:55]
	s_mov_b32 m0, s6
	s_nop 0
	global_load_lds_dwordx4 v188, s[54:55]
	s_waitcnt vmcnt(8)
	s_waitcnt lgkmcnt(0)
	s_barrier
	s_setprio 1
	v_mfma_f32_16x16x128_f8f6f4 v[96:99], v[26:33], v[210:217], v[96:99]
	v_mfma_f32_16x16x128_f8f6f4 v[92:95], v[18:25], v[210:217], v[92:95]
	v_mfma_f32_16x16x128_f8f6f4 v[80:83], v[26:33], v[218:225], v[80:83]
	v_mfma_f32_16x16x128_f8f6f4 v[76:79], v[18:25], v[218:225], v[76:79]
	v_mfma_f32_16x16x128_f8f6f4 v[64:67], v[26:33], v[234:241], v[64:67]
	v_mfma_f32_16x16x128_f8f6f4 v[60:63], v[18:25], v[234:241], v[60:63]
	v_mfma_f32_16x16x128_f8f6f4 v[48:51], v[26:33], v[242:249], v[48:51]
	v_mfma_f32_16x16x128_f8f6f4 v[44:47], v[18:25], v[242:249], v[44:47]
	v_mfma_f32_16x16x128_f8f6f4 v[88:91], v[10:17], v[210:217], v[88:91]
	v_mfma_f32_16x16x128_f8f6f4 v[84:87], v[2:9], v[210:217], v[84:87]
	v_mfma_f32_16x16x128_f8f6f4 v[72:75], v[10:17], v[218:225], v[72:75]
	v_mfma_f32_16x16x128_f8f6f4 v[68:71], v[2:9], v[218:225], v[68:71]
	v_mfma_f32_16x16x128_f8f6f4 v[56:59], v[10:17], v[234:241], v[56:59]
	v_mfma_f32_16x16x128_f8f6f4 v[52:55], v[2:9], v[234:241], v[52:55]
	v_mfma_f32_16x16x128_f8f6f4 v[40:43], v[10:17], v[242:249], v[40:43]
	v_mfma_f32_16x16x128_f8f6f4 v[36:39], v[2:9], v[242:249], v[36:39]
	s_setprio 0
	s_barrier
; #define PG8_STAGE(bufoff, gbase, voff) do { _Pragma("unroll") for (int _i = 0; _i < 2; ++_i) \
;         __builtin_amdgcn_global_load_lds((const unsigned*)((const char*)(gbase) + (voff)[_i]), (PG8_LAS unsigned*)(lds + (bufoff) + ldsw + _i * 8192), 16, 0, 0); } while (0)
; #define PG8_LDA(dst, b, h) do { _Pragma("unroll") for (int m = 0; m < 4; ++m) _Pragma("unroll") for (int k = 0; k < 2; ++k) dst[m][k] = *(const PG8_LAS bf16x8*)(lds + PG8_SA(b, h) + aoff + m * 2048 + k * 1024); } while (0)
; #define PG8_LDB(dst, b, h) do { _Pragma("unroll") for (int n = 0; n < 2; ++n) _Pragma("unroll") for (int k = 0; k < 2; ++k) dst[n][k] = *(const PG8_LAS bf16x8*)(lds + PG8_SB(b, h) + boff + n * 2048 + k * 1024); } while (0)
; #define PG8_WAIT_V(n) asm volatile("s_waitcnt vmcnt(" #n ")" ::: "memory")
; #define PG8_WAIT_L(n) asm volatile("s_waitcnt lgkmcnt(" #n ")" ::: "memory")
; #define PG8_BAR __builtin_amdgcn_s_barrier()
; #define PG8_SCHED __builtin_amdgcn_sched_barrier(0)
;     ...
;             PG8_LDB(B0, 1, 0); PG8_LDB(B1, 1, 1); PG8_SCHED; PG8_LDA(At, 1, 0); PG8_STAGE(PG8_SA(0, 1), a2 + hstepA, voffA);
;             PG8_WAIT_V(8); PG8_WAIT_L(0); PG8_BAR; PG8_MMA(0, 0, At, B0); PG8_MMA(0, 1, At, B1); PG8_BAR; PG8_SCHED;
;             PG8_LDA(At, 1, 1); PG8_STAGE(PG8_SB(1, 0), b3, voffB); PG8_STAGE(PG8_SB(1, 1), b3 + hstepB, voffB); PG8_STAGE(PG8_SA(1, 0), a3, voffA);
;             PG8_WAIT_V(8); PG8_WAIT_L(0); PG8_BAR; PG8_MMA(1, 0, At, B0); PG8_MMA(1, 1, At, B1); PG8_BAR; PG8_SCHED;
	s_add_i32 s75, 0, 0x18000
	s_add_i32 s76, 0, 0x1c000
	ds_read_b128 v[2:5], v226 offset:32768
	ds_read_b128 v[6:9], v226 offset:33792
	ds_read_b128 v[10:13], v226 offset:34816
	ds_read_b128 v[14:17], v226 offset:35840
	ds_read_b128 v[18:21], v226 offset:49152
	ds_read_b128 v[22:25], v226 offset:50176
	ds_read_b128 v[26:29], v226 offset:51200
	ds_read_b128 v[30:33], v226 offset:52224
	s_add_u32 s54, s54, 0x40000
	s_addc_u32 s55, s55, 0
	s_mov_b32 m0, s15
	ds_read_b128 v[210:213], v209 offset:32768
	ds_read_b128 v[214:217], v209 offset:33792
	ds_read_b128 v[218:221], v209 offset:34816
	ds_read_b128 v[222:225], v209 offset:35840
	ds_read_b128 v[234:237], v209 offset:36864
	ds_read_b128 v[238:241], v209 offset:37888
	ds_read_b128 v[242:245], v209 offset:38912
	ds_read_b128 v[246:249], v209 offset:39936
	global_load_lds_dwordx4 v190, s[54:55]
	s_mov_b32 m0, s34
	s_nop 0
	global_load_lds_dwordx4 v188, s[54:55]
	s_waitcnt vmcnt(8)
	s_waitcnt lgkmcnt(0)
	s_barrier
	s_setprio 1
	v_mfma_f32_16x16x128_f8f6f4 v[160:163], v[2:9], v[210:217], v[160:163]
	v_mfma_f32_16x16x128_f8f6f4 v[156:159], v[10:17], v[210:217], v[156:159]
	v_mfma_f32_16x16x128_f8f6f4 v[144:147], v[2:9], v[218:225], v[144:147]
	v_mfma_f32_16x16x128_f8f6f4 v[140:143], v[10:17], v[218:225], v[140:143]
	v_mfma_f32_16x16x128_f8f6f4 v[128:131], v[2:9], v[234:241], v[128:131]
	v_mfma_f32_16x16x128_f8f6f4 v[124:127], v[10:17], v[234:241], v[124:127]
	v_mfma_f32_16x16x128_f8f6f4 v[112:115], v[2:9], v[242:249], v[112:115]
	v_mfma_f32_16x16x128_f8f6f4 v[108:111], v[10:17], v[242:249], v[108:111]
	v_mfma_f32_16x16x128_f8f6f4 v[152:155], v[18:25], v[210:217], v[152:155]
	v_mfma_f32_16x16x128_f8f6f4 v[148:151], v[26:33], v[210:217], v[148:151]
	v_mfma_f32_16x16x128_f8f6f4 v[136:139], v[18:25], v[218:225], v[136:139]
	v_mfma_f32_16x16x128_f8f6f4 v[132:135], v[26:33], v[218:225], v[132:135]
	v_mfma_f32_16x16x128_f8f6f4 v[120:123], v[18:25], v[234:241], v[120:123]
	v_mfma_f32_16x16x128_f8f6f4 v[116:119], v[26:33], v[234:241], v[116:119]
	v_mfma_f32_16x16x128_f8f6f4 v[104:107], v[18:25], v[242:249], v[104:107]
	v_mfma_f32_16x16x128_f8f6f4 v[100:103], v[26:33], v[242:249], v[100:103]
	s_setprio 0
	s_barrier
	s_add_i32 s54, s75, s11
	s_mov_b32 m0, s54
	ds_read_b128 v[210:213], v209 offset:49152
	ds_read_b128 v[214:217], v209 offset:50176
	ds_read_b128 v[218:221], v209 offset:51200
	ds_read_b128 v[222:225], v209 offset:52224
	ds_read_b128 v[234:237], v209 offset:53248
	ds_read_b128 v[238:241], v209 offset:54272
	ds_read_b128 v[242:245], v209 offset:55296
	ds_read_b128 v[246:249], v209 offset:56320
	s_add_u32 s98, s52, 0x80
	s_addc_u32 s99, s53, 0
	global_load_lds_dwordx4 v34, s[98:99]
	s_add_i32 m0, s54, 0x2000
	s_add_u32 s52, s52, 0x40080
	s_addc_u32 s53, s53, 0
	s_add_i32 s54, s76, s11
	s_add_u32 s98, s52, 0xfffc0000
	s_addc_u32 s99, s53, -1
	global_load_lds_dwordx4 v186, s[98:99]
	s_mov_b32 m0, s54
	s_nop 0
	global_load_lds_dwordx4 v34, s[52:53]
	s_add_i32 m0, s54, 0x2000
	s_nop 0
	global_load_lds_dwordx4 v186, s[52:53]
	v_lshl_add_u64 v[198:199], v[202:203], 0, s[22:23]
	s_mov_b32 m0, s35
	s_nop 0
	global_load_lds_dwordx4 v[198:199], off
	v_lshl_add_u64 v[198:199], v[204:205], 0, s[22:23]
	s_mov_b32 m0, s58
	s_nop 0
	global_load_lds_dwordx4 v[198:199], off
	s_waitcnt vmcnt(8)
	s_waitcnt lgkmcnt(0)
	s_barrier
	s_setprio 1
	v_mfma_f32_16x16x128_f8f6f4 v[96:99], v[2:9], v[210:217], v[96:99]
	v_mfma_f32_16x16x128_f8f6f4 v[92:95], v[10:17], v[210:217], v[92:95]
	v_mfma_f32_16x16x128_f8f6f4 v[80:83], v[2:9], v[218:225], v[80:83]
	v_mfma_f32_16x16x128_f8f6f4 v[76:79], v[10:17], v[218:225], v[76:79]
	v_mfma_f32_16x16x128_f8f6f4 v[64:67], v[2:9], v[234:241], v[64:67]
	v_mfma_f32_16x16x128_f8f6f4 v[60:63], v[10:17], v[234:241], v[60:63]
	v_mfma_f32_16x16x128_f8f6f4 v[48:51], v[2:9], v[242:249], v[48:51]
	v_mfma_f32_16x16x128_f8f6f4 v[44:47], v[10:17], v[242:249], v[44:47]
	v_mfma_f32_16x16x128_f8f6f4 v[88:91], v[18:25], v[210:217], v[88:91]
	v_mfma_f32_16x16x128_f8f6f4 v[84:87], v[26:33], v[210:217], v[84:87]
	v_mfma_f32_16x16x128_f8f6f4 v[72:75], v[18:25], v[218:225], v[72:75]
	v_mfma_f32_16x16x128_f8f6f4 v[68:71], v[26:33], v[218:225], v[68:71]
	v_mfma_f32_16x16x128_f8f6f4 v[56:59], v[18:25], v[234:241], v[56:59]
	v_mfma_f32_16x16x128_f8f6f4 v[52:55], v[26:33], v[234:241], v[52:55]
	v_mfma_f32_16x16x128_f8f6f4 v[40:43], v[18:25], v[242:249], v[40:43]
	v_mfma_f32_16x16x128_f8f6f4 v[36:39], v[26:33], v[242:249], v[36:39]
	s_setprio 0
	s_barrier
	s_add_i32 s74, s74, 2
	s_add_u32 s50, s50, 0x100
	s_addc_u32 s51, s51, 0
	s_add_u32 s70, s70, 0x100
	s_addc_u32 s71, s71, 0
	s_cmp_gt_u32 s74, 13
	s_cbranch_scc0 .LBB0_1133
	s_and_b64 vcc, exec, s[28:29]
	s_cbranch_vccz .LBB0_1136
	s_barrier

; #define PG8_STAGE(bufoff, gbase, voff) do { _Pragma("unroll") for (int _i = 0; _i < 2; ++_i) \
;         __builtin_amdgcn_global_load_lds((const unsigned*)((const char*)(gbase) + (voff)[_i]), (PG8_LAS unsigned*)(lds + (bufoff) + ldsw + _i * 8192), 16, 0, 0); } while (0)
; #define PG8_LDA(dst, b, h) do { _Pragma("unroll") for (int m = 0; m < 4; ++m) _Pragma("unroll") for (int k = 0; k < 2; ++k) dst[m][k] = *(const PG8_LAS bf16x8*)(lds + PG8_SA(b, h) + aoff + m * 2048 + k * 1024); } while (0)
; #define PG8_LDB(dst, b, h) do { _Pragma("unroll") for (int n = 0; n < 2; ++n) _Pragma("unroll") for (int k = 0; k < 2; ++k) dst[n][k] = *(const PG8_LAS bf16x8*)(lds + PG8_SB(b, h) + boff + n * 2048 + k * 1024); } while (0)
; #define PG8_WAIT_V(n) asm volatile("s_waitcnt vmcnt(" #n ")" ::: "memory")
; #define PG8_WAIT_L(n) asm volatile("s_waitcnt lgkmcnt(" #n ")" ::: "memory")
; #define PG8_BAR __builtin_amdgcn_s_barrier()
; #define PG8_SCHED __builtin_amdgcn_sched_barrier(0)
;     ...
;             const bool last = (t == nt - 2);
;             const char* a1 = cA + (size_t)(t + 1) * kstep;
;             const char* a2 = last ? nA : cA + (size_t)(t + 2) * kstep; const char* b2 = last ? nB : cB + (size_t)(t + 2) * kstep;
;             const char* a3 = a2 + kstep; const char* b3 = b2 + kstep;
;             if (last && has_next) S.a_ready(nxt);
;             if constexpr (SP2) {
;             PG8_LDB(B0, 0, 0); PG8_LDB(B1, 0, 1); PG8_SCHED; PG8_LDA(At, 0, 0); PG8_STAGE(PG8_SA(1, 1), a1 + hstepA, voffA);
;             PG8_WAIT_V(8); PG8_WAIT_L(0); PG8_BAR; PG8_MMA(0, 0, At, B0); PG8_MMA(0, 1, At, B1); PG8_BAR; PG8_SCHED;
;             PG8_LDA(At, 0, 1); PG8_STAGE(PG8_SB(0, 0), b2, voffB); PG8_STAGE(PG8_SB(0, 1), b2 + hstepB, voffB); PG8_STAGE(PG8_SA(0, 0), a2, voffA);
;             PG8_WAIT_V(8); PG8_WAIT_L(0); PG8_BAR; PG8_MMA(1, 0, At, B0); PG8_MMA(1, 1, At, B1); PG8_BAR; PG8_SCHED;
.LBB0_1153:
	v_add_u32_e32 v162, 0x10000, v155
	s_add_u32 s34, s26, 0xfff80080
	s_addc_u32 s35, s27, -1
	s_add_i32 s37, 0, 0x10000
	s_cmp_eq_u32 s19, 28
	s_cselect_b32 s57, s6, s35
	s_cselect_b32 s56, s10, s34
	s_cselect_b32 s41, s11, s15
	s_cselect_b32 s40, s12, s13
	s_add_i32 s49, 0, 0x14000
	ds_read_b128 v[132:135], v162
	ds_read_b128 v[136:139], v162 offset:1024
	s_waitcnt vmcnt(0)
	ds_read_b128 v[158:161], v162 offset:2048
	ds_read_b128 v[186:189], v162 offset:3072
	ds_read_b128 v[190:193], v162 offset:16384
	ds_read_b128 v[194:197], v162 offset:17408
	ds_read_b128 v[198:201], v162 offset:18432
	ds_read_b128 v[202:205], v162 offset:19456
	s_add_i32 m0, s8, 0xc000
	ds_read_b128 v[206:209], v157
	ds_read_b128 v[210:213], v157 offset:1024
	ds_read_b128 v[214:217], v157 offset:2048
	ds_read_b128 v[218:221], v157 offset:3072
	ds_read_b128 v[222:225], v157 offset:4096
	ds_read_b128 v[234:237], v157 offset:5120
	ds_read_b128 v[238:241], v157 offset:6144
	ds_read_b128 v[242:245], v157 offset:7168
	global_load_lds_dwordx4 v150, s[26:27]
	s_add_i32 m0, s8, 0xe000
	s_nop 0
	global_load_lds_dwordx4 v152, s[26:27]
	s_waitcnt vmcnt(8)
	s_waitcnt lgkmcnt(0)
	s_barrier
	s_setprio 1
	v_mfma_f32_16x16x32_bf16 v[128:131], v[132:135], v[206:209], v[128:131]
	v_mfma_f32_16x16x32_bf16 v[124:127], v[158:161], v[206:209], v[124:127]
	v_mfma_f32_16x16x32_bf16 v[112:115], v[132:135], v[214:217], v[112:115]
	v_mfma_f32_16x16x32_bf16 v[108:111], v[158:161], v[214:217], v[108:111]
	v_mfma_f32_16x16x32_bf16 v[96:99], v[132:135], v[222:225], v[96:99]
	v_mfma_f32_16x16x32_bf16 v[92:95], v[158:161], v[222:225], v[92:95]
	v_mfma_f32_16x16x32_bf16 v[80:83], v[132:135], v[238:241], v[80:83]
	v_mfma_f32_16x16x32_bf16 v[76:79], v[158:161], v[238:241], v[76:79]
	v_mfma_f32_16x16x32_bf16 v[128:131], v[136:139], v[210:213], v[128:131]
	v_mfma_f32_16x16x32_bf16 v[124:127], v[186:189], v[210:213], v[124:127]
	v_mfma_f32_16x16x32_bf16 v[112:115], v[136:139], v[218:221], v[112:115]
	v_mfma_f32_16x16x32_bf16 v[108:111], v[186:189], v[218:221], v[108:111]
	v_mfma_f32_16x16x32_bf16 v[96:99], v[136:139], v[234:237], v[96:99]
	v_mfma_f32_16x16x32_bf16 v[92:95], v[186:189], v[234:237], v[92:95]
	v_mfma_f32_16x16x32_bf16 v[80:83], v[136:139], v[242:245], v[80:83]
	v_mfma_f32_16x16x32_bf16 v[76:79], v[186:189], v[242:245], v[76:79]
	v_mfma_f32_16x16x32_bf16 v[120:123], v[190:193], v[206:209], v[120:123]
	v_mfma_f32_16x16x32_bf16 v[116:119], v[198:201], v[206:209], v[116:119]
	v_mfma_f32_16x16x32_bf16 v[104:107], v[190:193], v[214:217], v[104:107]
	v_mfma_f32_16x16x32_bf16 v[100:103], v[198:201], v[214:217], v[100:103]
	v_mfma_f32_16x16x32_bf16 v[88:91], v[190:193], v[222:225], v[88:91]
	v_mfma_f32_16x16x32_bf16 v[84:87], v[198:201], v[222:225], v[84:87]
	v_mfma_f32_16x16x32_bf16 v[72:75], v[190:193], v[238:241], v[72:75]
	v_mfma_f32_16x16x32_bf16 v[68:71], v[198:201], v[238:241], v[68:71]
	v_mfma_f32_16x16x32_bf16 v[120:123], v[194:197], v[210:213], v[120:123]
	v_mfma_f32_16x16x32_bf16 v[116:119], v[202:205], v[210:213], v[116:119]
	v_mfma_f32_16x16x32_bf16 v[104:107], v[194:197], v[218:221], v[104:107]
	v_mfma_f32_16x16x32_bf16 v[100:103], v[202:205], v[218:221], v[100:103]
	v_mfma_f32_16x16x32_bf16 v[88:91], v[194:197], v[234:237], v[88:91]
	v_mfma_f32_16x16x32_bf16 v[84:87], v[202:205], v[234:237], v[84:87]
	v_mfma_f32_16x16x32_bf16 v[72:75], v[194:197], v[242:245], v[72:75]
	v_mfma_f32_16x16x32_bf16 v[68:71], v[202:205], v[242:245], v[68:71]
	s_setprio 0
	s_barrier
	s_add_i32 s34, s37, s7
	s_mov_b32 m0, s34
	ds_read_b128 v[206:209], v157 offset:16384
	ds_read_b128 v[210:213], v157 offset:17408
	ds_read_b128 v[214:217], v157 offset:18432
	ds_read_b128 v[218:221], v157 offset:19456
	ds_read_b128 v[222:225], v157 offset:20480
	ds_read_b128 v[234:237], v157 offset:21504
	ds_read_b128 v[238:241], v157 offset:22528
	ds_read_b128 v[242:245], v157 offset:23552
	global_load_lds_dwordx4 v142, s[40:41]
	s_add_i32 m0, s34, 0x2000
	s_add_u32 s34, s40, 0x80000
	s_addc_u32 s35, s41, 0
	s_add_i32 s37, s49, s7
	global_load_lds_dwordx4 v146, s[40:41]
	s_mov_b32 m0, s37
	s_nop 0
	global_load_lds_dwordx4 v142, s[34:35]
	s_add_i32 m0, s37, 0x2000
	s_nop 0
	global_load_lds_dwordx4 v146, s[34:35]
	s_mov_b32 m0, s8
	s_nop 0
	global_load_lds_dwordx4 v140, s[56:57]
	s_mov_b32 m0, s9
	s_nop 0
	global_load_lds_dwordx4 v144, s[56:57]
	s_waitcnt vmcnt(8)
	s_waitcnt lgkmcnt(0)
	s_barrier
	s_setprio 1
	v_mfma_f32_16x16x32_bf16 v[64:67], v[132:135], v[206:209], v[64:67]
	v_mfma_f32_16x16x32_bf16 v[60:63], v[158:161], v[206:209], v[60:63]
	v_mfma_f32_16x16x32_bf16 v[48:51], v[132:135], v[214:217], v[48:51]
	v_mfma_f32_16x16x32_bf16 v[44:47], v[158:161], v[214:217], v[44:47]
	v_mfma_f32_16x16x32_bf16 v[30:33], v[132:135], v[222:225], v[30:33]
	v_mfma_f32_16x16x32_bf16 v[26:29], v[158:161], v[222:225], v[26:29]
	v_mfma_f32_16x16x32_bf16 v[14:17], v[132:135], v[238:241], v[14:17]
	v_mfma_f32_16x16x32_bf16 v[10:13], v[158:161], v[238:241], v[10:13]
	v_mfma_f32_16x16x32_bf16 v[64:67], v[136:139], v[210:213], v[64:67]
	v_mfma_f32_16x16x32_bf16 v[60:63], v[186:189], v[210:213], v[60:63]
	v_mfma_f32_16x16x32_bf16 v[48:51], v[136:139], v[218:221], v[48:51]
	v_mfma_f32_16x16x32_bf16 v[44:47], v[186:189], v[218:221], v[44:47]
	v_mfma_f32_16x16x32_bf16 v[30:33], v[136:139], v[234:237], v[30:33]
	v_mfma_f32_16x16x32_bf16 v[26:29], v[186:189], v[234:237], v[26:29]
	v_mfma_f32_16x16x32_bf16 v[14:17], v[136:139], v[242:245], v[14:17]
	v_mfma_f32_16x16x32_bf16 v[10:13], v[186:189], v[242:245], v[10:13]
	v_mfma_f32_16x16x32_bf16 v[56:59], v[190:193], v[206:209], v[56:59]
	v_mfma_f32_16x16x32_bf16 v[52:55], v[198:201], v[206:209], v[52:55]
	v_mfma_f32_16x16x32_bf16 v[40:43], v[190:193], v[214:217], v[40:43]
	v_mfma_f32_16x16x32_bf16 v[36:39], v[198:201], v[214:217], v[36:39]
	v_mfma_f32_16x16x32_bf16 v[22:25], v[190:193], v[222:225], v[22:25]
	v_mfma_f32_16x16x32_bf16 v[18:21], v[198:201], v[222:225], v[18:21]
	v_mfma_f32_16x16x32_bf16 v[6:9], v[190:193], v[238:241], v[6:9]
	v_mfma_f32_16x16x32_bf16 v[2:5], v[198:201], v[238:241], v[2:5]
	v_mfma_f32_16x16x32_bf16 v[56:59], v[194:197], v[210:213], v[56:59]
	v_mfma_f32_16x16x32_bf16 v[52:55], v[202:205], v[210:213], v[52:55]
	v_mfma_f32_16x16x32_bf16 v[40:43], v[194:197], v[218:221], v[40:43]
	v_mfma_f32_16x16x32_bf16 v[36:39], v[202:205], v[218:221], v[36:39]
	v_mfma_f32_16x16x32_bf16 v[22:25], v[194:197], v[234:237], v[22:25]
	v_mfma_f32_16x16x32_bf16 v[18:21], v[202:205], v[234:237], v[18:21]
	v_mfma_f32_16x16x32_bf16 v[6:9], v[194:197], v[242:245], v[6:9]
	v_mfma_f32_16x16x32_bf16 v[2:5], v[202:205], v[242:245], v[2:5]
	s_setprio 0
	s_barrier
; #define PG8_STAGE(bufoff, gbase, voff) do { _Pragma("unroll") for (int _i = 0; _i < 2; ++_i) \
;         __builtin_amdgcn_global_load_lds((const unsigned*)((const char*)(gbase) + (voff)[_i]), (PG8_LAS unsigned*)(lds + (bufoff) + ldsw + _i * 8192), 16, 0, 0); } while (0)
; #define PG8_LDA(dst, b, h) do { _Pragma("unroll") for (int m = 0; m < 4; ++m) _Pragma("unroll") for (int k = 0; k < 2; ++k) dst[m][k] = *(const PG8_LAS bf16x8*)(lds + PG8_SA(b, h) + aoff + m * 2048 + k * 1024); } while (0)
; #define PG8_LDB(dst, b, h) do { _Pragma("unroll") for (int n = 0; n < 2; ++n) _Pragma("unroll") for (int k = 0; k < 2; ++k) dst[n][k] = *(const PG8_LAS bf16x8*)(lds + PG8_SB(b, h) + boff + n * 2048 + k * 1024); } while (0)
; #define PG8_WAIT_V(n) asm volatile("s_waitcnt vmcnt(" #n ")" ::: "memory")
; #define PG8_WAIT_L(n) asm volatile("s_waitcnt lgkmcnt(" #n ")" ::: "memory")
; #define PG8_BAR __builtin_amdgcn_s_barrier()
; #define PG8_SCHED __builtin_amdgcn_sched_barrier(0)
;     ...
;             PG8_LDB(B0, 1, 0); PG8_LDB(B1, 1, 1); PG8_SCHED; PG8_LDA(At, 1, 0); PG8_STAGE(PG8_SA(0, 1), a2 + hstepA, voffA);
;             PG8_WAIT_V(8); PG8_WAIT_L(0); PG8_BAR; PG8_MMA(0, 0, At, B0); PG8_MMA(0, 1, At, B1); PG8_BAR; PG8_SCHED;
;             PG8_LDA(At, 1, 1); PG8_STAGE(PG8_SB(1, 0), b3, voffB); PG8_STAGE(PG8_SB(1, 1), b3 + hstepB, voffB); PG8_STAGE(PG8_SA(1, 0), a3, voffA);
;             PG8_WAIT_V(8); PG8_WAIT_L(0); PG8_BAR; PG8_MMA(1, 0, At, B0); PG8_MMA(1, 1, At, B1); PG8_BAR; PG8_SCHED;
	s_add_i32 s37, 0, 0x18000
	s_add_i32 s49, 0, 0x1c000
	ds_read_b128 v[132:135], v162 offset:32768
	ds_read_b128 v[136:139], v162 offset:33792
	ds_read_b128 v[158:161], v162 offset:34816
	ds_read_b128 v[186:189], v162 offset:35840
	ds_read_b128 v[190:193], v162 offset:49152
	ds_read_b128 v[194:197], v162 offset:50176
	ds_read_b128 v[198:201], v162 offset:51200
	ds_read_b128 v[202:205], v162 offset:52224
	s_add_u32 s34, s56, 0x80000
	s_addc_u32 s35, s57, 0
	s_mov_b32 m0, s58
	ds_read_b128 v[206:209], v157 offset:32768
	ds_read_b128 v[210:213], v157 offset:33792
	ds_read_b128 v[214:217], v157 offset:34816
	ds_read_b128 v[218:221], v157 offset:35840
	ds_read_b128 v[222:225], v157 offset:36864
	ds_read_b128 v[234:237], v157 offset:37888
	ds_read_b128 v[238:241], v157 offset:38912
	ds_read_b128 v[242:245], v157 offset:39936
	global_load_lds_dwordx4 v140, s[34:35]
	s_mov_b32 m0, s59
	s_nop 0
	global_load_lds_dwordx4 v144, s[34:35]
	s_waitcnt vmcnt(8)
	s_waitcnt lgkmcnt(0)
	s_barrier
	s_setprio 1
	v_mfma_f32_16x16x32_bf16 v[128:131], v[132:135], v[206:209], v[128:131]
	v_mfma_f32_16x16x32_bf16 v[124:127], v[158:161], v[206:209], v[124:127]
	v_mfma_f32_16x16x32_bf16 v[112:115], v[132:135], v[214:217], v[112:115]
	v_mfma_f32_16x16x32_bf16 v[108:111], v[158:161], v[214:217], v[108:111]
	v_mfma_f32_16x16x32_bf16 v[96:99], v[132:135], v[222:225], v[96:99]
	v_mfma_f32_16x16x32_bf16 v[92:95], v[158:161], v[222:225], v[92:95]
	v_mfma_f32_16x16x32_bf16 v[80:83], v[132:135], v[238:241], v[80:83]
	v_mfma_f32_16x16x32_bf16 v[76:79], v[158:161], v[238:241], v[76:79]
	v_mfma_f32_16x16x32_bf16 v[128:131], v[136:139], v[210:213], v[128:131]
	v_mfma_f32_16x16x32_bf16 v[124:127], v[186:189], v[210:213], v[124:127]
	v_mfma_f32_16x16x32_bf16 v[112:115], v[136:139], v[218:221], v[112:115]
	v_mfma_f32_16x16x32_bf16 v[108:111], v[186:189], v[218:221], v[108:111]
	v_mfma_f32_16x16x32_bf16 v[96:99], v[136:139], v[234:237], v[96:99]
	v_mfma_f32_16x16x32_bf16 v[92:95], v[186:189], v[234:237], v[92:95]
	v_mfma_f32_16x16x32_bf16 v[80:83], v[136:139], v[242:245], v[80:83]
	v_mfma_f32_16x16x32_bf16 v[76:79], v[186:189], v[242:245], v[76:79]
	v_mfma_f32_16x16x32_bf16 v[120:123], v[190:193], v[206:209], v[120:123]
	v_mfma_f32_16x16x32_bf16 v[116:119], v[198:201], v[206:209], v[116:119]
	v_mfma_f32_16x16x32_bf16 v[104:107], v[190:193], v[214:217], v[104:107]
	v_mfma_f32_16x16x32_bf16 v[100:103], v[198:201], v[214:217], v[100:103]
	v_mfma_f32_16x16x32_bf16 v[88:91], v[190:193], v[222:225], v[88:91]
	v_mfma_f32_16x16x32_bf16 v[84:87], v[198:201], v[222:225], v[84:87]
	v_mfma_f32_16x16x32_bf16 v[72:75], v[190:193], v[238:241], v[72:75]
	v_mfma_f32_16x16x32_bf16 v[68:71], v[198:201], v[238:241], v[68:71]
	v_mfma_f32_16x16x32_bf16 v[120:123], v[194:197], v[210:213], v[120:123]
	v_mfma_f32_16x16x32_bf16 v[116:119], v[202:205], v[210:213], v[116:119]
	v_mfma_f32_16x16x32_bf16 v[104:107], v[194:197], v[218:221], v[104:107]
	v_mfma_f32_16x16x32_bf16 v[100:103], v[202:205], v[218:221], v[100:103]
	v_mfma_f32_16x16x32_bf16 v[88:91], v[194:197], v[234:237], v[88:91]
	v_mfma_f32_16x16x32_bf16 v[84:87], v[202:205], v[234:237], v[84:87]
	v_mfma_f32_16x16x32_bf16 v[72:75], v[194:197], v[242:245], v[72:75]
	v_mfma_f32_16x16x32_bf16 v[68:71], v[202:205], v[242:245], v[68:71]
	s_setprio 0
	s_barrier
	s_add_i32 s34, s37, s7
	s_mov_b32 m0, s34
	ds_read_b128 v[206:209], v157 offset:49152
	ds_read_b128 v[210:213], v157 offset:50176
	ds_read_b128 v[214:217], v157 offset:51200
	ds_read_b128 v[218:221], v157 offset:52224
	ds_read_b128 v[222:225], v157 offset:53248
	ds_read_b128 v[234:237], v157 offset:54272
	ds_read_b128 v[238:241], v157 offset:55296
	ds_read_b128 v[242:245], v157 offset:56320
	s_add_u32 s98, s40, 0x80
	s_addc_u32 s99, s41, 0
	global_load_lds_dwordx4 v142, s[98:99]
	s_add_i32 m0, s34, 0x2000
	s_add_u32 s34, s40, 0x80080
	s_addc_u32 s35, s41, 0
	s_add_i32 s37, s49, s7
	s_add_u32 s98, s40, 0x80
	s_addc_u32 s99, s41, 0
	global_load_lds_dwordx4 v146, s[98:99]
	s_mov_b32 m0, s37
	s_nop 0
	global_load_lds_dwordx4 v142, s[34:35]
	s_add_i32 m0, s37, 0x2000
	s_nop 0
	global_load_lds_dwordx4 v146, s[34:35]
	s_mov_b32 m0, s66
	s_nop 0
	s_add_u32 s98, s56, 0x80
	s_addc_u32 s99, s57, 0
	global_load_lds_dwordx4 v140, s[98:99]
	s_mov_b32 m0, s67
	s_nop 0
	s_add_u32 s98, s56, 0x80
	s_addc_u32 s99, s57, 0
	global_load_lds_dwordx4 v144, s[98:99]
	s_waitcnt vmcnt(8)
	s_waitcnt lgkmcnt(0)
	s_barrier
	s_setprio 1
	v_mfma_f32_16x16x32_bf16 v[64:67], v[132:135], v[206:209], v[64:67]
	v_mfma_f32_16x16x32_bf16 v[60:63], v[158:161], v[206:209], v[60:63]
	v_mfma_f32_16x16x32_bf16 v[48:51], v[132:135], v[214:217], v[48:51]
	v_mfma_f32_16x16x32_bf16 v[44:47], v[158:161], v[214:217], v[44:47]
	v_mfma_f32_16x16x32_bf16 v[30:33], v[132:135], v[222:225], v[30:33]
	v_mfma_f32_16x16x32_bf16 v[26:29], v[158:161], v[222:225], v[26:29]
	v_mfma_f32_16x16x32_bf16 v[14:17], v[132:135], v[238:241], v[14:17]
	v_mfma_f32_16x16x32_bf16 v[10:13], v[158:161], v[238:241], v[10:13]
	v_mfma_f32_16x16x32_bf16 v[64:67], v[136:139], v[210:213], v[64:67]
	v_mfma_f32_16x16x32_bf16 v[60:63], v[186:189], v[210:213], v[60:63]
	v_mfma_f32_16x16x32_bf16 v[48:51], v[136:139], v[218:221], v[48:51]
	v_mfma_f32_16x16x32_bf16 v[44:47], v[186:189], v[218:221], v[44:47]
	v_mfma_f32_16x16x32_bf16 v[30:33], v[136:139], v[234:237], v[30:33]
	v_mfma_f32_16x16x32_bf16 v[26:29], v[186:189], v[234:237], v[26:29]
	v_mfma_f32_16x16x32_bf16 v[14:17], v[136:139], v[242:245], v[14:17]
	v_mfma_f32_16x16x32_bf16 v[10:13], v[186:189], v[242:245], v[10:13]
	v_mfma_f32_16x16x32_bf16 v[56:59], v[190:193], v[206:209], v[56:59]
	v_mfma_f32_16x16x32_bf16 v[52:55], v[198:201], v[206:209], v[52:55]
	v_mfma_f32_16x16x32_bf16 v[40:43], v[190:193], v[214:217], v[40:43]
	v_mfma_f32_16x16x32_bf16 v[36:39], v[198:201], v[214:217], v[36:39]
	v_mfma_f32_16x16x32_bf16 v[22:25], v[190:193], v[222:225], v[22:25]
	v_mfma_f32_16x16x32_bf16 v[18:21], v[198:201], v[222:225], v[18:21]
	v_mfma_f32_16x16x32_bf16 v[6:9], v[190:193], v[238:241], v[6:9]
	v_mfma_f32_16x16x32_bf16 v[2:5], v[198:201], v[238:241], v[2:5]
	v_mfma_f32_16x16x32_bf16 v[56:59], v[194:197], v[210:213], v[56:59]
	v_mfma_f32_16x16x32_bf16 v[52:55], v[202:205], v[210:213], v[52:55]
	v_mfma_f32_16x16x32_bf16 v[40:43], v[194:197], v[218:221], v[40:43]
	v_mfma_f32_16x16x32_bf16 v[36:39], v[202:205], v[218:221], v[36:39]
	v_mfma_f32_16x16x32_bf16 v[22:25], v[194:197], v[234:237], v[22:25]
	v_mfma_f32_16x16x32_bf16 v[18:21], v[202:205], v[234:237], v[18:21]
	v_mfma_f32_16x16x32_bf16 v[6:9], v[194:197], v[242:245], v[6:9]
	v_mfma_f32_16x16x32_bf16 v[2:5], v[202:205], v[242:245], v[2:5]
	s_setprio 0
	s_barrier
	s_add_i32 s19, s19, 2
	s_add_u32 s26, s26, 0x100
	s_addc_u32 s27, s27, 0
	s_add_u32 s13, s13, 0x100
	s_addc_u32 s15, s15, 0
	s_cmp_gt_u32 s19, 29
	s_cbranch_scc0 .LBB0_1153
	s_and_b64 vcc, exec, s[46:47]
	s_cbranch_vccz .LBB0_1156
	s_barrier

; #define PG8_STAGE(bufoff, gbase, voff) do { _Pragma("unroll") for (int _i = 0; _i < 2; ++_i) \
;         __builtin_amdgcn_global_load_lds((const unsigned*)((const char*)(gbase) + (voff)[_i]), (PG8_LAS unsigned*)(lds + (bufoff) + ldsw + _i * 8192), 16, 0, 0); } while (0)
; #define PG8_LDA(dst, b, h) do { _Pragma("unroll") for (int m = 0; m < 4; ++m) _Pragma("unroll") for (int k = 0; k < 2; ++k) dst[m][k] = *(const PG8_LAS bf16x8*)(lds + PG8_SA(b, h) + aoff + m * 2048 + k * 1024); } while (0)
; #define PG8_LDB(dst, b, h) do { _Pragma("unroll") for (int n = 0; n < 2; ++n) _Pragma("unroll") for (int k = 0; k < 2; ++k) dst[n][k] = *(const PG8_LAS bf16x8*)(lds + PG8_SB(b, h) + boff + n * 2048 + k * 1024); } while (0)
; #define PG8_WAIT_V(n) asm volatile("s_waitcnt vmcnt(" #n ")" ::: "memory")
; #define PG8_WAIT_L(n) asm volatile("s_waitcnt lgkmcnt(" #n ")" ::: "memory")
; #define PG8_BAR __builtin_amdgcn_s_barrier()
; #define PG8_SCHED __builtin_amdgcn_sched_barrier(0)
;     ...
;             const bool last = (t == nt - 2);
;             const char* a1 = cA + (size_t)(t + 1) * kstep;
;             const char* a2 = last ? nA : cA + (size_t)(t + 2) * kstep; const char* b2 = last ? nB : cB + (size_t)(t + 2) * kstep;
;             const char* a3 = a2 + kstep; const char* b3 = b2 + kstep;
;             if (last && has_next) S.a_ready(nxt);
;             if constexpr (SP2) {
;             PG8_LDB(B0, 0, 0); PG8_LDB(B1, 0, 1); PG8_SCHED; PG8_LDA(At, 0, 0); PG8_STAGE(PG8_SA(1, 1), a1 + hstepA, voffA);
;             PG8_WAIT_V(8); PG8_WAIT_L(0); PG8_BAR; PG8_MMA(0, 0, At, B0); PG8_MMA(0, 1, At, B1); PG8_BAR; PG8_SCHED;
;             PG8_LDA(At, 0, 1); PG8_STAGE(PG8_SB(0, 0), b2, voffB); PG8_STAGE(PG8_SB(0, 1), b2 + hstepB, voffB); PG8_STAGE(PG8_SA(0, 0), a2, voffA);
.LBB0_1503:
	s_add_i32 s70, s58, 2
	s_add_u32 s71, s40, 0xfffc0080
	s_addc_u32 s59, s41, -1
	s_add_i32 s76, 0, 0x10000
	s_cmp_eq_u32 s63, s58
	s_cselect_b32 s59, s51, s59
	s_cselect_b32 s58, s68, s71
	s_cselect_b32 s75, s53, s61
	s_cselect_b32 s74, s52, s60
	s_add_i32 s71, 0, 0x14000
	v_add_u32_e32 v128, s76, v187
	v_add_u32_e32 v189, s71, v187
	ds_read_b128 v[108:111], v128
	ds_read_b128 v[112:115], v128 offset:1024
	ds_read_b128 v[124:127], v128 offset:2048
	ds_read_b128 v[128:131], v128 offset:3072
	ds_read_b128 v[160:163], v189
	ds_read_b128 v[190:193], v189 offset:1024
	ds_read_b128 v[194:197], v189 offset:2048
	ds_read_b128 v[198:201], v189 offset:3072
	s_add_i32 m0, s13, 0xc000
	ds_read_b128 v[202:205], v188
	ds_read_b128 v[206:209], v188 offset:1024
	ds_read_b128 v[210:213], v188 offset:2048
	ds_read_b128 v[214:217], v188 offset:3072
	ds_read_b128 v[218:221], v188 offset:4096
	ds_read_b128 v[222:225], v188 offset:5120
	ds_read_b128 v[234:237], v188 offset:6144
	ds_read_b128 v[238:241], v188 offset:7168
	global_load_lds_dwordx4 v156, s[40:41]
	s_add_i32 m0, s13, 0xe000
	s_nop 0
	global_load_lds_dwordx4 v158, s[40:41]
	s_waitcnt vmcnt(8)
	s_waitcnt lgkmcnt(0)
	s_barrier
	s_setprio 1
	v_mfma_f32_16x16x32_bf16 v[144:147], v[108:111], v[202:205], v[144:147]
	v_mfma_f32_16x16x32_bf16 v[140:143], v[124:127], v[202:205], v[140:143]
	v_mfma_f32_16x16x32_bf16 v[120:123], v[108:111], v[210:213], v[120:123]
	v_mfma_f32_16x16x32_bf16 v[116:119], v[124:127], v[210:213], v[116:119]
	v_mfma_f32_16x16x32_bf16 v[96:99], v[108:111], v[218:221], v[96:99]
	v_mfma_f32_16x16x32_bf16 v[92:95], v[124:127], v[218:221], v[92:95]
	v_mfma_f32_16x16x32_bf16 v[80:83], v[108:111], v[234:237], v[80:83]
	v_mfma_f32_16x16x32_bf16 v[76:79], v[124:127], v[234:237], v[76:79]
	v_mfma_f32_16x16x32_bf16 v[144:147], v[112:115], v[206:209], v[144:147]
	v_mfma_f32_16x16x32_bf16 v[140:143], v[128:131], v[206:209], v[140:143]
	v_mfma_f32_16x16x32_bf16 v[120:123], v[112:115], v[214:217], v[120:123]
	v_mfma_f32_16x16x32_bf16 v[116:119], v[128:131], v[214:217], v[116:119]
	v_mfma_f32_16x16x32_bf16 v[96:99], v[112:115], v[222:225], v[96:99]
	v_mfma_f32_16x16x32_bf16 v[92:95], v[128:131], v[222:225], v[92:95]
	v_mfma_f32_16x16x32_bf16 v[80:83], v[112:115], v[238:241], v[80:83]
	v_mfma_f32_16x16x32_bf16 v[76:79], v[128:131], v[238:241], v[76:79]
	v_mfma_f32_16x16x32_bf16 v[136:139], v[160:163], v[202:205], v[136:139]
	v_mfma_f32_16x16x32_bf16 v[132:135], v[194:197], v[202:205], v[132:135]
	v_mfma_f32_16x16x32_bf16 v[104:107], v[160:163], v[210:213], v[104:107]
	v_mfma_f32_16x16x32_bf16 v[100:103], v[194:197], v[210:213], v[100:103]
	v_mfma_f32_16x16x32_bf16 v[88:91], v[160:163], v[218:221], v[88:91]
	v_mfma_f32_16x16x32_bf16 v[84:87], v[194:197], v[218:221], v[84:87]
	v_mfma_f32_16x16x32_bf16 v[72:75], v[160:163], v[234:237], v[72:75]
	v_mfma_f32_16x16x32_bf16 v[68:71], v[194:197], v[234:237], v[68:71]
	v_mfma_f32_16x16x32_bf16 v[136:139], v[190:193], v[206:209], v[136:139]
	v_mfma_f32_16x16x32_bf16 v[132:135], v[198:201], v[206:209], v[132:135]
	v_mfma_f32_16x16x32_bf16 v[104:107], v[190:193], v[214:217], v[104:107]
	v_mfma_f32_16x16x32_bf16 v[100:103], v[198:201], v[214:217], v[100:103]
	v_mfma_f32_16x16x32_bf16 v[88:91], v[190:193], v[222:225], v[88:91]
	v_mfma_f32_16x16x32_bf16 v[84:87], v[198:201], v[222:225], v[84:87]
	v_mfma_f32_16x16x32_bf16 v[72:75], v[190:193], v[238:241], v[72:75]
	v_mfma_f32_16x16x32_bf16 v[68:71], v[198:201], v[238:241], v[68:71]
	s_setprio 0
	s_barrier
	s_add_i32 s76, s76, s12
	v_lshl_add_u64 v[226:227], s[74:75], 0, v[34:35]
	s_mov_b32 m0, s76
	ds_read_b128 v[202:205], v188 offset:16384
	ds_read_b128 v[206:209], v188 offset:17408
	ds_read_b128 v[210:213], v188 offset:18432
	ds_read_b128 v[214:217], v188 offset:19456
	ds_read_b128 v[218:221], v188 offset:20480
	ds_read_b128 v[222:225], v188 offset:21504
	ds_read_b128 v[234:237], v188 offset:22528
	ds_read_b128 v[238:241], v188 offset:23552
	global_load_lds_dwordx4 v34, s[74:75]
	s_add_i32 m0, s76, 0x2000
	v_lshl_add_u64 v[242:243], s[74:75], 0, v[152:153]
	s_add_u32 s74, s74, s28
	s_addc_u32 s75, s75, s29
	s_add_i32 s71, s71, s12
	global_load_lds_dwordx4 v[242:243], off
	v_lshl_add_u64 v[244:245], s[74:75], 0, v[34:35]
	s_mov_b32 m0, s71
	v_lshl_add_u64 v[246:247], s[74:75], 0, v[152:153]
	global_load_lds_dwordx4 v34, s[74:75]
	s_add_i32 m0, s71, 0x2000
	v_lshl_add_u64 v[248:249], s[58:59], 0, v[148:149]
	global_load_lds_dwordx4 v152, s[74:75]
	s_mov_b32 m0, s13
	v_lshl_add_u64 v[250:251], s[58:59], 0, v[150:151]
	global_load_lds_dwordx4 v148, s[58:59]
	s_mov_b32 m0, s15
	s_nop 0
	global_load_lds_dwordx4 v150, s[58:59]
	s_waitcnt vmcnt(8)
	s_waitcnt lgkmcnt(0)
	s_barrier
; #define PG8_STAGE(bufoff, gbase, voff) do { _Pragma("unroll") for (int _i = 0; _i < 2; ++_i) \
;         __builtin_amdgcn_global_load_lds((const unsigned*)((const char*)(gbase) + (voff)[_i]), (PG8_LAS unsigned*)(lds + (bufoff) + ldsw + _i * 8192), 16, 0, 0); } while (0)
; #define PG8_LDA(dst, b, h) do { _Pragma("unroll") for (int m = 0; m < 4; ++m) _Pragma("unroll") for (int k = 0; k < 2; ++k) dst[m][k] = *(const PG8_LAS bf16x8*)(lds + PG8_SA(b, h) + aoff + m * 2048 + k * 1024); } while (0)
; #define PG8_LDB(dst, b, h) do { _Pragma("unroll") for (int n = 0; n < 2; ++n) _Pragma("unroll") for (int k = 0; k < 2; ++k) dst[n][k] = *(const PG8_LAS bf16x8*)(lds + PG8_SB(b, h) + boff + n * 2048 + k * 1024); } while (0)
; #define PG8_WAIT_V(n) asm volatile("s_waitcnt vmcnt(" #n ")" ::: "memory")
; #define PG8_WAIT_L(n) asm volatile("s_waitcnt lgkmcnt(" #n ")" ::: "memory")
; #define PG8_BAR __builtin_amdgcn_s_barrier()
; #define PG8_SCHED __builtin_amdgcn_sched_barrier(0)
;     ...
;             PG8_WAIT_V(8); PG8_WAIT_L(0); PG8_BAR; PG8_MMA(1, 0, At, B0); PG8_MMA(1, 1, At, B1); PG8_BAR; PG8_SCHED;
;             PG8_LDB(B0, 1, 0); PG8_LDB(B1, 1, 1); PG8_SCHED; PG8_LDA(At, 1, 0); PG8_STAGE(PG8_SA(0, 1), a2 + hstepA, voffA);
;             PG8_WAIT_V(8); PG8_WAIT_L(0); PG8_BAR; PG8_MMA(0, 0, At, B0); PG8_MMA(0, 1, At, B1); PG8_BAR; PG8_SCHED;
	s_setprio 1
	v_mfma_f32_16x16x32_bf16 v[64:67], v[108:111], v[202:205], v[64:67]
	v_mfma_f32_16x16x32_bf16 v[60:63], v[124:127], v[202:205], v[60:63]
	v_mfma_f32_16x16x32_bf16 v[48:51], v[108:111], v[210:213], v[48:51]
	v_mfma_f32_16x16x32_bf16 v[44:47], v[124:127], v[210:213], v[44:47]
	v_mfma_f32_16x16x32_bf16 v[30:33], v[108:111], v[218:221], v[30:33]
	v_mfma_f32_16x16x32_bf16 v[26:29], v[124:127], v[218:221], v[26:29]
	v_mfma_f32_16x16x32_bf16 v[14:17], v[108:111], v[234:237], v[14:17]
	v_mfma_f32_16x16x32_bf16 v[10:13], v[124:127], v[234:237], v[10:13]
	v_mfma_f32_16x16x32_bf16 v[64:67], v[112:115], v[206:209], v[64:67]
	v_mfma_f32_16x16x32_bf16 v[60:63], v[128:131], v[206:209], v[60:63]
	v_mfma_f32_16x16x32_bf16 v[48:51], v[112:115], v[214:217], v[48:51]
	v_mfma_f32_16x16x32_bf16 v[44:47], v[128:131], v[214:217], v[44:47]
	v_mfma_f32_16x16x32_bf16 v[30:33], v[112:115], v[222:225], v[30:33]
	v_mfma_f32_16x16x32_bf16 v[26:29], v[128:131], v[222:225], v[26:29]
	v_mfma_f32_16x16x32_bf16 v[14:17], v[112:115], v[238:241], v[14:17]
	v_mfma_f32_16x16x32_bf16 v[10:13], v[128:131], v[238:241], v[10:13]
	v_mfma_f32_16x16x32_bf16 v[56:59], v[160:163], v[202:205], v[56:59]
	v_mfma_f32_16x16x32_bf16 v[52:55], v[194:197], v[202:205], v[52:55]
	v_mfma_f32_16x16x32_bf16 v[40:43], v[160:163], v[210:213], v[40:43]
	v_mfma_f32_16x16x32_bf16 v[36:39], v[194:197], v[210:213], v[36:39]
	v_mfma_f32_16x16x32_bf16 v[22:25], v[160:163], v[218:221], v[22:25]
	v_mfma_f32_16x16x32_bf16 v[18:21], v[194:197], v[218:221], v[18:21]
	v_mfma_f32_16x16x32_bf16 v[6:9], v[160:163], v[234:237], v[6:9]
	v_mfma_f32_16x16x32_bf16 v[2:5], v[194:197], v[234:237], v[2:5]
	v_mfma_f32_16x16x32_bf16 v[56:59], v[190:193], v[206:209], v[56:59]
	v_mfma_f32_16x16x32_bf16 v[52:55], v[198:201], v[206:209], v[52:55]
	v_mfma_f32_16x16x32_bf16 v[40:43], v[190:193], v[214:217], v[40:43]
	v_mfma_f32_16x16x32_bf16 v[36:39], v[198:201], v[214:217], v[36:39]
	v_mfma_f32_16x16x32_bf16 v[22:25], v[190:193], v[222:225], v[22:25]
	v_mfma_f32_16x16x32_bf16 v[18:21], v[198:201], v[222:225], v[18:21]
	v_mfma_f32_16x16x32_bf16 v[6:9], v[190:193], v[238:241], v[6:9]
	v_mfma_f32_16x16x32_bf16 v[2:5], v[198:201], v[238:241], v[2:5]
	s_setprio 0
	s_barrier
	s_add_i32 s71, 0, 0x18000
	s_add_i32 s74, 0, 0x1c000
	v_add_u32_e32 v128, s71, v187
	v_add_u32_e32 v189, s74, v187
	ds_read_b128 v[108:111], v128
	ds_read_b128 v[112:115], v128 offset:1024
	ds_read_b128 v[124:127], v128 offset:2048
	ds_read_b128 v[128:131], v128 offset:3072
	ds_read_b128 v[160:163], v189
	ds_read_b128 v[190:193], v189 offset:1024
	ds_read_b128 v[194:197], v189 offset:2048
	ds_read_b128 v[198:201], v189 offset:3072
	s_add_u32 s58, s58, 0x40000
	s_addc_u32 s59, s59, 0
	s_mov_b32 m0, s21
	ds_read_b128 v[202:205], v188 offset:32768
	ds_read_b128 v[206:209], v188 offset:33792
	ds_read_b128 v[210:213], v188 offset:34816
	ds_read_b128 v[214:217], v188 offset:35840
	ds_read_b128 v[218:221], v188 offset:36864
	ds_read_b128 v[222:225], v188 offset:37888
	ds_read_b128 v[234:237], v188 offset:38912
	ds_read_b128 v[238:241], v188 offset:39936
	global_load_lds_dwordx4 v148, s[58:59]
	s_mov_b32 m0, s34
	s_nop 0
	global_load_lds_dwordx4 v150, s[58:59]
	s_waitcnt vmcnt(8)
	s_waitcnt lgkmcnt(0)
	s_barrier
	s_setprio 1
	v_mfma_f32_16x16x32_bf16 v[144:147], v[108:111], v[202:205], v[144:147]
	v_mfma_f32_16x16x32_bf16 v[140:143], v[124:127], v[202:205], v[140:143]
	v_mfma_f32_16x16x32_bf16 v[120:123], v[108:111], v[210:213], v[120:123]
	v_mfma_f32_16x16x32_bf16 v[116:119], v[124:127], v[210:213], v[116:119]
	v_mfma_f32_16x16x32_bf16 v[96:99], v[108:111], v[218:221], v[96:99]
	v_mfma_f32_16x16x32_bf16 v[92:95], v[124:127], v[218:221], v[92:95]
	v_mfma_f32_16x16x32_bf16 v[80:83], v[108:111], v[234:237], v[80:83]
	v_mfma_f32_16x16x32_bf16 v[76:79], v[124:127], v[234:237], v[76:79]
	v_mfma_f32_16x16x32_bf16 v[144:147], v[112:115], v[206:209], v[144:147]
	v_mfma_f32_16x16x32_bf16 v[140:143], v[128:131], v[206:209], v[140:143]
	v_mfma_f32_16x16x32_bf16 v[120:123], v[112:115], v[214:217], v[120:123]
	v_mfma_f32_16x16x32_bf16 v[116:119], v[128:131], v[214:217], v[116:119]
	v_mfma_f32_16x16x32_bf16 v[96:99], v[112:115], v[222:225], v[96:99]
	v_mfma_f32_16x16x32_bf16 v[92:95], v[128:131], v[222:225], v[92:95]
	v_mfma_f32_16x16x32_bf16 v[80:83], v[112:115], v[238:241], v[80:83]
	v_mfma_f32_16x16x32_bf16 v[76:79], v[128:131], v[238:241], v[76:79]
	v_mfma_f32_16x16x32_bf16 v[136:139], v[160:163], v[202:205], v[136:139]
	v_mfma_f32_16x16x32_bf16 v[132:135], v[194:197], v[202:205], v[132:135]
	v_mfma_f32_16x16x32_bf16 v[104:107], v[160:163], v[210:213], v[104:107]
	v_mfma_f32_16x16x32_bf16 v[100:103], v[194:197], v[210:213], v[100:103]
	v_mfma_f32_16x16x32_bf16 v[88:91], v[160:163], v[218:221], v[88:91]
	v_mfma_f32_16x16x32_bf16 v[84:87], v[194:197], v[218:221], v[84:87]
	v_mfma_f32_16x16x32_bf16 v[72:75], v[160:163], v[234:237], v[72:75]
	v_mfma_f32_16x16x32_bf16 v[68:71], v[194:197], v[234:237], v[68:71]
	v_mfma_f32_16x16x32_bf16 v[136:139], v[190:193], v[206:209], v[136:139]
	v_mfma_f32_16x16x32_bf16 v[132:135], v[198:201], v[206:209], v[132:135]
	v_mfma_f32_16x16x32_bf16 v[104:107], v[190:193], v[214:217], v[104:107]
	v_mfma_f32_16x16x32_bf16 v[100:103], v[198:201], v[214:217], v[100:103]
	v_mfma_f32_16x16x32_bf16 v[88:91], v[190:193], v[222:225], v[88:91]
	v_mfma_f32_16x16x32_bf16 v[84:87], v[198:201], v[222:225], v[84:87]
	v_mfma_f32_16x16x32_bf16 v[72:75], v[190:193], v[238:241], v[72:75]
	v_mfma_f32_16x16x32_bf16 v[68:71], v[198:201], v[238:241], v[68:71]
	s_setprio 0
	s_barrier
; #define PG8_STAGE(bufoff, gbase, voff) do { _Pragma("unroll") for (int _i = 0; _i < 2; ++_i) \
;         __builtin_amdgcn_global_load_lds((const unsigned*)((const char*)(gbase) + (voff)[_i]), (PG8_LAS unsigned*)(lds + (bufoff) + ldsw + _i * 8192), 16, 0, 0); } while (0)
; #define PG8_LDA(dst, b, h) do { _Pragma("unroll") for (int m = 0; m < 4; ++m) _Pragma("unroll") for (int k = 0; k < 2; ++k) dst[m][k] = *(const PG8_LAS bf16x8*)(lds + PG8_SA(b, h) + aoff + m * 2048 + k * 1024); } while (0)
; #define PG8_WAIT_V(n) asm volatile("s_waitcnt vmcnt(" #n ")" ::: "memory")
; #define PG8_WAIT_L(n) asm volatile("s_waitcnt lgkmcnt(" #n ")" ::: "memory")
; #define PG8_BAR __builtin_amdgcn_s_barrier()
; #define PG8_SCHED __builtin_amdgcn_sched_barrier(0)
;     ...
;             PG8_LDA(At, 1, 1); PG8_STAGE(PG8_SB(1, 0), b3, voffB); PG8_STAGE(PG8_SB(1, 1), b3 + hstepB, voffB); PG8_STAGE(PG8_SA(1, 0), a3, voffA);
;             PG8_WAIT_V(8); PG8_WAIT_L(0); PG8_BAR; PG8_MMA(1, 0, At, B0); PG8_MMA(1, 1, At, B1); PG8_BAR; PG8_SCHED;
	s_add_i32 s58, s71, s12
	v_lshl_add_u64 v[226:227], v[226:227], 0, s[22:23]
	s_mov_b32 m0, s58
	ds_read_b128 v[202:205], v188 offset:49152
	ds_read_b128 v[206:209], v188 offset:50176
	ds_read_b128 v[210:213], v188 offset:51200
	ds_read_b128 v[214:217], v188 offset:52224
	ds_read_b128 v[218:221], v188 offset:53248
	ds_read_b128 v[222:225], v188 offset:54272
	ds_read_b128 v[234:237], v188 offset:55296
	ds_read_b128 v[238:241], v188 offset:56320
	global_load_lds_dwordx4 v[226:227], off
	v_lshl_add_u64 v[226:227], v[242:243], 0, s[22:23]
	s_add_i32 m0, s58, 0x2000
	s_add_i32 s58, s74, s12
	global_load_lds_dwordx4 v[226:227], off
	v_lshl_add_u64 v[226:227], v[244:245], 0, s[22:23]
	s_mov_b32 m0, s58
	s_nop 0
	global_load_lds_dwordx4 v[226:227], off
	v_lshl_add_u64 v[226:227], v[246:247], 0, s[22:23]
	s_add_i32 m0, s58, 0x2000
	s_nop 0
	global_load_lds_dwordx4 v[226:227], off
	v_lshl_add_u64 v[226:227], v[248:249], 0, s[22:23]
	s_mov_b32 m0, s57
	s_nop 0
	global_load_lds_dwordx4 v[226:227], off
	v_lshl_add_u64 v[226:227], v[250:251], 0, s[22:23]
	s_mov_b32 m0, s62
	s_nop 0
	global_load_lds_dwordx4 v[226:227], off
	s_waitcnt vmcnt(8)
	s_waitcnt lgkmcnt(0)
	s_barrier
	s_setprio 1
	v_mfma_f32_16x16x32_bf16 v[64:67], v[108:111], v[202:205], v[64:67]
	v_mfma_f32_16x16x32_bf16 v[60:63], v[124:127], v[202:205], v[60:63]
	v_mfma_f32_16x16x32_bf16 v[48:51], v[108:111], v[210:213], v[48:51]
	v_mfma_f32_16x16x32_bf16 v[44:47], v[124:127], v[210:213], v[44:47]
	v_mfma_f32_16x16x32_bf16 v[30:33], v[108:111], v[218:221], v[30:33]
	v_mfma_f32_16x16x32_bf16 v[26:29], v[124:127], v[218:221], v[26:29]
	v_mfma_f32_16x16x32_bf16 v[14:17], v[108:111], v[234:237], v[14:17]
	v_mfma_f32_16x16x32_bf16 v[10:13], v[124:127], v[234:237], v[10:13]
	v_mfma_f32_16x16x32_bf16 v[64:67], v[112:115], v[206:209], v[64:67]
	v_mfma_f32_16x16x32_bf16 v[60:63], v[128:131], v[206:209], v[60:63]
	v_mfma_f32_16x16x32_bf16 v[48:51], v[112:115], v[214:217], v[48:51]
	v_mfma_f32_16x16x32_bf16 v[44:47], v[128:131], v[214:217], v[44:47]
	v_mfma_f32_16x16x32_bf16 v[30:33], v[112:115], v[222:225], v[30:33]
	v_mfma_f32_16x16x32_bf16 v[26:29], v[128:131], v[222:225], v[26:29]
	v_mfma_f32_16x16x32_bf16 v[14:17], v[112:115], v[238:241], v[14:17]
	v_mfma_f32_16x16x32_bf16 v[10:13], v[128:131], v[238:241], v[10:13]
	v_mfma_f32_16x16x32_bf16 v[56:59], v[160:163], v[202:205], v[56:59]
	v_mfma_f32_16x16x32_bf16 v[52:55], v[194:197], v[202:205], v[52:55]
	v_mfma_f32_16x16x32_bf16 v[40:43], v[160:163], v[210:213], v[40:43]
	v_mfma_f32_16x16x32_bf16 v[36:39], v[194:197], v[210:213], v[36:39]
	v_mfma_f32_16x16x32_bf16 v[22:25], v[160:163], v[218:221], v[22:25]
	v_mfma_f32_16x16x32_bf16 v[18:21], v[194:197], v[218:221], v[18:21]
	v_mfma_f32_16x16x32_bf16 v[6:9], v[160:163], v[234:237], v[6:9]
	v_mfma_f32_16x16x32_bf16 v[2:5], v[194:197], v[234:237], v[2:5]
	v_mfma_f32_16x16x32_bf16 v[56:59], v[190:193], v[206:209], v[56:59]
	v_mfma_f32_16x16x32_bf16 v[52:55], v[198:201], v[206:209], v[52:55]
	v_mfma_f32_16x16x32_bf16 v[40:43], v[190:193], v[214:217], v[40:43]
	v_mfma_f32_16x16x32_bf16 v[36:39], v[198:201], v[214:217], v[36:39]
	v_mfma_f32_16x16x32_bf16 v[22:25], v[190:193], v[222:225], v[22:25]
	v_mfma_f32_16x16x32_bf16 v[18:21], v[198:201], v[222:225], v[18:21]
	v_mfma_f32_16x16x32_bf16 v[6:9], v[190:193], v[238:241], v[6:9]
	v_mfma_f32_16x16x32_bf16 v[2:5], v[198:201], v[238:241], v[2:5]
	s_setprio 0
	s_barrier
	s_add_u32 s40, s40, 0x100
	s_addc_u32 s41, s41, 0
	s_add_u32 s60, s60, 0x100
	s_addc_u32 s61, s61, 0
	s_cmp_ge_i32 s70, s35
	s_mov_b32 s58, s70
	s_cbranch_scc0 .LBB0_1503
	s_movk_i32 s71, 0x6ff

; #define PG8_STAGE(bufoff, gbase, voff) do { _Pragma("unroll") for (int _i = 0; _i < 2; ++_i) \
;         __builtin_amdgcn_global_load_lds((const unsigned*)((const char*)(gbase) + (voff)[_i]), (PG8_LAS unsigned*)(lds + (bufoff) + ldsw + _i * 8192), 16, 0, 0); } while (0)
; #define PG8_LDA(dst, b, h) do { _Pragma("unroll") for (int m = 0; m < 4; ++m) _Pragma("unroll") for (int k = 0; k < 2; ++k) dst[m][k] = *(const PG8_LAS bf16x8*)(lds + PG8_SA(b, h) + aoff + m * 2048 + k * 1024); } while (0)
; #define PG8_LDB(dst, b, h) do { _Pragma("unroll") for (int n = 0; n < 2; ++n) _Pragma("unroll") for (int k = 0; k < 2; ++k) dst[n][k] = *(const PG8_LAS bf16x8*)(lds + PG8_SB(b, h) + boff + n * 2048 + k * 1024); } while (0)
; #define PG8_WAIT_V(n) asm volatile("s_waitcnt vmcnt(" #n ")" ::: "memory")
; #define PG8_WAIT_L(n) asm volatile("s_waitcnt lgkmcnt(" #n ")" ::: "memory")
; #define PG8_BAR __builtin_amdgcn_s_barrier()
; #define PG8_SCHED __builtin_amdgcn_sched_barrier(0)
;     ...
;             const bool last = (t == nt - 2);
;             const char* a1 = cA + (size_t)(t + 1) * kstep;
;             const char* a2 = last ? nA : cA + (size_t)(t + 2) * kstep; const char* b2 = last ? nB : cB + (size_t)(t + 2) * kstep;
;             const char* a3 = a2 + kstep; const char* b3 = b2 + kstep;
;             if (last && has_next) S.a_ready(nxt);
;             if constexpr (SP2) {
;             PG8_LDB(B0, 0, 0); PG8_LDB(B1, 0, 1); PG8_SCHED; PG8_LDA(At, 0, 0); PG8_STAGE(PG8_SA(1, 1), a1 + hstepA, voffA);
;             PG8_WAIT_V(8); PG8_WAIT_L(0); PG8_BAR; PG8_MMA(0, 0, At, B0); PG8_MMA(0, 1, At, B1); PG8_BAR; PG8_SCHED;
;             PG8_LDA(At, 0, 1); PG8_STAGE(PG8_SB(0, 0), b2, voffB); PG8_STAGE(PG8_SB(0, 1), b2 + hstepB, voffB); PG8_STAGE(PG8_SA(0, 0), a2, voffA);
;             PG8_WAIT_V(8); PG8_WAIT_L(0); PG8_BAR; PG8_MMA(1, 0, At, B0); PG8_MMA(1, 1, At, B1); PG8_BAR; PG8_SCHED;
.LBB0_2023:
	v_add_u32_e32 v163, 0x10000, v235
	s_add_u32 s35, s40, 0xfffc0080
	s_addc_u32 s37, s41, -1
	s_add_i32 s43, 0, 0x10000
	s_cmp_eq_u32 s34, 12
	s_cselect_b32 s57, s49, s37
	s_cselect_b32 s56, s48, s35
	s_cselect_b32 s55, s51, s24
	s_cselect_b32 s54, s50, s15
	s_add_i32 s35, 0, 0x14000
	ds_read_b128 v[142:145], v163
	ds_read_b128 v[146:149], v163 offset:1024
	ds_read_b128 v[150:153], v163 offset:2048
	ds_read_b128 v[154:157], v163 offset:3072
	ds_read_b128 v[158:161], v163 offset:16384
	ds_read_b128 v[186:189], v163 offset:17408
	ds_read_b128 v[190:193], v163 offset:18432
	ds_read_b128 v[194:197], v163 offset:19456
	s_add_i32 m0, s53, 0xc000
	ds_read_b128 v[198:201], v237
	ds_read_b128 v[202:205], v237 offset:1024
	ds_read_b128 v[206:209], v237 offset:2048
	ds_read_b128 v[210:213], v237 offset:3072
	ds_read_b128 v[214:217], v237 offset:4096
	ds_read_b128 v[218:221], v237 offset:5120
	ds_read_b128 v[222:225], v237 offset:6144
	ds_read_b128 v[238:241], v237 offset:7168
	global_load_lds_dwordx4 v138, s[40:41]
	s_add_i32 m0, s53, 0xe000
	s_nop 0
	global_load_lds_dwordx4 v140, s[40:41]
	s_waitcnt vmcnt(8)
	s_waitcnt lgkmcnt(0)
	s_barrier
	s_setprio 1
	v_mfma_f32_16x16x32_bf16 v[128:131], v[142:145], v[198:201], v[128:131]
	v_mfma_f32_16x16x32_bf16 v[124:127], v[150:153], v[198:201], v[124:127]
	v_mfma_f32_16x16x32_bf16 v[120:123], v[142:145], v[206:209], v[120:123]
	v_mfma_f32_16x16x32_bf16 v[116:119], v[150:153], v[206:209], v[116:119]
	v_mfma_f32_16x16x32_bf16 v[112:115], v[142:145], v[214:217], v[112:115]
	v_mfma_f32_16x16x32_bf16 v[108:111], v[150:153], v[214:217], v[108:111]
	v_mfma_f32_16x16x32_bf16 v[104:107], v[142:145], v[222:225], v[104:107]
	v_mfma_f32_16x16x32_bf16 v[100:103], v[150:153], v[222:225], v[100:103]
	v_mfma_f32_16x16x32_bf16 v[128:131], v[146:149], v[202:205], v[128:131]
	v_mfma_f32_16x16x32_bf16 v[124:127], v[154:157], v[202:205], v[124:127]
	v_mfma_f32_16x16x32_bf16 v[120:123], v[146:149], v[210:213], v[120:123]
	v_mfma_f32_16x16x32_bf16 v[116:119], v[154:157], v[210:213], v[116:119]
	v_mfma_f32_16x16x32_bf16 v[112:115], v[146:149], v[218:221], v[112:115]
	v_mfma_f32_16x16x32_bf16 v[108:111], v[154:157], v[218:221], v[108:111]
	v_mfma_f32_16x16x32_bf16 v[104:107], v[146:149], v[238:241], v[104:107]
	v_mfma_f32_16x16x32_bf16 v[100:103], v[154:157], v[238:241], v[100:103]
	v_mfma_f32_16x16x32_bf16 v[96:99], v[158:161], v[198:201], v[96:99]
	v_mfma_f32_16x16x32_bf16 v[92:95], v[190:193], v[198:201], v[92:95]
	v_mfma_f32_16x16x32_bf16 v[88:91], v[158:161], v[206:209], v[88:91]
	v_mfma_f32_16x16x32_bf16 v[84:87], v[190:193], v[206:209], v[84:87]
	v_mfma_f32_16x16x32_bf16 v[80:83], v[158:161], v[214:217], v[80:83]
	v_mfma_f32_16x16x32_bf16 v[76:79], v[190:193], v[214:217], v[76:79]
	v_mfma_f32_16x16x32_bf16 v[72:75], v[158:161], v[222:225], v[72:75]
	v_mfma_f32_16x16x32_bf16 v[68:71], v[190:193], v[222:225], v[68:71]
	v_mfma_f32_16x16x32_bf16 v[96:99], v[186:189], v[202:205], v[96:99]
	v_mfma_f32_16x16x32_bf16 v[92:95], v[194:197], v[202:205], v[92:95]
	v_mfma_f32_16x16x32_bf16 v[88:91], v[186:189], v[210:213], v[88:91]
	v_mfma_f32_16x16x32_bf16 v[84:87], v[194:197], v[210:213], v[84:87]
	v_mfma_f32_16x16x32_bf16 v[80:83], v[186:189], v[218:221], v[80:83]
	v_mfma_f32_16x16x32_bf16 v[76:79], v[194:197], v[218:221], v[76:79]
	v_mfma_f32_16x16x32_bf16 v[72:75], v[186:189], v[238:241], v[72:75]
	v_mfma_f32_16x16x32_bf16 v[68:71], v[194:197], v[238:241], v[68:71]
	s_setprio 0
	s_barrier
	s_add_i32 s37, s43, s21
	s_mov_b32 m0, s37
	ds_read_b128 v[198:201], v237 offset:16384
	ds_read_b128 v[202:205], v237 offset:17408
	ds_read_b128 v[206:209], v237 offset:18432
	ds_read_b128 v[210:213], v237 offset:19456
	ds_read_b128 v[214:217], v237 offset:20480
	ds_read_b128 v[218:221], v237 offset:21504
	ds_read_b128 v[222:225], v237 offset:22528
	ds_read_b128 v[238:241], v237 offset:23552
	global_load_lds_dwordx4 v34, s[54:55]
	s_add_i32 m0, s37, 0x2000
	s_add_u32 s66, s54, 0x40000
	s_addc_u32 s67, s55, 0
	s_add_i32 s35, s35, s21
	global_load_lds_dwordx4 v136, s[54:55]
	s_mov_b32 m0, s35
	s_nop 0
	global_load_lds_dwordx4 v34, s[66:67]
	s_add_i32 m0, s35, 0x2000
	s_nop 0
	global_load_lds_dwordx4 v136, s[66:67]
	s_mov_b32 m0, s53
	s_nop 0
	global_load_lds_dwordx4 v132, s[56:57]
	s_mov_b32 m0, s58
	s_nop 0
	global_load_lds_dwordx4 v134, s[56:57]
	s_waitcnt vmcnt(8)
	s_waitcnt lgkmcnt(0)
	s_barrier
	s_setprio 1
	v_mfma_f32_16x16x32_bf16 v[64:67], v[142:145], v[198:201], v[64:67]
	v_mfma_f32_16x16x32_bf16 v[60:63], v[150:153], v[198:201], v[60:63]
	v_mfma_f32_16x16x32_bf16 v[56:59], v[142:145], v[206:209], v[56:59]
	v_mfma_f32_16x16x32_bf16 v[52:55], v[150:153], v[206:209], v[52:55]
	v_mfma_f32_16x16x32_bf16 v[48:51], v[142:145], v[214:217], v[48:51]
	v_mfma_f32_16x16x32_bf16 v[44:47], v[150:153], v[214:217], v[44:47]
	v_mfma_f32_16x16x32_bf16 v[40:43], v[142:145], v[222:225], v[40:43]
	v_mfma_f32_16x16x32_bf16 v[36:39], v[150:153], v[222:225], v[36:39]
	v_mfma_f32_16x16x32_bf16 v[64:67], v[146:149], v[202:205], v[64:67]
	v_mfma_f32_16x16x32_bf16 v[60:63], v[154:157], v[202:205], v[60:63]
	v_mfma_f32_16x16x32_bf16 v[56:59], v[146:149], v[210:213], v[56:59]
	v_mfma_f32_16x16x32_bf16 v[52:55], v[154:157], v[210:213], v[52:55]
	v_mfma_f32_16x16x32_bf16 v[48:51], v[146:149], v[218:221], v[48:51]
	v_mfma_f32_16x16x32_bf16 v[44:47], v[154:157], v[218:221], v[44:47]
	v_mfma_f32_16x16x32_bf16 v[40:43], v[146:149], v[238:241], v[40:43]
	v_mfma_f32_16x16x32_bf16 v[36:39], v[154:157], v[238:241], v[36:39]
	v_mfma_f32_16x16x32_bf16 v[30:33], v[158:161], v[198:201], v[30:33]
	v_mfma_f32_16x16x32_bf16 v[26:29], v[190:193], v[198:201], v[26:29]
	v_mfma_f32_16x16x32_bf16 v[22:25], v[158:161], v[206:209], v[22:25]
	v_mfma_f32_16x16x32_bf16 v[18:21], v[190:193], v[206:209], v[18:21]
	v_mfma_f32_16x16x32_bf16 v[14:17], v[158:161], v[214:217], v[14:17]
	v_mfma_f32_16x16x32_bf16 v[10:13], v[190:193], v[214:217], v[10:13]
	v_mfma_f32_16x16x32_bf16 v[6:9], v[158:161], v[222:225], v[6:9]
	v_mfma_f32_16x16x32_bf16 v[2:5], v[190:193], v[222:225], v[2:5]
	v_mfma_f32_16x16x32_bf16 v[30:33], v[186:189], v[202:205], v[30:33]
	v_mfma_f32_16x16x32_bf16 v[26:29], v[194:197], v[202:205], v[26:29]
	v_mfma_f32_16x16x32_bf16 v[22:25], v[186:189], v[210:213], v[22:25]
	v_mfma_f32_16x16x32_bf16 v[18:21], v[194:197], v[210:213], v[18:21]
	v_mfma_f32_16x16x32_bf16 v[14:17], v[186:189], v[218:221], v[14:17]
	v_mfma_f32_16x16x32_bf16 v[10:13], v[194:197], v[218:221], v[10:13]
	v_mfma_f32_16x16x32_bf16 v[6:9], v[186:189], v[238:241], v[6:9]
	v_mfma_f32_16x16x32_bf16 v[2:5], v[194:197], v[238:241], v[2:5]
	s_setprio 0
	s_barrier
; #define PG8_STAGE(bufoff, gbase, voff) do { _Pragma("unroll") for (int _i = 0; _i < 2; ++_i) \
;         __builtin_amdgcn_global_load_lds((const unsigned*)((const char*)(gbase) + (voff)[_i]), (PG8_LAS unsigned*)(lds + (bufoff) + ldsw + _i * 8192), 16, 0, 0); } while (0)
; #define PG8_LDA(dst, b, h) do { _Pragma("unroll") for (int m = 0; m < 4; ++m) _Pragma("unroll") for (int k = 0; k < 2; ++k) dst[m][k] = *(const PG8_LAS bf16x8*)(lds + PG8_SA(b, h) + aoff + m * 2048 + k * 1024); } while (0)
; #define PG8_LDB(dst, b, h) do { _Pragma("unroll") for (int n = 0; n < 2; ++n) _Pragma("unroll") for (int k = 0; k < 2; ++k) dst[n][k] = *(const PG8_LAS bf16x8*)(lds + PG8_SB(b, h) + boff + n * 2048 + k * 1024); } while (0)
; #define PG8_WAIT_V(n) asm volatile("s_waitcnt vmcnt(" #n ")" ::: "memory")
; #define PG8_WAIT_L(n) asm volatile("s_waitcnt lgkmcnt(" #n ")" ::: "memory")
; #define PG8_BAR __builtin_amdgcn_s_barrier()
; #define PG8_SCHED __builtin_amdgcn_sched_barrier(0)
;     ...
;             PG8_LDB(B0, 1, 0); PG8_LDB(B1, 1, 1); PG8_SCHED; PG8_LDA(At, 1, 0); PG8_STAGE(PG8_SA(0, 1), a2 + hstepA, voffA);
;             PG8_WAIT_V(8); PG8_WAIT_L(0); PG8_BAR; PG8_MMA(0, 0, At, B0); PG8_MMA(0, 1, At, B1); PG8_BAR; PG8_SCHED;
;             PG8_LDA(At, 1, 1); PG8_STAGE(PG8_SB(1, 0), b3, voffB); PG8_STAGE(PG8_SB(1, 1), b3 + hstepB, voffB); PG8_STAGE(PG8_SA(1, 0), a3, voffA);
;             PG8_WAIT_V(8); PG8_WAIT_L(0); PG8_BAR; PG8_MMA(1, 0, At, B0); PG8_MMA(1, 1, At, B1); PG8_BAR; PG8_SCHED;
	s_add_i32 s35, 0, 0x18000
	s_add_i32 s37, 0, 0x1c000
	ds_read_b128 v[142:145], v163 offset:32768
	ds_read_b128 v[146:149], v163 offset:33792
	ds_read_b128 v[150:153], v163 offset:34816
	ds_read_b128 v[154:157], v163 offset:35840
	ds_read_b128 v[158:161], v163 offset:49152
	ds_read_b128 v[186:189], v163 offset:50176
	ds_read_b128 v[190:193], v163 offset:51200
	ds_read_b128 v[194:197], v163 offset:52224
	s_add_u32 s56, s56, 0x40000
	s_addc_u32 s57, s57, 0
	s_mov_b32 m0, s59
	ds_read_b128 v[198:201], v237 offset:32768
	ds_read_b128 v[202:205], v237 offset:33792
	ds_read_b128 v[206:209], v237 offset:34816
	ds_read_b128 v[210:213], v237 offset:35840
	ds_read_b128 v[214:217], v237 offset:36864
	ds_read_b128 v[218:221], v237 offset:37888
	ds_read_b128 v[222:225], v237 offset:38912
	ds_read_b128 v[238:241], v237 offset:39936
	global_load_lds_dwordx4 v132, s[56:57]
	s_mov_b32 m0, s60
	s_nop 0
	global_load_lds_dwordx4 v134, s[56:57]
	s_waitcnt vmcnt(8)
	s_waitcnt lgkmcnt(0)
	s_barrier
	s_setprio 1
	v_mfma_f32_16x16x32_bf16 v[128:131], v[142:145], v[198:201], v[128:131]
	v_mfma_f32_16x16x32_bf16 v[124:127], v[150:153], v[198:201], v[124:127]
	v_mfma_f32_16x16x32_bf16 v[120:123], v[142:145], v[206:209], v[120:123]
	v_mfma_f32_16x16x32_bf16 v[116:119], v[150:153], v[206:209], v[116:119]
	v_mfma_f32_16x16x32_bf16 v[112:115], v[142:145], v[214:217], v[112:115]
	v_mfma_f32_16x16x32_bf16 v[108:111], v[150:153], v[214:217], v[108:111]
	v_mfma_f32_16x16x32_bf16 v[104:107], v[142:145], v[222:225], v[104:107]
	v_mfma_f32_16x16x32_bf16 v[100:103], v[150:153], v[222:225], v[100:103]
	v_mfma_f32_16x16x32_bf16 v[128:131], v[146:149], v[202:205], v[128:131]
	v_mfma_f32_16x16x32_bf16 v[124:127], v[154:157], v[202:205], v[124:127]
	v_mfma_f32_16x16x32_bf16 v[120:123], v[146:149], v[210:213], v[120:123]
	v_mfma_f32_16x16x32_bf16 v[116:119], v[154:157], v[210:213], v[116:119]
	v_mfma_f32_16x16x32_bf16 v[112:115], v[146:149], v[218:221], v[112:115]
	v_mfma_f32_16x16x32_bf16 v[108:111], v[154:157], v[218:221], v[108:111]
	v_mfma_f32_16x16x32_bf16 v[104:107], v[146:149], v[238:241], v[104:107]
	v_mfma_f32_16x16x32_bf16 v[100:103], v[154:157], v[238:241], v[100:103]
	v_mfma_f32_16x16x32_bf16 v[96:99], v[158:161], v[198:201], v[96:99]
	v_mfma_f32_16x16x32_bf16 v[92:95], v[190:193], v[198:201], v[92:95]
	v_mfma_f32_16x16x32_bf16 v[88:91], v[158:161], v[206:209], v[88:91]
	v_mfma_f32_16x16x32_bf16 v[84:87], v[190:193], v[206:209], v[84:87]
	v_mfma_f32_16x16x32_bf16 v[80:83], v[158:161], v[214:217], v[80:83]
	v_mfma_f32_16x16x32_bf16 v[76:79], v[190:193], v[214:217], v[76:79]
	v_mfma_f32_16x16x32_bf16 v[72:75], v[158:161], v[222:225], v[72:75]
	v_mfma_f32_16x16x32_bf16 v[68:71], v[190:193], v[222:225], v[68:71]
	v_mfma_f32_16x16x32_bf16 v[96:99], v[186:189], v[202:205], v[96:99]
	v_mfma_f32_16x16x32_bf16 v[92:95], v[194:197], v[202:205], v[92:95]
	v_mfma_f32_16x16x32_bf16 v[88:91], v[186:189], v[210:213], v[88:91]
	v_mfma_f32_16x16x32_bf16 v[84:87], v[194:197], v[210:213], v[84:87]
	v_mfma_f32_16x16x32_bf16 v[80:83], v[186:189], v[218:221], v[80:83]
	v_mfma_f32_16x16x32_bf16 v[76:79], v[194:197], v[218:221], v[76:79]
	v_mfma_f32_16x16x32_bf16 v[72:75], v[186:189], v[238:241], v[72:75]
	v_mfma_f32_16x16x32_bf16 v[68:71], v[194:197], v[238:241], v[68:71]
	s_setprio 0
	s_barrier
	s_add_i32 s35, s35, s21
	s_mov_b32 m0, s35
	ds_read_b128 v[198:201], v237 offset:49152
	ds_read_b128 v[202:205], v237 offset:50176
	ds_read_b128 v[206:209], v237 offset:51200
	ds_read_b128 v[210:213], v237 offset:52224
	ds_read_b128 v[214:217], v237 offset:53248
	ds_read_b128 v[218:221], v237 offset:54272
	ds_read_b128 v[222:225], v237 offset:55296
	ds_read_b128 v[238:241], v237 offset:56320
	s_add_u32 s98, s54, 0x80
	s_addc_u32 s99, s55, 0
	global_load_lds_dwordx4 v34, s[98:99]
	s_add_i32 m0, s35, 0x2000
	s_add_u32 s54, s54, 0x40080
	s_addc_u32 s55, s55, 0
	s_add_i32 s35, s37, s21
	s_add_u32 s98, s54, 0xfffc0000
	s_addc_u32 s99, s55, -1
	global_load_lds_dwordx4 v136, s[98:99]
	s_mov_b32 m0, s35
	s_nop 0
	global_load_lds_dwordx4 v34, s[54:55]
	s_add_i32 m0, s35, 0x2000
	s_nop 0
	global_load_lds_dwordx4 v136, s[54:55]
	s_mov_b32 m0, s61
	s_nop 0
	s_add_u32 s98, s56, 0xfffc0080
	s_addc_u32 s99, s57, -1
	global_load_lds_dwordx4 v132, s[98:99]
	s_mov_b32 m0, s62
	s_nop 0
	s_add_u32 s98, s56, 0xfffc0080
	s_addc_u32 s99, s57, -1
	global_load_lds_dwordx4 v134, s[98:99]
	s_waitcnt vmcnt(8)
	s_waitcnt lgkmcnt(0)
	s_barrier
	s_setprio 1
	v_mfma_f32_16x16x32_bf16 v[64:67], v[142:145], v[198:201], v[64:67]
	v_mfma_f32_16x16x32_bf16 v[60:63], v[150:153], v[198:201], v[60:63]
	v_mfma_f32_16x16x32_bf16 v[56:59], v[142:145], v[206:209], v[56:59]
	v_mfma_f32_16x16x32_bf16 v[52:55], v[150:153], v[206:209], v[52:55]
	v_mfma_f32_16x16x32_bf16 v[48:51], v[142:145], v[214:217], v[48:51]
	v_mfma_f32_16x16x32_bf16 v[44:47], v[150:153], v[214:217], v[44:47]
	v_mfma_f32_16x16x32_bf16 v[40:43], v[142:145], v[222:225], v[40:43]
	v_mfma_f32_16x16x32_bf16 v[36:39], v[150:153], v[222:225], v[36:39]
	v_mfma_f32_16x16x32_bf16 v[64:67], v[146:149], v[202:205], v[64:67]
	v_mfma_f32_16x16x32_bf16 v[60:63], v[154:157], v[202:205], v[60:63]
	v_mfma_f32_16x16x32_bf16 v[56:59], v[146:149], v[210:213], v[56:59]
	v_mfma_f32_16x16x32_bf16 v[52:55], v[154:157], v[210:213], v[52:55]
	v_mfma_f32_16x16x32_bf16 v[48:51], v[146:149], v[218:221], v[48:51]
	v_mfma_f32_16x16x32_bf16 v[44:47], v[154:157], v[218:221], v[44:47]
	v_mfma_f32_16x16x32_bf16 v[40:43], v[146:149], v[238:241], v[40:43]
	v_mfma_f32_16x16x32_bf16 v[36:39], v[154:157], v[238:241], v[36:39]
	v_mfma_f32_16x16x32_bf16 v[30:33], v[158:161], v[198:201], v[30:33]
	v_mfma_f32_16x16x32_bf16 v[26:29], v[190:193], v[198:201], v[26:29]
	v_mfma_f32_16x16x32_bf16 v[22:25], v[158:161], v[206:209], v[22:25]
	v_mfma_f32_16x16x32_bf16 v[18:21], v[190:193], v[206:209], v[18:21]
	v_mfma_f32_16x16x32_bf16 v[14:17], v[158:161], v[214:217], v[14:17]
	v_mfma_f32_16x16x32_bf16 v[10:13], v[190:193], v[214:217], v[10:13]
	v_mfma_f32_16x16x32_bf16 v[6:9], v[158:161], v[222:225], v[6:9]
	v_mfma_f32_16x16x32_bf16 v[2:5], v[190:193], v[222:225], v[2:5]
	v_mfma_f32_16x16x32_bf16 v[30:33], v[186:189], v[202:205], v[30:33]
	v_mfma_f32_16x16x32_bf16 v[26:29], v[194:197], v[202:205], v[26:29]
	v_mfma_f32_16x16x32_bf16 v[22:25], v[186:189], v[210:213], v[22:25]
	v_mfma_f32_16x16x32_bf16 v[18:21], v[194:197], v[210:213], v[18:21]
	v_mfma_f32_16x16x32_bf16 v[14:17], v[186:189], v[218:221], v[14:17]
	v_mfma_f32_16x16x32_bf16 v[10:13], v[194:197], v[218:221], v[10:13]
	v_mfma_f32_16x16x32_bf16 v[6:9], v[186:189], v[238:241], v[6:9]
	v_mfma_f32_16x16x32_bf16 v[2:5], v[194:197], v[238:241], v[2:5]
	s_setprio 0
	s_barrier
	s_add_i32 s34, s34, 2
	s_add_u32 s40, s40, 0x100
	s_addc_u32 s41, s41, 0
	s_add_u32 s15, s15, 0x100
	s_addc_u32 s24, s24, 0
	s_cmp_gt_u32 s34, 13
	s_cbranch_scc0 .LBB0_2023
	s_and_b64 vcc, exec, s[30:31]
	s_cbranch_vccz .LBB0_2026
	s_barrier

; #define PG8_STAGE(bufoff, gbase, voff) do { _Pragma("unroll") for (int _i = 0; _i < 2; ++_i) \
;         __builtin_amdgcn_global_load_lds((const unsigned*)((const char*)(gbase) + (voff)[_i]), (PG8_LAS unsigned*)(lds + (bufoff) + ldsw + _i * 8192), 16, 0, 0); } while (0)
; #define PG8_LDA(dst, b, h) do { _Pragma("unroll") for (int m = 0; m < 4; ++m) _Pragma("unroll") for (int k = 0; k < 2; ++k) dst[m][k] = *(const PG8_LAS bf16x8*)(lds + PG8_SA(b, h) + aoff + m * 2048 + k * 1024); } while (0)
; #define PG8_LDB(dst, b, h) do { _Pragma("unroll") for (int n = 0; n < 2; ++n) _Pragma("unroll") for (int k = 0; k < 2; ++k) dst[n][k] = *(const PG8_LAS bf16x8*)(lds + PG8_SB(b, h) + boff + n * 2048 + k * 1024); } while (0)
; #define PG8_WAIT_V(n) asm volatile("s_waitcnt vmcnt(" #n ")" ::: "memory")
; #define PG8_WAIT_L(n) asm volatile("s_waitcnt lgkmcnt(" #n ")" ::: "memory")
; #define PG8_BAR __builtin_amdgcn_s_barrier()
; #define PG8_SCHED __builtin_amdgcn_sched_barrier(0)
;     ...
;             const bool last = (t == nt - 2);
;             const char* a1 = cA + (size_t)(t + 1) * kstep;
;             const char* a2 = last ? nA : cA + (size_t)(t + 2) * kstep; const char* b2 = last ? nB : cB + (size_t)(t + 2) * kstep;
;             const char* a3 = a2 + kstep; const char* b3 = b2 + kstep;
;             if (last && has_next) S.a_ready(nxt);
;             if constexpr (SP2) {
;             PG8_LDB(B0, 0, 0); PG8_LDB(B1, 0, 1); PG8_SCHED; PG8_LDA(At, 0, 0); PG8_STAGE(PG8_SA(1, 1), a1 + hstepA, voffA);
;             PG8_WAIT_V(8); PG8_WAIT_L(0); PG8_BAR; PG8_MMA(0, 0, At, B0); PG8_MMA(0, 1, At, B1); PG8_BAR; PG8_SCHED;
;             PG8_LDA(At, 0, 1); PG8_STAGE(PG8_SB(0, 0), b2, voffB); PG8_STAGE(PG8_SB(0, 1), b2 + hstepB, voffB); PG8_STAGE(PG8_SA(0, 0), a2, voffA);
;             PG8_WAIT_V(8); PG8_WAIT_L(0); PG8_BAR; PG8_MMA(1, 0, At, B0); PG8_MMA(1, 1, At, B1); PG8_BAR; PG8_SCHED;
.LBB0_2138:
	v_add_u32_e32 v226, 0x10000, v143
	s_add_u32 s48, s46, 0xfff80080
	s_addc_u32 s49, s47, -1
	s_add_i32 s61, 0, 0x10000
	s_cmp_eq_u32 s60, 28
	s_cselect_b32 s51, s41, s49
	s_cselect_b32 s50, s56, s48
	s_cselect_b32 s49, s37, s59
	s_cselect_b32 s48, s57, s58
	s_add_i32 s64, 0, 0x14000
	ds_read_b128 v[146:149], v226
	ds_read_b128 v[150:153], v226 offset:1024
	ds_read_b128 v[154:157], v226 offset:2048
	ds_read_b128 v[158:161], v226 offset:3072
	ds_read_b128 v[186:189], v226 offset:16384
	ds_read_b128 v[190:193], v226 offset:17408
	ds_read_b128 v[194:197], v226 offset:18432
	ds_read_b128 v[198:201], v226 offset:19456
	s_add_i32 m0, s21, 0xc000
	ds_read_b128 v[202:205], v145
	ds_read_b128 v[206:209], v145 offset:1024
	ds_read_b128 v[210:213], v145 offset:2048
	ds_read_b128 v[214:217], v145 offset:3072
	ds_read_b128 v[218:221], v145 offset:4096
	ds_read_b128 v[222:225], v145 offset:5120
	ds_read_b128 v[234:237], v145 offset:6144
	ds_read_b128 v[238:241], v145 offset:7168
	global_load_lds_dwordx4 v138, s[46:47]
	s_add_i32 m0, s21, 0xe000
	s_nop 0
	global_load_lds_dwordx4 v140, s[46:47]
	s_waitcnt vmcnt(8)
	s_waitcnt lgkmcnt(0)
	s_barrier
	s_setprio 1
	v_mfma_f32_16x16x32_bf16 v[128:131], v[146:149], v[202:205], v[128:131]
	v_mfma_f32_16x16x32_bf16 v[124:127], v[154:157], v[202:205], v[124:127]
	v_mfma_f32_16x16x32_bf16 v[120:123], v[146:149], v[210:213], v[120:123]
	v_mfma_f32_16x16x32_bf16 v[116:119], v[154:157], v[210:213], v[116:119]
	v_mfma_f32_16x16x32_bf16 v[104:107], v[146:149], v[218:221], v[104:107]
	v_mfma_f32_16x16x32_bf16 v[100:103], v[154:157], v[218:221], v[100:103]
	v_mfma_f32_16x16x32_bf16 v[88:91], v[146:149], v[234:237], v[88:91]
	v_mfma_f32_16x16x32_bf16 v[84:87], v[154:157], v[234:237], v[84:87]
	v_mfma_f32_16x16x32_bf16 v[128:131], v[150:153], v[206:209], v[128:131]
	v_mfma_f32_16x16x32_bf16 v[124:127], v[158:161], v[206:209], v[124:127]
	v_mfma_f32_16x16x32_bf16 v[120:123], v[150:153], v[214:217], v[120:123]
	v_mfma_f32_16x16x32_bf16 v[116:119], v[158:161], v[214:217], v[116:119]
	v_mfma_f32_16x16x32_bf16 v[104:107], v[150:153], v[222:225], v[104:107]
	v_mfma_f32_16x16x32_bf16 v[100:103], v[158:161], v[222:225], v[100:103]
	v_mfma_f32_16x16x32_bf16 v[88:91], v[150:153], v[238:241], v[88:91]
	v_mfma_f32_16x16x32_bf16 v[84:87], v[158:161], v[238:241], v[84:87]
	v_mfma_f32_16x16x32_bf16 v[112:115], v[186:189], v[202:205], v[112:115]
	v_mfma_f32_16x16x32_bf16 v[108:111], v[194:197], v[202:205], v[108:111]
	v_mfma_f32_16x16x32_bf16 v[96:99], v[186:189], v[210:213], v[96:99]
	v_mfma_f32_16x16x32_bf16 v[92:95], v[194:197], v[210:213], v[92:95]
	v_mfma_f32_16x16x32_bf16 v[80:83], v[186:189], v[218:221], v[80:83]
	v_mfma_f32_16x16x32_bf16 v[76:79], v[194:197], v[218:221], v[76:79]
	v_mfma_f32_16x16x32_bf16 v[72:75], v[186:189], v[234:237], v[72:75]
	v_mfma_f32_16x16x32_bf16 v[68:71], v[194:197], v[234:237], v[68:71]
	v_mfma_f32_16x16x32_bf16 v[112:115], v[190:193], v[206:209], v[112:115]
	v_mfma_f32_16x16x32_bf16 v[108:111], v[198:201], v[206:209], v[108:111]
	v_mfma_f32_16x16x32_bf16 v[96:99], v[190:193], v[214:217], v[96:99]
	v_mfma_f32_16x16x32_bf16 v[92:95], v[198:201], v[214:217], v[92:95]
	v_mfma_f32_16x16x32_bf16 v[80:83], v[190:193], v[222:225], v[80:83]
	v_mfma_f32_16x16x32_bf16 v[76:79], v[198:201], v[222:225], v[76:79]
	v_mfma_f32_16x16x32_bf16 v[72:75], v[190:193], v[238:241], v[72:75]
	v_mfma_f32_16x16x32_bf16 v[68:71], v[198:201], v[238:241], v[68:71]
	s_setprio 0
	s_barrier
	s_add_i32 s61, s61, s15
	s_mov_b32 m0, s61
	ds_read_b128 v[202:205], v145 offset:16384
	ds_read_b128 v[206:209], v145 offset:17408
	ds_read_b128 v[210:213], v145 offset:18432
	ds_read_b128 v[214:217], v145 offset:19456
	ds_read_b128 v[218:221], v145 offset:20480
	ds_read_b128 v[222:225], v145 offset:21504
	ds_read_b128 v[234:237], v145 offset:22528
	ds_read_b128 v[238:241], v145 offset:23552
	global_load_lds_dwordx4 v34, s[48:49]
	s_add_i32 m0, s61, 0x2000
	s_add_u32 s62, s48, 0x80000
	s_addc_u32 s63, s49, 0
	s_add_i32 s61, s64, s15
	global_load_lds_dwordx4 v136, s[48:49]
	s_mov_b32 m0, s61
	v_lshl_add_u64 v[244:245], s[50:51], 0, v[134:135]
	global_load_lds_dwordx4 v34, s[62:63]
	s_add_i32 m0, s61, 0x2000
	s_nop 0
	global_load_lds_dwordx4 v136, s[62:63]
	v_lshl_add_u64 v[242:243], s[50:51], 0, v[132:133]
	s_mov_b32 m0, s21
	s_nop 0
	global_load_lds_dwordx4 v132, s[50:51]
	s_mov_b32 m0, s34
	s_nop 0
	global_load_lds_dwordx4 v134, s[50:51]
	s_waitcnt vmcnt(8)
	s_waitcnt lgkmcnt(0)
	s_barrier
	s_setprio 1
	v_mfma_f32_16x16x32_bf16 v[64:67], v[146:149], v[202:205], v[64:67]
	v_mfma_f32_16x16x32_bf16 v[60:63], v[154:157], v[202:205], v[60:63]
	v_mfma_f32_16x16x32_bf16 v[56:59], v[146:149], v[210:213], v[56:59]
	v_mfma_f32_16x16x32_bf16 v[52:55], v[154:157], v[210:213], v[52:55]
	v_mfma_f32_16x16x32_bf16 v[40:43], v[146:149], v[218:221], v[40:43]
	v_mfma_f32_16x16x32_bf16 v[36:39], v[154:157], v[218:221], v[36:39]
	v_mfma_f32_16x16x32_bf16 v[22:25], v[146:149], v[234:237], v[22:25]
	v_mfma_f32_16x16x32_bf16 v[18:21], v[154:157], v[234:237], v[18:21]
	v_mfma_f32_16x16x32_bf16 v[64:67], v[150:153], v[206:209], v[64:67]
	v_mfma_f32_16x16x32_bf16 v[60:63], v[158:161], v[206:209], v[60:63]
	v_mfma_f32_16x16x32_bf16 v[56:59], v[150:153], v[214:217], v[56:59]
	v_mfma_f32_16x16x32_bf16 v[52:55], v[158:161], v[214:217], v[52:55]
	v_mfma_f32_16x16x32_bf16 v[40:43], v[150:153], v[222:225], v[40:43]
	v_mfma_f32_16x16x32_bf16 v[36:39], v[158:161], v[222:225], v[36:39]
	v_mfma_f32_16x16x32_bf16 v[22:25], v[150:153], v[238:241], v[22:25]
	v_mfma_f32_16x16x32_bf16 v[18:21], v[158:161], v[238:241], v[18:21]
	v_mfma_f32_16x16x32_bf16 v[48:51], v[186:189], v[202:205], v[48:51]
	v_mfma_f32_16x16x32_bf16 v[44:47], v[194:197], v[202:205], v[44:47]
	v_mfma_f32_16x16x32_bf16 v[30:33], v[186:189], v[210:213], v[30:33]
	v_mfma_f32_16x16x32_bf16 v[26:29], v[194:197], v[210:213], v[26:29]
	v_mfma_f32_16x16x32_bf16 v[14:17], v[186:189], v[218:221], v[14:17]
	v_mfma_f32_16x16x32_bf16 v[10:13], v[194:197], v[218:221], v[10:13]
	v_mfma_f32_16x16x32_bf16 v[6:9], v[186:189], v[234:237], v[6:9]
	v_mfma_f32_16x16x32_bf16 v[2:5], v[194:197], v[234:237], v[2:5]
	v_mfma_f32_16x16x32_bf16 v[48:51], v[190:193], v[206:209], v[48:51]
	v_mfma_f32_16x16x32_bf16 v[44:47], v[198:201], v[206:209], v[44:47]
	v_mfma_f32_16x16x32_bf16 v[30:33], v[190:193], v[214:217], v[30:33]
	v_mfma_f32_16x16x32_bf16 v[26:29], v[198:201], v[214:217], v[26:29]
	v_mfma_f32_16x16x32_bf16 v[14:17], v[190:193], v[222:225], v[14:17]
	v_mfma_f32_16x16x32_bf16 v[10:13], v[198:201], v[222:225], v[10:13]
	v_mfma_f32_16x16x32_bf16 v[6:9], v[190:193], v[238:241], v[6:9]
	v_mfma_f32_16x16x32_bf16 v[2:5], v[198:201], v[238:241], v[2:5]
	s_setprio 0
	s_barrier
; #define PG8_STAGE(bufoff, gbase, voff) do { _Pragma("unroll") for (int _i = 0; _i < 2; ++_i) \
;         __builtin_amdgcn_global_load_lds((const unsigned*)((const char*)(gbase) + (voff)[_i]), (PG8_LAS unsigned*)(lds + (bufoff) + ldsw + _i * 8192), 16, 0, 0); } while (0)
; #define PG8_LDA(dst, b, h) do { _Pragma("unroll") for (int m = 0; m < 4; ++m) _Pragma("unroll") for (int k = 0; k < 2; ++k) dst[m][k] = *(const PG8_LAS bf16x8*)(lds + PG8_SA(b, h) + aoff + m * 2048 + k * 1024); } while (0)
; #define PG8_LDB(dst, b, h) do { _Pragma("unroll") for (int n = 0; n < 2; ++n) _Pragma("unroll") for (int k = 0; k < 2; ++k) dst[n][k] = *(const PG8_LAS bf16x8*)(lds + PG8_SB(b, h) + boff + n * 2048 + k * 1024); } while (0)
; #define PG8_WAIT_V(n) asm volatile("s_waitcnt vmcnt(" #n ")" ::: "memory")
; #define PG8_WAIT_L(n) asm volatile("s_waitcnt lgkmcnt(" #n ")" ::: "memory")
; #define PG8_BAR __builtin_amdgcn_s_barrier()
; #define PG8_SCHED __builtin_amdgcn_sched_barrier(0)
;     ...
;             PG8_LDB(B0, 1, 0); PG8_LDB(B1, 1, 1); PG8_SCHED; PG8_LDA(At, 1, 0); PG8_STAGE(PG8_SA(0, 1), a2 + hstepA, voffA);
;             PG8_WAIT_V(8); PG8_WAIT_L(0); PG8_BAR; PG8_MMA(0, 0, At, B0); PG8_MMA(0, 1, At, B1); PG8_BAR; PG8_SCHED;
;             PG8_LDA(At, 1, 1); PG8_STAGE(PG8_SB(1, 0), b3, voffB); PG8_STAGE(PG8_SB(1, 1), b3 + hstepB, voffB); PG8_STAGE(PG8_SA(1, 0), a3, voffA);
;             PG8_WAIT_V(8); PG8_WAIT_L(0); PG8_BAR; PG8_MMA(1, 0, At, B0); PG8_MMA(1, 1, At, B1); PG8_BAR; PG8_SCHED;
	s_add_i32 s61, 0, 0x18000
	s_add_i32 s62, 0, 0x1c000
	ds_read_b128 v[146:149], v226 offset:32768
	ds_read_b128 v[150:153], v226 offset:33792
	ds_read_b128 v[154:157], v226 offset:34816
	ds_read_b128 v[158:161], v226 offset:35840
	ds_read_b128 v[186:189], v226 offset:49152
	ds_read_b128 v[190:193], v226 offset:50176
	ds_read_b128 v[194:197], v226 offset:51200
	ds_read_b128 v[198:201], v226 offset:52224
	s_add_u32 s50, s50, 0x80000
	s_addc_u32 s51, s51, 0
	s_mov_b32 m0, s35
	ds_read_b128 v[202:205], v145 offset:32768
	ds_read_b128 v[206:209], v145 offset:33792
	ds_read_b128 v[210:213], v145 offset:34816
	ds_read_b128 v[214:217], v145 offset:35840
	ds_read_b128 v[218:221], v145 offset:36864
	ds_read_b128 v[222:225], v145 offset:37888
	ds_read_b128 v[234:237], v145 offset:38912
	ds_read_b128 v[238:241], v145 offset:39936
	global_load_lds_dwordx4 v132, s[50:51]
	s_mov_b32 m0, s52
	s_nop 0
	global_load_lds_dwordx4 v134, s[50:51]
	s_waitcnt vmcnt(8)
	s_waitcnt lgkmcnt(0)
	s_barrier
	s_setprio 1
	v_mfma_f32_16x16x32_bf16 v[128:131], v[146:149], v[202:205], v[128:131]
	v_mfma_f32_16x16x32_bf16 v[124:127], v[154:157], v[202:205], v[124:127]
	v_mfma_f32_16x16x32_bf16 v[120:123], v[146:149], v[210:213], v[120:123]
	v_mfma_f32_16x16x32_bf16 v[116:119], v[154:157], v[210:213], v[116:119]
	v_mfma_f32_16x16x32_bf16 v[104:107], v[146:149], v[218:221], v[104:107]
	v_mfma_f32_16x16x32_bf16 v[100:103], v[154:157], v[218:221], v[100:103]
	v_mfma_f32_16x16x32_bf16 v[88:91], v[146:149], v[234:237], v[88:91]
	v_mfma_f32_16x16x32_bf16 v[84:87], v[154:157], v[234:237], v[84:87]
	v_mfma_f32_16x16x32_bf16 v[128:131], v[150:153], v[206:209], v[128:131]
	v_mfma_f32_16x16x32_bf16 v[124:127], v[158:161], v[206:209], v[124:127]
	v_mfma_f32_16x16x32_bf16 v[120:123], v[150:153], v[214:217], v[120:123]
	v_mfma_f32_16x16x32_bf16 v[116:119], v[158:161], v[214:217], v[116:119]
	v_mfma_f32_16x16x32_bf16 v[104:107], v[150:153], v[222:225], v[104:107]
	v_mfma_f32_16x16x32_bf16 v[100:103], v[158:161], v[222:225], v[100:103]
	v_mfma_f32_16x16x32_bf16 v[88:91], v[150:153], v[238:241], v[88:91]
	v_mfma_f32_16x16x32_bf16 v[84:87], v[158:161], v[238:241], v[84:87]
	v_mfma_f32_16x16x32_bf16 v[112:115], v[186:189], v[202:205], v[112:115]
	v_mfma_f32_16x16x32_bf16 v[108:111], v[194:197], v[202:205], v[108:111]
	v_mfma_f32_16x16x32_bf16 v[96:99], v[186:189], v[210:213], v[96:99]
	v_mfma_f32_16x16x32_bf16 v[92:95], v[194:197], v[210:213], v[92:95]
	v_mfma_f32_16x16x32_bf16 v[80:83], v[186:189], v[218:221], v[80:83]
	v_mfma_f32_16x16x32_bf16 v[76:79], v[194:197], v[218:221], v[76:79]
	v_mfma_f32_16x16x32_bf16 v[72:75], v[186:189], v[234:237], v[72:75]
	v_mfma_f32_16x16x32_bf16 v[68:71], v[194:197], v[234:237], v[68:71]
	v_mfma_f32_16x16x32_bf16 v[112:115], v[190:193], v[206:209], v[112:115]
	v_mfma_f32_16x16x32_bf16 v[108:111], v[198:201], v[206:209], v[108:111]
	v_mfma_f32_16x16x32_bf16 v[96:99], v[190:193], v[214:217], v[96:99]
	v_mfma_f32_16x16x32_bf16 v[92:95], v[198:201], v[214:217], v[92:95]
	v_mfma_f32_16x16x32_bf16 v[80:83], v[190:193], v[222:225], v[80:83]
	v_mfma_f32_16x16x32_bf16 v[76:79], v[198:201], v[222:225], v[76:79]
	v_mfma_f32_16x16x32_bf16 v[72:75], v[190:193], v[238:241], v[72:75]
	v_mfma_f32_16x16x32_bf16 v[68:71], v[198:201], v[238:241], v[68:71]
	s_setprio 0
	s_barrier
	s_add_i32 s50, s61, s15
	s_mov_b32 m0, s50
	ds_read_b128 v[202:205], v145 offset:49152
	ds_read_b128 v[206:209], v145 offset:50176
	ds_read_b128 v[210:213], v145 offset:51200
	ds_read_b128 v[214:217], v145 offset:52224
	ds_read_b128 v[218:221], v145 offset:53248
	ds_read_b128 v[222:225], v145 offset:54272
	ds_read_b128 v[234:237], v145 offset:55296
	ds_read_b128 v[238:241], v145 offset:56320
	s_add_u32 s98, s48, 0x80
	s_addc_u32 s99, s49, 0
	global_load_lds_dwordx4 v34, s[98:99]
	s_add_i32 m0, s50, 0x2000
	s_add_u32 s48, s48, 0x80080
	s_addc_u32 s49, s49, 0
	s_add_i32 s50, s62, s15
	s_add_u32 s98, s48, 0xfff80000
	s_addc_u32 s99, s49, -1
	global_load_lds_dwordx4 v136, s[98:99]
	s_mov_b32 m0, s50
	s_nop 0
	global_load_lds_dwordx4 v34, s[48:49]
	s_add_i32 m0, s50, 0x2000
	s_nop 0
	global_load_lds_dwordx4 v136, s[48:49]
	v_lshl_add_u64 v[162:163], v[242:243], 0, s[22:23]
	s_mov_b32 m0, s24
	s_nop 0
	global_load_lds_dwordx4 v[162:163], off
	v_lshl_add_u64 v[162:163], v[244:245], 0, s[22:23]
	s_mov_b32 m0, s53
	s_nop 0
	global_load_lds_dwordx4 v[162:163], off
	s_waitcnt vmcnt(8)
	s_waitcnt lgkmcnt(0)
	s_barrier
	s_setprio 1
	v_mfma_f32_16x16x32_bf16 v[64:67], v[146:149], v[202:205], v[64:67]
	v_mfma_f32_16x16x32_bf16 v[60:63], v[154:157], v[202:205], v[60:63]
	v_mfma_f32_16x16x32_bf16 v[56:59], v[146:149], v[210:213], v[56:59]
	v_mfma_f32_16x16x32_bf16 v[52:55], v[154:157], v[210:213], v[52:55]
	v_mfma_f32_16x16x32_bf16 v[40:43], v[146:149], v[218:221], v[40:43]
	v_mfma_f32_16x16x32_bf16 v[36:39], v[154:157], v[218:221], v[36:39]
	v_mfma_f32_16x16x32_bf16 v[22:25], v[146:149], v[234:237], v[22:25]
	v_mfma_f32_16x16x32_bf16 v[18:21], v[154:157], v[234:237], v[18:21]
	v_mfma_f32_16x16x32_bf16 v[64:67], v[150:153], v[206:209], v[64:67]
	v_mfma_f32_16x16x32_bf16 v[60:63], v[158:161], v[206:209], v[60:63]
	v_mfma_f32_16x16x32_bf16 v[56:59], v[150:153], v[214:217], v[56:59]
	v_mfma_f32_16x16x32_bf16 v[52:55], v[158:161], v[214:217], v[52:55]
	v_mfma_f32_16x16x32_bf16 v[40:43], v[150:153], v[222:225], v[40:43]
	v_mfma_f32_16x16x32_bf16 v[36:39], v[158:161], v[222:225], v[36:39]
	v_mfma_f32_16x16x32_bf16 v[22:25], v[150:153], v[238:241], v[22:25]
	v_mfma_f32_16x16x32_bf16 v[18:21], v[158:161], v[238:241], v[18:21]
	v_mfma_f32_16x16x32_bf16 v[48:51], v[186:189], v[202:205], v[48:51]
	v_mfma_f32_16x16x32_bf16 v[44:47], v[194:197], v[202:205], v[44:47]
	v_mfma_f32_16x16x32_bf16 v[30:33], v[186:189], v[210:213], v[30:33]
	v_mfma_f32_16x16x32_bf16 v[26:29], v[194:197], v[210:213], v[26:29]
	v_mfma_f32_16x16x32_bf16 v[14:17], v[186:189], v[218:221], v[14:17]
	v_mfma_f32_16x16x32_bf16 v[10:13], v[194:197], v[218:221], v[10:13]
	v_mfma_f32_16x16x32_bf16 v[6:9], v[186:189], v[234:237], v[6:9]
	v_mfma_f32_16x16x32_bf16 v[2:5], v[194:197], v[234:237], v[2:5]
	v_mfma_f32_16x16x32_bf16 v[48:51], v[190:193], v[206:209], v[48:51]
	v_mfma_f32_16x16x32_bf16 v[44:47], v[198:201], v[206:209], v[44:47]
	v_mfma_f32_16x16x32_bf16 v[30:33], v[190:193], v[214:217], v[30:33]
	v_mfma_f32_16x16x32_bf16 v[26:29], v[198:201], v[214:217], v[26:29]
	v_mfma_f32_16x16x32_bf16 v[14:17], v[190:193], v[222:225], v[14:17]
	v_mfma_f32_16x16x32_bf16 v[10:13], v[198:201], v[222:225], v[10:13]
	v_mfma_f32_16x16x32_bf16 v[6:9], v[190:193], v[238:241], v[6:9]
	v_mfma_f32_16x16x32_bf16 v[2:5], v[198:201], v[238:241], v[2:5]
	s_setprio 0
	s_barrier
	s_add_i32 s60, s60, 2
	s_add_u32 s46, s46, 0x100
	s_addc_u32 s47, s47, 0
	s_add_u32 s58, s58, 0x100
	s_addc_u32 s59, s59, 0
	s_cmp_gt_u32 s60, 29
	s_cbranch_scc0 .LBB0_2138
	s_and_b64 vcc, exec, s[28:29]
	s_cbranch_vccz .LBB0_2141
	s_barrier
